# dn_prep substitution: first fmac of each partial-sum chain becomes a mul (drops the zero-init move), bit-identical
# speedup vs baseline: 1.0210x; 1.0005x over previous
; #define LAS __attribute__((address_space(3)))
; __device__ __forceinline__ float bf2f(unsigned short v) { return __uint_as_float(((unsigned)v) << 16); }
; __device__ __forceinline__ void dn_prep_item(const Args& a, LAS unsigned char* lds, int item, int tid, int wave, int lane, int& cwh, int next_item) {
;     ...
;         { const LAS unsigned char* src = lds + (tid < 128 ? L_V : L_KH) + 2 * (tid & 127); const LAS float* fac = tid < 128 ? betas : bks;
; #pragma unroll
;           for (int i = 0; i < 64; ++i) x[i] = bf2f(*(const LAS unsigned short*)(src + i * KS_)) * fac[i]; }
.LBB0_878:
	s_and_b64 vcc, exec, s[22:23]
	s_cbranch_vccz .LBB0_880
	ds_read_b128 v[0:3], v190
	ds_read_u16 v4, v189
	ds_read_u16 v5, v189 offset:272
	ds_read_u16 v6, v189 offset:544
	ds_read_u16 v10, v189 offset:816
	ds_read_u16 v11, v189 offset:1088
	ds_read_u16 v12, v189 offset:1360
	ds_read_u16 v13, v189 offset:1632
	ds_read_u16 v14, v189 offset:1904
	s_waitcnt lgkmcnt(7)
	v_lshlrev_b32_e32 v4, 16, v4
	v_mul_f32_e32 v71, v0, v4
	s_waitcnt lgkmcnt(6)
	v_lshlrev_b32_e32 v0, 16, v5
	v_mul_f32_e32 v1, v1, v0
	s_waitcnt lgkmcnt(5)
	v_lshlrev_b32_e32 v0, 16, v6
	ds_read_b128 v[6:9], v191
	v_mul_f32_e32 v5, v2, v0
	s_waitcnt lgkmcnt(5)
	v_lshlrev_b32_e32 v0, 16, v10
	v_mul_f32_e32 v2, v3, v0
	s_waitcnt lgkmcnt(4)
	v_lshlrev_b32_e32 v0, 16, v11
	s_waitcnt lgkmcnt(0)
	v_mul_f32_e32 v4, v6, v0
	v_lshlrev_b32_e32 v0, 16, v12
	v_mul_f32_e32 v6, v7, v0
	v_lshlrev_b32_e32 v0, 16, v13
	v_mul_f32_e32 v8, v8, v0
	v_lshlrev_b32_e32 v0, 16, v14
	v_mul_f32_e32 v10, v9, v0
	ds_read_b128 v[14:17], v192
	ds_read_u16 v0, v189 offset:2176
	ds_read_u16 v3, v189 offset:2448
	ds_read_u16 v7, v189 offset:2720
	ds_read_u16 v9, v189 offset:2992
	ds_read_u16 v11, v189 offset:3264
	ds_read_u16 v13, v189 offset:3536
	ds_read_u16 v19, v189 offset:3808
	ds_read_u16 v21, v189 offset:4080
	s_waitcnt lgkmcnt(7)
	v_lshlrev_b32_e32 v0, 16, v0
	ds_read_b128 v[24:27], v193
	v_mul_f32_e32 v12, v14, v0
	s_waitcnt lgkmcnt(7)
	v_lshlrev_b32_e32 v0, 16, v3
	v_mul_f32_e32 v14, v15, v0
	s_waitcnt lgkmcnt(6)
	v_lshlrev_b32_e32 v0, 16, v7
	v_mul_f32_e32 v18, v16, v0
	s_waitcnt lgkmcnt(5)
	v_lshlrev_b32_e32 v0, 16, v9
	v_mul_f32_e32 v20, v17, v0
	s_waitcnt lgkmcnt(4)
	v_lshlrev_b32_e32 v0, 16, v11
	s_waitcnt lgkmcnt(0)
	v_mul_f32_e32 v22, v24, v0
	v_lshlrev_b32_e32 v0, 16, v13
	v_mul_f32_e32 v24, v25, v0
	v_lshlrev_b32_e32 v0, 16, v19
	v_mul_f32_e32 v26, v26, v0
	v_lshlrev_b32_e32 v0, 16, v21
	v_mul_f32_e32 v30, v27, v0
	ds_read_b128 v[34:37], v194
	ds_read_u16 v0, v189 offset:4352
	ds_read_u16 v3, v189 offset:4624
	ds_read_u16 v7, v189 offset:4896
	ds_read_u16 v9, v189 offset:5168
	ds_read_u16 v11, v189 offset:5440
	ds_read_u16 v13, v189 offset:5712
	ds_read_u16 v15, v189 offset:5984
	ds_read_u16 v16, v189 offset:6256
	s_waitcnt lgkmcnt(7)
	v_lshlrev_b32_e32 v0, 16, v0
	ds_read_b128 v[42:45], v195
	v_mul_f32_e32 v32, v34, v0
	s_waitcnt lgkmcnt(7)
	v_lshlrev_b32_e32 v0, 16, v3
	v_mul_f32_e32 v34, v35, v0
	s_waitcnt lgkmcnt(6)
	v_lshlrev_b32_e32 v0, 16, v7
	v_mul_f32_e32 v38, v36, v0
	s_waitcnt lgkmcnt(5)
	v_lshlrev_b32_e32 v0, 16, v9
	v_mul_f32_e32 v40, v37, v0
	s_waitcnt lgkmcnt(4)
	v_lshlrev_b32_e32 v0, 16, v11
	s_waitcnt lgkmcnt(0)
	v_mul_f32_e32 v42, v42, v0
	v_lshlrev_b32_e32 v0, 16, v13
	v_mul_f32_e32 v46, v43, v0
	v_lshlrev_b32_e32 v0, 16, v15
	v_mul_f32_e32 v72, v44, v0
	v_lshlrev_b32_e32 v0, 16, v16
	v_mul_f32_e32 v74, v45, v0
	ds_read_b128 v[80:83], v196
	ds_read_u16 v0, v189 offset:6528
	ds_read_u16 v3, v189 offset:6800
	ds_read_u16 v7, v189 offset:7072
	ds_read_u16 v9, v189 offset:7344
	ds_read_u16 v11, v189 offset:7616
	ds_read_u16 v13, v189 offset:7888
	ds_read_u16 v15, v189 offset:8160
	ds_read_u16 v16, v189 offset:8432
	s_waitcnt lgkmcnt(7)
	v_lshlrev_b32_e32 v0, 16, v0
	ds_read_b128 v[92:95], v197
	v_mul_f32_e32 v78, v80, v0
	s_waitcnt lgkmcnt(7)
	v_lshlrev_b32_e32 v0, 16, v3
	v_mul_f32_e32 v80, v81, v0
	s_waitcnt lgkmcnt(6)
	v_lshlrev_b32_e32 v0, 16, v7
	v_mul_f32_e32 v84, v82, v0
	s_waitcnt lgkmcnt(5)
	v_lshlrev_b32_e32 v0, 16, v9
	v_mul_f32_e32 v86, v83, v0
	s_waitcnt lgkmcnt(4)
	v_lshlrev_b32_e32 v0, 16, v11
	s_waitcnt lgkmcnt(0)
	v_mul_f32_e32 v90, v92, v0
	v_lshlrev_b32_e32 v0, 16, v13
	v_mul_f32_e32 v92, v93, v0
	v_lshlrev_b32_e32 v0, 16, v15
	v_mul_f32_e32 v96, v94, v0
	v_lshlrev_b32_e32 v0, 16, v16
	v_mul_f32_e32 v98, v95, v0
	ds_read_b128 v[102:105], v198
	ds_read_u16 v0, v189 offset:8704
	ds_read_u16 v3, v189 offset:8976
	ds_read_u16 v7, v189 offset:9248
	ds_read_u16 v9, v189 offset:9520
	ds_read_u16 v11, v189 offset:9792
	ds_read_u16 v13, v189 offset:10064
	ds_read_u16 v15, v189 offset:10336
	ds_read_u16 v16, v189 offset:10608
	s_waitcnt lgkmcnt(7)
	v_lshlrev_b32_e32 v0, 16, v0
	ds_read_b128 v[118:121], v199
	v_mul_f32_e32 v102, v102, v0
	s_waitcnt lgkmcnt(7)
	v_lshlrev_b32_e32 v0, 16, v3
	v_mul_f32_e32 v106, v103, v0
	s_waitcnt lgkmcnt(6)
	v_lshlrev_b32_e32 v0, 16, v7
	v_mul_f32_e32 v108, v104, v0
	s_waitcnt lgkmcnt(5)
	v_lshlrev_b32_e32 v0, 16, v9
	v_mul_f32_e32 v112, v105, v0
	s_waitcnt lgkmcnt(4)
	v_lshlrev_b32_e32 v0, 16, v11
	s_waitcnt lgkmcnt(0)
	v_mul_f32_e32 v116, v118, v0
	v_lshlrev_b32_e32 v0, 16, v13
	v_mul_f32_e32 v118, v119, v0
	v_lshlrev_b32_e32 v0, 16, v15
	v_mul_f32_e32 v122, v120, v0
	v_lshlrev_b32_e32 v0, 16, v16
	v_mul_f32_e32 v126, v121, v0
	ds_read_b128 v[130:133], v201
	ds_read_u16 v0, v189 offset:10880
	ds_read_u16 v3, v189 offset:11152
	ds_read_u16 v7, v189 offset:11424
	ds_read_u16 v9, v189 offset:11696
	ds_read_u16 v11, v189 offset:11968
	ds_read_u16 v13, v189 offset:12240
	ds_read_u16 v15, v189 offset:12512
	ds_read_u16 v16, v189 offset:12784
	s_waitcnt lgkmcnt(7)
	v_lshlrev_b32_e32 v0, 16, v0
	ds_read_b128 v[144:147], v202
	v_mul_f32_e32 v130, v130, v0
	s_waitcnt lgkmcnt(7)
	v_lshlrev_b32_e32 v0, 16, v3
	v_mul_f32_e32 v134, v131, v0
	s_waitcnt lgkmcnt(6)
	v_lshlrev_b32_e32 v0, 16, v7
	v_mul_f32_e32 v138, v132, v0
	s_waitcnt lgkmcnt(5)
	v_lshlrev_b32_e32 v0, 16, v9
	v_mul_f32_e32 v142, v133, v0
	s_waitcnt lgkmcnt(4)
	v_lshlrev_b32_e32 v0, 16, v11
	s_waitcnt lgkmcnt(0)
; #define LAS __attribute__((address_space(3)))
; __device__ __forceinline__ float bf2f(unsigned short v) { return __uint_as_float(((unsigned)v) << 16); }
; __device__ __forceinline__ void dn_prep_item(const Args& a, LAS unsigned char* lds, int item, int tid, int wave, int lane, int& cwh, int next_item) {
;     ...
;           for (int i = 0; i < 64; ++i) x[i] = bf2f(*(const LAS unsigned short*)(src + i * KS_)) * fac[i]; }
;         { const LAS float* lrow = Lm + (lane & 15);
; #pragma unroll
;         for (int i = 1; i < 64; ++i) { float sa[4] = { x[i], 0.f, 0.f, 0.f };
;             int lr[4];
; #pragma unroll
;             for (int g = 0; g < (i + 15) / 16; ++g) lr[g] = __float_as_int(lrow[i * 68 + 16 * g]);
; #pragma unroll
;             for (int j = 0; j < i; ++j) { fmac_rowbcast_sel(sa[j & 3], lr[j >> 4], x[j], j); }
;             x[i] = (sa[0] + sa[1]) + (sa[2] + sa[3]); } }
	v_mul_f32_e32 v144, v144, v0
	v_lshlrev_b32_e32 v0, 16, v13
	v_mul_f32_e32 v140, v145, v0
	v_lshlrev_b32_e32 v0, 16, v15
	v_mul_f32_e32 v136, v146, v0
	v_lshlrev_b32_e32 v0, 16, v16
	v_mul_f32_e32 v132, v147, v0
	ds_read_b128 v[234:237], v203
	ds_read_u16 v0, v189 offset:13056
	ds_read_u16 v3, v189 offset:13328
	ds_read_u16 v7, v189 offset:13600
	ds_read_u16 v9, v189 offset:13872
	ds_read_u16 v11, v189 offset:14144
	ds_read_u16 v13, v189 offset:14416
	ds_read_u16 v15, v189 offset:14688
	ds_read_u16 v16, v189 offset:14960
	s_waitcnt lgkmcnt(7)
	v_lshlrev_b32_e32 v0, 16, v0
	ds_read_b128 v[238:241], v204
	v_mul_f32_e32 v128, v234, v0
	s_waitcnt lgkmcnt(7)
	v_lshlrev_b32_e32 v0, 16, v3
	v_mul_f32_e32 v124, v235, v0
	s_waitcnt lgkmcnt(6)
	v_lshlrev_b32_e32 v0, 16, v7
	v_mul_f32_e32 v120, v236, v0
	s_waitcnt lgkmcnt(5)
	v_lshlrev_b32_e32 v0, 16, v9
	v_mul_f32_e32 v114, v237, v0
	s_waitcnt lgkmcnt(4)
	v_lshlrev_b32_e32 v0, 16, v11
	s_waitcnt lgkmcnt(0)
	v_mul_f32_e32 v110, v238, v0
	v_lshlrev_b32_e32 v0, 16, v13
	v_mul_f32_e32 v104, v239, v0
	v_lshlrev_b32_e32 v0, 16, v15
	v_mul_f32_e32 v100, v240, v0
	v_lshlrev_b32_e32 v0, 16, v16
	v_mul_f32_e32 v94, v241, v0
	ds_read_b128 v[234:237], v205
	ds_read_u16 v0, v189 offset:15232
	ds_read_u16 v3, v189 offset:15504
	ds_read_u16 v7, v189 offset:15776
	ds_read_u16 v9, v189 offset:16048
	ds_read_u16 v11, v189 offset:16320
	ds_read_u16 v13, v189 offset:16592
	ds_read_u16 v15, v189 offset:16864
	ds_read_u16 v17, v189 offset:17136
	s_waitcnt lgkmcnt(7)
	v_lshlrev_b32_e32 v0, 16, v0
	ds_read_b128 v[238:241], v207
	v_mul_f32_e32 v88, v234, v0
	s_waitcnt lgkmcnt(7)
	v_lshlrev_b32_e32 v0, 16, v3
	v_mul_f32_e32 v82, v235, v0
	s_waitcnt lgkmcnt(6)
	v_lshlrev_b32_e32 v0, 16, v7
	v_mul_f32_e32 v76, v236, v0
	s_waitcnt lgkmcnt(5)
	v_lshlrev_b32_e32 v0, 16, v9
	v_mul_f32_e32 v44, v237, v0
	s_waitcnt lgkmcnt(4)
	v_lshlrev_b32_e32 v0, 16, v11
	s_waitcnt lgkmcnt(0)
	v_mul_f32_e32 v36, v238, v0
	v_lshlrev_b32_e32 v0, 16, v13
	v_mul_f32_e32 v28, v239, v0
	v_add_u32_e32 v0, 0x8800, v208
	ds_read2_b32 v[242:243], v0 offset0:68 offset1:136
	s_waitcnt lgkmcnt(0)
	v_add_u32_e32 v254, 0x8a00, v208
	ds_read2_b32 v[246:247], v254 offset0:76 offset1:144
	v_fmac_f32_dpp v1, v242, v71 row_newbcast:0 row_mask:0xf bank_mask:0xf
	v_fmac_f32_dpp v5, v243, v71 row_newbcast:0 row_mask:0xf bank_mask:0xf
	v_add_f32_e32 v234, 0, v1
	v_add_u32_e32 v1, 0x8a00, v208
	s_nop 0
	v_mul_f32_dpp v1, v243, v234 row_newbcast:1 row_mask:0xf bank_mask:0xf
	s_waitcnt lgkmcnt(0)
	v_add_u32_e32 v254, 0x8c00, v208
	ds_read2_b32 v[248:249], v254 offset0:84 offset1:152
	v_fmac_f32_dpp v2, v246, v71 row_newbcast:0 row_mask:0xf bank_mask:0xf
	v_add_f32_e32 v1, v5, v1
	v_add_f32_e32 v235, 0, v1
	v_mul_f32_dpp v3, v246, v235 row_newbcast:2 row_mask:0xf bank_mask:0xf
	v_mul_f32_dpp v56, v246, v234 row_newbcast:1 row_mask:0xf bank_mask:0xf
	v_fmac_f32_dpp v4, v247, v71 row_newbcast:0 row_mask:0xf bank_mask:0xf
	v_mul_f32_dpp v146, v247, v234 row_newbcast:1 row_mask:0xf bank_mask:0xf
	v_mul_f32_dpp v5, v247, v235 row_newbcast:2 row_mask:0xf bank_mask:0xf
	v_add_u32_e32 v1, 0x8c00, v208
	v_pk_add_f32 v[2:3], v[2:3], v[56:57]
	v_pk_add_f32 v[2:3], v[2:3], v[2:3] op_sel:[0,1] op_sel_hi:[1,0]
	s_nop 0
	v_mul_f32_dpp v147, v247, v2 row_newbcast:3 row_mask:0xf bank_mask:0xf
	s_waitcnt lgkmcnt(0)
	v_add_u32_e32 v254, 0x8e00, v208
	ds_read2_b32 v[250:251], v254 offset0:92 offset1:160
	v_fmac_f32_dpp v6, v248, v71 row_newbcast:0 row_mask:0xf bank_mask:0xf
	v_pk_add_f32 v[4:5], v[4:5], v[146:147]
	v_pk_add_f32 v[4:5], v[4:5], v[4:5] op_sel:[0,1] op_sel_hi:[1,0]
	v_mul_f32_dpp v146, v248, v234 row_newbcast:1 row_mask:0xf bank_mask:0xf
	v_mul_f32_dpp v7, v248, v235 row_newbcast:2 row_mask:0xf bank_mask:0xf
	v_fmac_f32_dpp v6, v248, v4 row_newbcast:4 row_mask:0xf bank_mask:0xf
	v_mul_f32_dpp v147, v248, v2 row_newbcast:3 row_mask:0xf bank_mask:0xf
	v_fmac_f32_dpp v8, v249, v71 row_newbcast:0 row_mask:0xf bank_mask:0xf
	v_pk_add_f32 v[6:7], v[6:7], v[146:147]
	v_mul_f32_dpp v146, v249, v234 row_newbcast:1 row_mask:0xf bank_mask:0xf
	v_pk_add_f32 v[6:7], v[6:7], v[6:7] op_sel:[0,1] op_sel_hi:[1,0]
	v_mul_f32_dpp v9, v249, v235 row_newbcast:2 row_mask:0xf bank_mask:0xf
	v_fmac_f32_dpp v8, v249, v4 row_newbcast:4 row_mask:0xf bank_mask:0xf
	v_fmac_f32_dpp v146, v249, v6 row_newbcast:5 row_mask:0xf bank_mask:0xf
	v_mul_f32_dpp v147, v249, v2 row_newbcast:3 row_mask:0xf bank_mask:0xf
	v_add_u32_e32 v1, 0x8e00, v208
	v_pk_add_f32 v[8:9], v[8:9], v[146:147]
	s_nop 0
	s_waitcnt lgkmcnt(0)
	v_add_u32_e32 v254, 0x9000, v208
	ds_read2_b32 v[252:253], v254 offset0:100 offset1:168
	v_fmac_f32_dpp v10, v250, v71 row_newbcast:0 row_mask:0xf bank_mask:0xf
	v_mul_f32_dpp v146, v250, v234 row_newbcast:1 row_mask:0xf bank_mask:0xf
	v_mul_f32_dpp v11, v250, v235 row_newbcast:2 row_mask:0xf bank_mask:0xf
	v_pk_add_f32 v[8:9], v[8:9], v[8:9] op_sel:[0,1] op_sel_hi:[1,0]
	v_fmac_f32_dpp v10, v250, v4 row_newbcast:4 row_mask:0xf bank_mask:0xf
	v_fmac_f32_dpp v146, v250, v6 row_newbcast:5 row_mask:0xf bank_mask:0xf
	v_fmac_f32_dpp v11, v250, v8 row_newbcast:6 row_mask:0xf bank_mask:0xf
	v_mul_f32_dpp v147, v250, v2 row_newbcast:3 row_mask:0xf bank_mask:0xf
	v_pk_add_f32 v[10:11], v[10:11], v[146:147]
	v_fmac_f32_dpp v12, v251, v71 row_newbcast:0 row_mask:0xf bank_mask:0xf
	v_mul_f32_dpp v146, v251, v234 row_newbcast:1 row_mask:0xf bank_mask:0xf
	v_mul_f32_dpp v13, v251, v235 row_newbcast:2 row_mask:0xf bank_mask:0xf
	v_mul_f32_dpp v147, v251, v2 row_newbcast:3 row_mask:0xf bank_mask:0xf
	v_fmac_f32_dpp v12, v251, v4 row_newbcast:4 row_mask:0xf bank_mask:0xf
	v_fmac_f32_dpp v146, v251, v6 row_newbcast:5 row_mask:0xf bank_mask:0xf
	v_add_u32_e32 v1, 0x9000, v208
	v_fmac_f32_dpp v13, v251, v8 row_newbcast:6 row_mask:0xf bank_mask:0xf
	v_lshlrev_b32_e32 v0, 16, v15
	v_pk_add_f32 v[10:11], v[10:11], v[10:11] op_sel:[0,1] op_sel_hi:[1,0]
	s_nop 0
	v_fmac_f32_dpp v147, v251, v10 row_newbcast:7 row_mask:0xf bank_mask:0xf
	s_waitcnt lgkmcnt(0)
; #define LAS __attribute__((address_space(3)))
; __device__ __forceinline__ void dn_prep_item(const Args& a, LAS unsigned char* lds, int item, int tid, int wave, int lane, int& cwh, int next_item) {
;     ...
;         { const LAS float* lrow = Lm + (lane & 15);
; #pragma unroll
;         for (int i = 1; i < 64; ++i) { float sa[4] = { x[i], 0.f, 0.f, 0.f };
;             int lr[4];
; #pragma unroll
;             for (int g = 0; g < (i + 15) / 16; ++g) lr[g] = __float_as_int(lrow[i * 68 + 16 * g]);
; #pragma unroll
;             for (int j = 0; j < i; ++j) { fmac_rowbcast_sel(sa[j & 3], lr[j >> 4], x[j], j); }
;             x[i] = (sa[0] + sa[1]) + (sa[2] + sa[3]); } }
	v_add_u32_e32 v254, 0x9200, v208
	ds_read2_b32 v[242:243], v254 offset0:108 offset1:176
	v_fmac_f32_dpp v14, v252, v71 row_newbcast:0 row_mask:0xf bank_mask:0xf
	v_pk_add_f32 v[12:13], v[12:13], v[146:147]
	v_mul_f32_dpp v146, v252, v234 row_newbcast:1 row_mask:0xf bank_mask:0xf
	v_mul_f32_dpp v15, v252, v235 row_newbcast:2 row_mask:0xf bank_mask:0xf
	v_fmac_f32_dpp v14, v252, v4 row_newbcast:4 row_mask:0xf bank_mask:0xf
	v_pk_add_f32 v[12:13], v[12:13], v[12:13] op_sel:[0,1] op_sel_hi:[1,0]
	v_mul_f32_dpp v147, v252, v2 row_newbcast:3 row_mask:0xf bank_mask:0xf
	v_fmac_f32_dpp v146, v252, v6 row_newbcast:5 row_mask:0xf bank_mask:0xf
	v_fmac_f32_dpp v15, v252, v8 row_newbcast:6 row_mask:0xf bank_mask:0xf
	v_fmac_f32_dpp v18, v253, v71 row_newbcast:0 row_mask:0xf bank_mask:0xf
	v_fmac_f32_dpp v14, v252, v12 row_newbcast:8 row_mask:0xf bank_mask:0xf
	v_fmac_f32_dpp v147, v252, v10 row_newbcast:7 row_mask:0xf bank_mask:0xf
	v_mul_f32_dpp v19, v253, v235 row_newbcast:2 row_mask:0xf bank_mask:0xf
	v_fmac_f32_dpp v18, v253, v4 row_newbcast:4 row_mask:0xf bank_mask:0xf
	v_add_u32_e32 v1, 0x9200, v208
	v_pk_add_f32 v[14:15], v[14:15], v[146:147]
	v_mul_f32_dpp v146, v253, v234 row_newbcast:1 row_mask:0xf bank_mask:0xf
	v_fmac_f32_dpp v146, v253, v6 row_newbcast:5 row_mask:0xf bank_mask:0xf
	v_pk_add_f32 v[14:15], v[14:15], v[14:15] op_sel:[0,1] op_sel_hi:[1,0]
	v_mul_f32_dpp v147, v253, v2 row_newbcast:3 row_mask:0xf bank_mask:0xf
	v_fmac_f32_dpp v19, v253, v8 row_newbcast:6 row_mask:0xf bank_mask:0xf
	v_fmac_f32_dpp v18, v253, v12 row_newbcast:8 row_mask:0xf bank_mask:0xf
	v_fmac_f32_dpp v146, v253, v14 row_newbcast:9 row_mask:0xf bank_mask:0xf
	v_fmac_f32_dpp v147, v253, v10 row_newbcast:7 row_mask:0xf bank_mask:0xf
	s_nop 0
	v_pk_add_f32 v[18:19], v[18:19], v[146:147]
	s_waitcnt lgkmcnt(0)
	v_add_u32_e32 v254, 0x9400, v208
	ds_read2_b32 v[246:247], v254 offset0:116 offset1:184
	v_fmac_f32_dpp v20, v242, v71 row_newbcast:0 row_mask:0xf bank_mask:0xf
	v_mul_f32_dpp v146, v242, v234 row_newbcast:1 row_mask:0xf bank_mask:0xf
	v_mul_f32_dpp v21, v242, v235 row_newbcast:2 row_mask:0xf bank_mask:0xf
	v_fmac_f32_dpp v20, v242, v4 row_newbcast:4 row_mask:0xf bank_mask:0xf
	v_fmac_f32_dpp v146, v242, v6 row_newbcast:5 row_mask:0xf bank_mask:0xf
	v_fmac_f32_dpp v21, v242, v8 row_newbcast:6 row_mask:0xf bank_mask:0xf
	v_pk_add_f32 v[18:19], v[18:19], v[18:19] op_sel:[0,1] op_sel_hi:[1,0]
	v_mul_f32_dpp v147, v242, v2 row_newbcast:3 row_mask:0xf bank_mask:0xf
	v_fmac_f32_dpp v20, v242, v12 row_newbcast:8 row_mask:0xf bank_mask:0xf
	v_fmac_f32_dpp v146, v242, v14 row_newbcast:9 row_mask:0xf bank_mask:0xf
	v_fmac_f32_dpp v21, v242, v18 row_newbcast:10 row_mask:0xf bank_mask:0xf
	v_fmac_f32_dpp v147, v242, v10 row_newbcast:7 row_mask:0xf bank_mask:0xf
	v_fmac_f32_dpp v22, v243, v71 row_newbcast:0 row_mask:0xf bank_mask:0xf
	v_mul_f32_dpp v23, v243, v235 row_newbcast:2 row_mask:0xf bank_mask:0xf
	v_add_u32_e32 v1, 0x9400, v208
	v_pk_add_f32 v[20:21], v[20:21], v[146:147]
	v_mul_f32_dpp v146, v243, v234 row_newbcast:1 row_mask:0xf bank_mask:0xf
	v_mul_f32_dpp v147, v243, v2 row_newbcast:3 row_mask:0xf bank_mask:0xf
	v_fmac_f32_dpp v22, v243, v4 row_newbcast:4 row_mask:0xf bank_mask:0xf
	v_fmac_f32_dpp v146, v243, v6 row_newbcast:5 row_mask:0xf bank_mask:0xf
	v_fmac_f32_dpp v23, v243, v8 row_newbcast:6 row_mask:0xf bank_mask:0xf
	v_pk_add_f32 v[20:21], v[20:21], v[20:21] op_sel:[0,1] op_sel_hi:[1,0]
	v_fmac_f32_dpp v147, v243, v10 row_newbcast:7 row_mask:0xf bank_mask:0xf
	v_fmac_f32_dpp v22, v243, v12 row_newbcast:8 row_mask:0xf bank_mask:0xf
	v_fmac_f32_dpp v146, v243, v14 row_newbcast:9 row_mask:0xf bank_mask:0xf
	v_fmac_f32_dpp v23, v243, v18 row_newbcast:10 row_mask:0xf bank_mask:0xf
	s_nop 0
	v_fmac_f32_dpp v147, v243, v20 row_newbcast:11 row_mask:0xf bank_mask:0xf
	s_waitcnt lgkmcnt(0)
	v_add_u32_e32 v254, 0x9600, v208
	ds_read2_b32 v[248:249], v254 offset0:124 offset1:192
	v_fmac_f32_dpp v24, v246, v71 row_newbcast:0 row_mask:0xf bank_mask:0xf
	v_pk_add_f32 v[22:23], v[22:23], v[146:147]
	v_mul_f32_dpp v146, v246, v234 row_newbcast:1 row_mask:0xf bank_mask:0xf
	v_mul_f32_dpp v25, v246, v235 row_newbcast:2 row_mask:0xf bank_mask:0xf
	v_fmac_f32_dpp v24, v246, v4 row_newbcast:4 row_mask:0xf bank_mask:0xf
	v_mul_f32_dpp v147, v246, v2 row_newbcast:3 row_mask:0xf bank_mask:0xf
	v_fmac_f32_dpp v146, v246, v6 row_newbcast:5 row_mask:0xf bank_mask:0xf
	v_fmac_f32_dpp v25, v246, v8 row_newbcast:6 row_mask:0xf bank_mask:0xf
	v_pk_add_f32 v[22:23], v[22:23], v[22:23] op_sel:[0,1] op_sel_hi:[1,0]
	v_fmac_f32_dpp v24, v246, v12 row_newbcast:8 row_mask:0xf bank_mask:0xf
	v_fmac_f32_dpp v147, v246, v10 row_newbcast:7 row_mask:0xf bank_mask:0xf
	v_fmac_f32_dpp v146, v246, v14 row_newbcast:9 row_mask:0xf bank_mask:0xf
	v_fmac_f32_dpp v25, v246, v18 row_newbcast:10 row_mask:0xf bank_mask:0xf
	v_fmac_f32_dpp v26, v247, v71 row_newbcast:0 row_mask:0xf bank_mask:0xf
	v_fmac_f32_dpp v24, v246, v22 row_newbcast:12 row_mask:0xf bank_mask:0xf
	v_fmac_f32_dpp v147, v246, v20 row_newbcast:11 row_mask:0xf bank_mask:0xf
	v_mul_f32_dpp v27, v247, v235 row_newbcast:2 row_mask:0xf bank_mask:0xf
	v_fmac_f32_dpp v26, v247, v4 row_newbcast:4 row_mask:0xf bank_mask:0xf
	v_add_u32_e32 v1, 0x9600, v208
	v_pk_add_f32 v[24:25], v[24:25], v[146:147]
	v_mul_f32_dpp v146, v247, v234 row_newbcast:1 row_mask:0xf bank_mask:0xf
	v_fmac_f32_dpp v146, v247, v6 row_newbcast:5 row_mask:0xf bank_mask:0xf
	v_mul_f32_dpp v147, v247, v2 row_newbcast:3 row_mask:0xf bank_mask:0xf
	v_fmac_f32_dpp v27, v247, v8 row_newbcast:6 row_mask:0xf bank_mask:0xf
	v_fmac_f32_dpp v26, v247, v12 row_newbcast:8 row_mask:0xf bank_mask:0xf
	v_pk_add_f32 v[24:25], v[24:25], v[24:25] op_sel:[0,1] op_sel_hi:[1,0]
	v_fmac_f32_dpp v146, v247, v14 row_newbcast:9 row_mask:0xf bank_mask:0xf
	v_fmac_f32_dpp v147, v247, v10 row_newbcast:7 row_mask:0xf bank_mask:0xf
	v_fmac_f32_dpp v27, v247, v18 row_newbcast:10 row_mask:0xf bank_mask:0xf
	v_fmac_f32_dpp v26, v247, v22 row_newbcast:12 row_mask:0xf bank_mask:0xf
	v_fmac_f32_dpp v146, v247, v24 row_newbcast:13 row_mask:0xf bank_mask:0xf
	v_fmac_f32_dpp v147, v247, v20 row_newbcast:11 row_mask:0xf bank_mask:0xf
	s_nop 0
	v_pk_add_f32 v[26:27], v[26:27], v[146:147]
	s_waitcnt lgkmcnt(0)
; #define LAS __attribute__((address_space(3)))
; __device__ __forceinline__ void dn_prep_item(const Args& a, LAS unsigned char* lds, int item, int tid, int wave, int lane, int& cwh, int next_item) {
;     ...
;         { const LAS float* lrow = Lm + (lane & 15);
; #pragma unroll
;         for (int i = 1; i < 64; ++i) { float sa[4] = { x[i], 0.f, 0.f, 0.f };
;             int lr[4];
; #pragma unroll
;             for (int g = 0; g < (i + 15) / 16; ++g) lr[g] = __float_as_int(lrow[i * 68 + 16 * g]);
; #pragma unroll
;             for (int j = 0; j < i; ++j) { fmac_rowbcast_sel(sa[j & 3], lr[j >> 4], x[j], j); }
;             x[i] = (sa[0] + sa[1]) + (sa[2] + sa[3]); } }
	v_add_u32_e32 v254, 0x9800, v208
	ds_read2_b32 v[250:251], v254 offset0:132 offset1:148
	v_fmac_f32_dpp v30, v248, v71 row_newbcast:0 row_mask:0xf bank_mask:0xf
	v_mul_f32_dpp v146, v248, v234 row_newbcast:1 row_mask:0xf bank_mask:0xf
	v_mul_f32_dpp v31, v248, v235 row_newbcast:2 row_mask:0xf bank_mask:0xf
	v_fmac_f32_dpp v30, v248, v4 row_newbcast:4 row_mask:0xf bank_mask:0xf
	v_fmac_f32_dpp v146, v248, v6 row_newbcast:5 row_mask:0xf bank_mask:0xf
	v_fmac_f32_dpp v31, v248, v8 row_newbcast:6 row_mask:0xf bank_mask:0xf
	v_mul_f32_dpp v147, v248, v2 row_newbcast:3 row_mask:0xf bank_mask:0xf
	v_pk_add_f32 v[26:27], v[26:27], v[26:27] op_sel:[0,1] op_sel_hi:[1,0]
	v_fmac_f32_dpp v30, v248, v12 row_newbcast:8 row_mask:0xf bank_mask:0xf
	v_fmac_f32_dpp v146, v248, v14 row_newbcast:9 row_mask:0xf bank_mask:0xf
	v_fmac_f32_dpp v31, v248, v18 row_newbcast:10 row_mask:0xf bank_mask:0xf
	v_fmac_f32_dpp v147, v248, v10 row_newbcast:7 row_mask:0xf bank_mask:0xf
	v_fmac_f32_dpp v30, v248, v22 row_newbcast:12 row_mask:0xf bank_mask:0xf
	v_fmac_f32_dpp v146, v248, v24 row_newbcast:13 row_mask:0xf bank_mask:0xf
	v_fmac_f32_dpp v31, v248, v26 row_newbcast:14 row_mask:0xf bank_mask:0xf
	v_fmac_f32_dpp v147, v248, v20 row_newbcast:11 row_mask:0xf bank_mask:0xf
	v_fmac_f32_dpp v32, v249, v71 row_newbcast:0 row_mask:0xf bank_mask:0xf
	v_mul_f32_dpp v33, v249, v235 row_newbcast:2 row_mask:0xf bank_mask:0xf
	v_add_u32_e32 v1, 0x9800, v208
	v_pk_add_f32 v[30:31], v[30:31], v[146:147]
	v_mul_f32_dpp v146, v249, v234 row_newbcast:1 row_mask:0xf bank_mask:0xf
	v_mul_f32_dpp v147, v249, v2 row_newbcast:3 row_mask:0xf bank_mask:0xf
	v_fmac_f32_dpp v32, v249, v4 row_newbcast:4 row_mask:0xf bank_mask:0xf
	v_fmac_f32_dpp v146, v249, v6 row_newbcast:5 row_mask:0xf bank_mask:0xf
	v_fmac_f32_dpp v33, v249, v8 row_newbcast:6 row_mask:0xf bank_mask:0xf
	v_pk_add_f32 v[30:31], v[30:31], v[30:31] op_sel:[0,1] op_sel_hi:[1,0]
	v_fmac_f32_dpp v147, v249, v10 row_newbcast:7 row_mask:0xf bank_mask:0xf
	v_fmac_f32_dpp v32, v249, v12 row_newbcast:8 row_mask:0xf bank_mask:0xf
	v_fmac_f32_dpp v146, v249, v14 row_newbcast:9 row_mask:0xf bank_mask:0xf
	v_fmac_f32_dpp v33, v249, v18 row_newbcast:10 row_mask:0xf bank_mask:0xf
	s_nop 0
	v_fmac_f32_dpp v147, v249, v20 row_newbcast:11 row_mask:0xf bank_mask:0xf
	v_fmac_f32_dpp v32, v249, v22 row_newbcast:12 row_mask:0xf bank_mask:0xf
	v_fmac_f32_dpp v146, v249, v24 row_newbcast:13 row_mask:0xf bank_mask:0xf
	v_fmac_f32_dpp v33, v249, v26 row_newbcast:14 row_mask:0xf bank_mask:0xf
	s_waitcnt lgkmcnt(0)
	v_add_u32_e32 v254, 0x9800, v208
	ds_read2_b32 v[252:253], v254 offset0:200 offset1:216
	v_fmac_f32_dpp v34, v250, v71 row_newbcast:0 row_mask:0xf bank_mask:0xf
	v_fmac_f32_dpp v147, v249, v30 row_newbcast:15 row_mask:0xf bank_mask:0xf
	v_mul_f32_dpp v35, v250, v235 row_newbcast:2 row_mask:0xf bank_mask:0xf
	v_fmac_f32_dpp v34, v250, v4 row_newbcast:4 row_mask:0xf bank_mask:0xf
	s_nop 0
	v_pk_add_f32 v[32:33], v[32:33], v[146:147]
	v_mul_f32_dpp v146, v250, v234 row_newbcast:1 row_mask:0xf bank_mask:0xf
	v_mul_f32_dpp v147, v250, v2 row_newbcast:3 row_mask:0xf bank_mask:0xf
	v_fmac_f32_dpp v146, v250, v6 row_newbcast:5 row_mask:0xf bank_mask:0xf
	v_fmac_f32_dpp v35, v250, v8 row_newbcast:6 row_mask:0xf bank_mask:0xf
	v_fmac_f32_dpp v34, v250, v12 row_newbcast:8 row_mask:0xf bank_mask:0xf
	v_pk_add_f32 v[32:33], v[32:33], v[32:33] op_sel:[0,1] op_sel_hi:[1,0]
	v_fmac_f32_dpp v147, v250, v10 row_newbcast:7 row_mask:0xf bank_mask:0xf
	v_fmac_f32_dpp v146, v250, v14 row_newbcast:9 row_mask:0xf bank_mask:0xf
	v_fmac_f32_dpp v35, v250, v18 row_newbcast:10 row_mask:0xf bank_mask:0xf
	v_fmac_f32_dpp v34, v250, v22 row_newbcast:12 row_mask:0xf bank_mask:0xf
	s_waitcnt lgkmcnt(0)
	v_add_u32_e32 v254, 0x9c00, v208
	ds_read2_b32 v[242:243], v254 offset0:12 offset1:28
	v_fmac_f32_dpp v38, v252, v71 row_newbcast:0 row_mask:0xf bank_mask:0xf
	v_fmac_f32_dpp v147, v250, v20 row_newbcast:11 row_mask:0xf bank_mask:0xf
	v_fmac_f32_dpp v146, v250, v24 row_newbcast:13 row_mask:0xf bank_mask:0xf
	v_fmac_f32_dpp v35, v250, v26 row_newbcast:14 row_mask:0xf bank_mask:0xf
	v_fmac_f32_dpp v34, v251, v32 row_newbcast:0 row_mask:0xf bank_mask:0xf
	v_mul_f32_dpp v39, v252, v235 row_newbcast:2 row_mask:0xf bank_mask:0xf
	v_fmac_f32_dpp v38, v252, v4 row_newbcast:4 row_mask:0xf bank_mask:0xf
	s_nop 0
	v_fmac_f32_dpp v147, v250, v30 row_newbcast:15 row_mask:0xf bank_mask:0xf
	v_add_u32_e32 v1, 0x9c00, v208
	v_pk_add_f32 v[34:35], v[34:35], v[146:147]
	v_mul_f32_dpp v146, v252, v234 row_newbcast:1 row_mask:0xf bank_mask:0xf
	v_fmac_f32_dpp v146, v252, v6 row_newbcast:5 row_mask:0xf bank_mask:0xf
	v_mul_f32_dpp v147, v252, v2 row_newbcast:3 row_mask:0xf bank_mask:0xf
	v_fmac_f32_dpp v39, v252, v8 row_newbcast:6 row_mask:0xf bank_mask:0xf
	v_fmac_f32_dpp v38, v252, v12 row_newbcast:8 row_mask:0xf bank_mask:0xf
	v_pk_add_f32 v[34:35], v[34:35], v[34:35] op_sel:[0,1] op_sel_hi:[1,0]
	v_fmac_f32_dpp v146, v252, v14 row_newbcast:9 row_mask:0xf bank_mask:0xf
	v_fmac_f32_dpp v147, v252, v10 row_newbcast:7 row_mask:0xf bank_mask:0xf
	v_fmac_f32_dpp v39, v252, v18 row_newbcast:10 row_mask:0xf bank_mask:0xf
	v_fmac_f32_dpp v38, v252, v22 row_newbcast:12 row_mask:0xf bank_mask:0xf
	v_fmac_f32_dpp v146, v252, v24 row_newbcast:13 row_mask:0xf bank_mask:0xf
	v_fmac_f32_dpp v147, v252, v20 row_newbcast:11 row_mask:0xf bank_mask:0xf
	v_fmac_f32_dpp v39, v252, v26 row_newbcast:14 row_mask:0xf bank_mask:0xf
	v_fmac_f32_dpp v38, v253, v32 row_newbcast:0 row_mask:0xf bank_mask:0xf
	s_nop 0
	v_fmac_f32_dpp v146, v253, v34 row_newbcast:1 row_mask:0xf bank_mask:0xf
	v_fmac_f32_dpp v147, v252, v30 row_newbcast:15 row_mask:0xf bank_mask:0xf
	s_waitcnt lgkmcnt(0)
; #define LAS __attribute__((address_space(3)))
; __device__ __forceinline__ void dn_prep_item(const Args& a, LAS unsigned char* lds, int item, int tid, int wave, int lane, int& cwh, int next_item) {
;     ...
;         { const LAS float* lrow = Lm + (lane & 15);
; #pragma unroll
;         for (int i = 1; i < 64; ++i) { float sa[4] = { x[i], 0.f, 0.f, 0.f };
;             int lr[4];
; #pragma unroll
;             for (int g = 0; g < (i + 15) / 16; ++g) lr[g] = __float_as_int(lrow[i * 68 + 16 * g]);
; #pragma unroll
;             for (int j = 0; j < i; ++j) { fmac_rowbcast_sel(sa[j & 3], lr[j >> 4], x[j], j); }
;             x[i] = (sa[0] + sa[1]) + (sa[2] + sa[3]); } }
	v_add_u32_e32 v254, 0x9c00, v208
	ds_read2_b32 v[246:247], v254 offset0:80 offset1:96
	v_fmac_f32_dpp v40, v242, v71 row_newbcast:0 row_mask:0xf bank_mask:0xf
	v_mul_f32_dpp v41, v242, v235 row_newbcast:2 row_mask:0xf bank_mask:0xf
	v_pk_add_f32 v[38:39], v[38:39], v[146:147]
	v_mul_f32_dpp v146, v242, v234 row_newbcast:1 row_mask:0xf bank_mask:0xf
	v_fmac_f32_dpp v40, v242, v4 row_newbcast:4 row_mask:0xf bank_mask:0xf
	v_fmac_f32_dpp v146, v242, v6 row_newbcast:5 row_mask:0xf bank_mask:0xf
	v_fmac_f32_dpp v41, v242, v8 row_newbcast:6 row_mask:0xf bank_mask:0xf
	v_mul_f32_dpp v147, v242, v2 row_newbcast:3 row_mask:0xf bank_mask:0xf
	v_pk_add_f32 v[38:39], v[38:39], v[38:39] op_sel:[0,1] op_sel_hi:[1,0]
	v_fmac_f32_dpp v40, v242, v12 row_newbcast:8 row_mask:0xf bank_mask:0xf
	v_fmac_f32_dpp v146, v242, v14 row_newbcast:9 row_mask:0xf bank_mask:0xf
	v_fmac_f32_dpp v41, v242, v18 row_newbcast:10 row_mask:0xf bank_mask:0xf
	v_fmac_f32_dpp v147, v242, v10 row_newbcast:7 row_mask:0xf bank_mask:0xf
	s_nop 0
	v_fmac_f32_dpp v40, v242, v22 row_newbcast:12 row_mask:0xf bank_mask:0xf
	v_fmac_f32_dpp v146, v242, v24 row_newbcast:13 row_mask:0xf bank_mask:0xf
	v_fmac_f32_dpp v41, v242, v26 row_newbcast:14 row_mask:0xf bank_mask:0xf
	v_fmac_f32_dpp v147, v242, v20 row_newbcast:11 row_mask:0xf bank_mask:0xf
	s_waitcnt lgkmcnt(0)
	v_add_u32_e32 v254, 0x9c00, v208
	ds_read2_b32 v[248:249], v254 offset0:148 offset1:164
	v_fmac_f32_dpp v42, v246, v71 row_newbcast:0 row_mask:0xf bank_mask:0xf
	v_mul_f32_dpp v43, v246, v235 row_newbcast:2 row_mask:0xf bank_mask:0xf
	v_fmac_f32_dpp v40, v243, v32 row_newbcast:0 row_mask:0xf bank_mask:0xf
	v_fmac_f32_dpp v146, v243, v34 row_newbcast:1 row_mask:0xf bank_mask:0xf
	v_fmac_f32_dpp v41, v243, v38 row_newbcast:2 row_mask:0xf bank_mask:0xf
	v_fmac_f32_dpp v147, v242, v30 row_newbcast:15 row_mask:0xf bank_mask:0xf
	s_nop 0
	v_fmac_f32_dpp v42, v246, v4 row_newbcast:4 row_mask:0xf bank_mask:0xf
	v_fmac_f32_dpp v43, v246, v8 row_newbcast:6 row_mask:0xf bank_mask:0xf
	s_nop 0
	v_pk_add_f32 v[40:41], v[40:41], v[146:147]
	v_mul_f32_dpp v146, v246, v234 row_newbcast:1 row_mask:0xf bank_mask:0xf
	v_mul_f32_dpp v147, v246, v2 row_newbcast:3 row_mask:0xf bank_mask:0xf
	v_fmac_f32_dpp v146, v246, v6 row_newbcast:5 row_mask:0xf bank_mask:0xf
	v_fmac_f32_dpp v42, v246, v12 row_newbcast:8 row_mask:0xf bank_mask:0xf
	v_fmac_f32_dpp v43, v246, v18 row_newbcast:10 row_mask:0xf bank_mask:0xf
	v_pk_add_f32 v[40:41], v[40:41], v[40:41] op_sel:[0,1] op_sel_hi:[1,0]
	v_fmac_f32_dpp v147, v246, v10 row_newbcast:7 row_mask:0xf bank_mask:0xf
	v_fmac_f32_dpp v146, v246, v14 row_newbcast:9 row_mask:0xf bank_mask:0xf
	v_fmac_f32_dpp v42, v246, v22 row_newbcast:12 row_mask:0xf bank_mask:0xf
	v_fmac_f32_dpp v43, v246, v26 row_newbcast:14 row_mask:0xf bank_mask:0xf
	s_waitcnt lgkmcnt(0)
	v_add_u32_e32 v254, 0x9c00, v208
	ds_read2_b32 v[250:251], v254 offset0:216 offset1:232
	v_fmac_f32_dpp v46, v248, v71 row_newbcast:0 row_mask:0xf bank_mask:0xf
	v_fmac_f32_dpp v147, v246, v20 row_newbcast:11 row_mask:0xf bank_mask:0xf
	v_fmac_f32_dpp v146, v246, v24 row_newbcast:13 row_mask:0xf bank_mask:0xf
	v_fmac_f32_dpp v42, v247, v32 row_newbcast:0 row_mask:0xf bank_mask:0xf
	v_fmac_f32_dpp v43, v247, v38 row_newbcast:2 row_mask:0xf bank_mask:0xf
	v_mul_f32_dpp v47, v248, v235 row_newbcast:2 row_mask:0xf bank_mask:0xf
	v_fmac_f32_dpp v46, v248, v4 row_newbcast:4 row_mask:0xf bank_mask:0xf
	s_nop 0
	v_fmac_f32_dpp v147, v246, v30 row_newbcast:15 row_mask:0xf bank_mask:0xf
	v_fmac_f32_dpp v146, v247, v34 row_newbcast:1 row_mask:0xf bank_mask:0xf
	v_fmac_f32_dpp v147, v247, v40 row_newbcast:3 row_mask:0xf bank_mask:0xf
	v_fmac_f32_dpp v47, v248, v8 row_newbcast:6 row_mask:0xf bank_mask:0xf
	v_fmac_f32_dpp v46, v248, v12 row_newbcast:8 row_mask:0xf bank_mask:0xf
	s_nop 0
	v_pk_add_f32 v[42:43], v[42:43], v[146:147]
	v_mul_f32_dpp v146, v248, v234 row_newbcast:1 row_mask:0xf bank_mask:0xf
	v_mul_f32_dpp v147, v248, v2 row_newbcast:3 row_mask:0xf bank_mask:0xf
	v_fmac_f32_dpp v146, v248, v6 row_newbcast:5 row_mask:0xf bank_mask:0xf
	v_fmac_f32_dpp v47, v248, v18 row_newbcast:10 row_mask:0xf bank_mask:0xf
	v_fmac_f32_dpp v46, v248, v22 row_newbcast:12 row_mask:0xf bank_mask:0xf
	v_pk_add_f32 v[42:43], v[42:43], v[42:43] op_sel:[0,1] op_sel_hi:[1,0]
	v_fmac_f32_dpp v147, v248, v10 row_newbcast:7 row_mask:0xf bank_mask:0xf
	v_fmac_f32_dpp v146, v248, v14 row_newbcast:9 row_mask:0xf bank_mask:0xf
	v_fmac_f32_dpp v47, v248, v26 row_newbcast:14 row_mask:0xf bank_mask:0xf
	v_fmac_f32_dpp v46, v249, v32 row_newbcast:0 row_mask:0xf bank_mask:0xf
	s_waitcnt lgkmcnt(0)
; #define LAS __attribute__((address_space(3)))
; __device__ __forceinline__ void dn_prep_item(const Args& a, LAS unsigned char* lds, int item, int tid, int wave, int lane, int& cwh, int next_item) {
;     ...
;         { const LAS float* lrow = Lm + (lane & 15);
; #pragma unroll
;         for (int i = 1; i < 64; ++i) { float sa[4] = { x[i], 0.f, 0.f, 0.f };
;             int lr[4];
; #pragma unroll
;             for (int g = 0; g < (i + 15) / 16; ++g) lr[g] = __float_as_int(lrow[i * 68 + 16 * g]);
; #pragma unroll
;             for (int j = 0; j < i; ++j) { fmac_rowbcast_sel(sa[j & 3], lr[j >> 4], x[j], j); }
;             x[i] = (sa[0] + sa[1]) + (sa[2] + sa[3]); } }
	v_add_u32_e32 v254, 0xa000, v208
	ds_read2_b32 v[252:253], v254 offset0:28 offset1:44
	v_fmac_f32_dpp v72, v250, v71 row_newbcast:0 row_mask:0xf bank_mask:0xf
	v_mul_f32_dpp v73, v250, v235 row_newbcast:2 row_mask:0xf bank_mask:0xf
	v_fmac_f32_dpp v147, v248, v20 row_newbcast:11 row_mask:0xf bank_mask:0xf
	v_fmac_f32_dpp v146, v248, v24 row_newbcast:13 row_mask:0xf bank_mask:0xf
	v_fmac_f32_dpp v47, v249, v38 row_newbcast:2 row_mask:0xf bank_mask:0xf
	v_fmac_f32_dpp v46, v249, v42 row_newbcast:4 row_mask:0xf bank_mask:0xf
	s_nop 0
	v_fmac_f32_dpp v72, v250, v4 row_newbcast:4 row_mask:0xf bank_mask:0xf
	v_fmac_f32_dpp v73, v250, v8 row_newbcast:6 row_mask:0xf bank_mask:0xf
	v_fmac_f32_dpp v147, v248, v30 row_newbcast:15 row_mask:0xf bank_mask:0xf
	v_fmac_f32_dpp v146, v249, v34 row_newbcast:1 row_mask:0xf bank_mask:0xf
	v_add_u32_e32 v1, 0xa000, v208
	v_fmac_f32_dpp v147, v249, v40 row_newbcast:3 row_mask:0xf bank_mask:0xf
	v_fmac_f32_dpp v72, v250, v12 row_newbcast:8 row_mask:0xf bank_mask:0xf
	v_fmac_f32_dpp v73, v250, v18 row_newbcast:10 row_mask:0xf bank_mask:0xf
	v_pk_add_f32 v[46:47], v[46:47], v[146:147]
	v_mul_f32_dpp v146, v250, v234 row_newbcast:1 row_mask:0xf bank_mask:0xf
	v_fmac_f32_dpp v146, v250, v6 row_newbcast:5 row_mask:0xf bank_mask:0xf
	v_mul_f32_dpp v147, v250, v2 row_newbcast:3 row_mask:0xf bank_mask:0xf
	v_fmac_f32_dpp v72, v250, v22 row_newbcast:12 row_mask:0xf bank_mask:0xf
	v_fmac_f32_dpp v73, v250, v26 row_newbcast:14 row_mask:0xf bank_mask:0xf
	v_pk_add_f32 v[46:47], v[46:47], v[46:47] op_sel:[0,1] op_sel_hi:[1,0]
	v_fmac_f32_dpp v146, v250, v14 row_newbcast:9 row_mask:0xf bank_mask:0xf
	v_fmac_f32_dpp v147, v250, v10 row_newbcast:7 row_mask:0xf bank_mask:0xf
	v_fmac_f32_dpp v72, v251, v32 row_newbcast:0 row_mask:0xf bank_mask:0xf
	v_fmac_f32_dpp v73, v251, v38 row_newbcast:2 row_mask:0xf bank_mask:0xf
	s_nop 0
	v_fmac_f32_dpp v146, v250, v24 row_newbcast:13 row_mask:0xf bank_mask:0xf
	v_fmac_f32_dpp v147, v250, v20 row_newbcast:11 row_mask:0xf bank_mask:0xf
	v_fmac_f32_dpp v72, v251, v42 row_newbcast:4 row_mask:0xf bank_mask:0xf
	s_waitcnt lgkmcnt(0)
	v_add_u32_e32 v254, 0xa000, v208
	ds_read2_b32 v[242:243], v254 offset0:96 offset1:112
	v_fmac_f32_dpp v74, v252, v71 row_newbcast:0 row_mask:0xf bank_mask:0xf
	v_mul_f32_dpp v75, v252, v235 row_newbcast:2 row_mask:0xf bank_mask:0xf
	v_fmac_f32_dpp v146, v251, v34 row_newbcast:1 row_mask:0xf bank_mask:0xf
	v_fmac_f32_dpp v147, v250, v30 row_newbcast:15 row_mask:0xf bank_mask:0xf
	v_fmac_f32_dpp v74, v252, v4 row_newbcast:4 row_mask:0xf bank_mask:0xf
	v_fmac_f32_dpp v75, v252, v8 row_newbcast:6 row_mask:0xf bank_mask:0xf
	v_fmac_f32_dpp v146, v251, v46 row_newbcast:5 row_mask:0xf bank_mask:0xf
	v_fmac_f32_dpp v147, v251, v40 row_newbcast:3 row_mask:0xf bank_mask:0xf
	v_fmac_f32_dpp v74, v252, v12 row_newbcast:8 row_mask:0xf bank_mask:0xf
	v_fmac_f32_dpp v75, v252, v18 row_newbcast:10 row_mask:0xf bank_mask:0xf
	s_nop 0
	v_pk_add_f32 v[72:73], v[72:73], v[146:147]
	v_mul_f32_dpp v146, v252, v234 row_newbcast:1 row_mask:0xf bank_mask:0xf
	v_fmac_f32_dpp v146, v252, v6 row_newbcast:5 row_mask:0xf bank_mask:0xf
	v_mul_f32_dpp v147, v252, v2 row_newbcast:3 row_mask:0xf bank_mask:0xf
	v_fmac_f32_dpp v74, v252, v22 row_newbcast:12 row_mask:0xf bank_mask:0xf
	v_fmac_f32_dpp v75, v252, v26 row_newbcast:14 row_mask:0xf bank_mask:0xf
	v_pk_add_f32 v[72:73], v[72:73], v[72:73] op_sel:[0,1] op_sel_hi:[1,0]
	v_fmac_f32_dpp v146, v252, v14 row_newbcast:9 row_mask:0xf bank_mask:0xf
	v_fmac_f32_dpp v147, v252, v10 row_newbcast:7 row_mask:0xf bank_mask:0xf
	v_fmac_f32_dpp v74, v253, v32 row_newbcast:0 row_mask:0xf bank_mask:0xf
	v_fmac_f32_dpp v75, v253, v38 row_newbcast:2 row_mask:0xf bank_mask:0xf
	s_waitcnt lgkmcnt(0)
	v_add_u32_e32 v254, 0xa000, v208
	ds_read2_b32 v[246:247], v254 offset0:164 offset1:180
	v_fmac_f32_dpp v78, v242, v71 row_newbcast:0 row_mask:0xf bank_mask:0xf
	v_mul_f32_dpp v79, v242, v235 row_newbcast:2 row_mask:0xf bank_mask:0xf
	v_fmac_f32_dpp v146, v252, v24 row_newbcast:13 row_mask:0xf bank_mask:0xf
	v_fmac_f32_dpp v147, v252, v20 row_newbcast:11 row_mask:0xf bank_mask:0xf
	v_fmac_f32_dpp v74, v253, v42 row_newbcast:4 row_mask:0xf bank_mask:0xf
	v_fmac_f32_dpp v75, v253, v72 row_newbcast:6 row_mask:0xf bank_mask:0xf
	s_nop 0
	v_fmac_f32_dpp v78, v242, v4 row_newbcast:4 row_mask:0xf bank_mask:0xf
	v_fmac_f32_dpp v79, v242, v8 row_newbcast:6 row_mask:0xf bank_mask:0xf
	v_fmac_f32_dpp v146, v253, v34 row_newbcast:1 row_mask:0xf bank_mask:0xf
	v_fmac_f32_dpp v147, v252, v30 row_newbcast:15 row_mask:0xf bank_mask:0xf
	v_fmac_f32_dpp v146, v253, v46 row_newbcast:5 row_mask:0xf bank_mask:0xf
	v_fmac_f32_dpp v147, v253, v40 row_newbcast:3 row_mask:0xf bank_mask:0xf
	v_fmac_f32_dpp v78, v242, v12 row_newbcast:8 row_mask:0xf bank_mask:0xf
	v_fmac_f32_dpp v79, v242, v18 row_newbcast:10 row_mask:0xf bank_mask:0xf
	s_nop 0
	v_pk_add_f32 v[74:75], v[74:75], v[146:147]
	v_mul_f32_dpp v146, v242, v234 row_newbcast:1 row_mask:0xf bank_mask:0xf
	v_mul_f32_dpp v147, v242, v2 row_newbcast:3 row_mask:0xf bank_mask:0xf
	v_fmac_f32_dpp v146, v242, v6 row_newbcast:5 row_mask:0xf bank_mask:0xf
	v_fmac_f32_dpp v78, v242, v22 row_newbcast:12 row_mask:0xf bank_mask:0xf
	v_fmac_f32_dpp v79, v242, v26 row_newbcast:14 row_mask:0xf bank_mask:0xf
	v_pk_add_f32 v[74:75], v[74:75], v[74:75] op_sel:[0,1] op_sel_hi:[1,0]
	v_fmac_f32_dpp v147, v242, v10 row_newbcast:7 row_mask:0xf bank_mask:0xf
	v_fmac_f32_dpp v146, v242, v14 row_newbcast:9 row_mask:0xf bank_mask:0xf
	v_fmac_f32_dpp v78, v243, v32 row_newbcast:0 row_mask:0xf bank_mask:0xf
	v_fmac_f32_dpp v79, v243, v38 row_newbcast:2 row_mask:0xf bank_mask:0xf
	s_waitcnt lgkmcnt(0)
; #define LAS __attribute__((address_space(3)))
; __device__ __forceinline__ void dn_prep_item(const Args& a, LAS unsigned char* lds, int item, int tid, int wave, int lane, int& cwh, int next_item) {
;     ...
;         { const LAS float* lrow = Lm + (lane & 15);
; #pragma unroll
;         for (int i = 1; i < 64; ++i) { float sa[4] = { x[i], 0.f, 0.f, 0.f };
;             int lr[4];
; #pragma unroll
;             for (int g = 0; g < (i + 15) / 16; ++g) lr[g] = __float_as_int(lrow[i * 68 + 16 * g]);
; #pragma unroll
;             for (int j = 0; j < i; ++j) { fmac_rowbcast_sel(sa[j & 3], lr[j >> 4], x[j], j); }
;             x[i] = (sa[0] + sa[1]) + (sa[2] + sa[3]); } }
	v_add_u32_e32 v254, 0xa000, v208
	ds_read2_b32 v[248:249], v254 offset0:232 offset1:248
	v_fmac_f32_dpp v80, v246, v71 row_newbcast:0 row_mask:0xf bank_mask:0xf
	v_mul_f32_dpp v81, v246, v235 row_newbcast:2 row_mask:0xf bank_mask:0xf
	v_fmac_f32_dpp v147, v242, v20 row_newbcast:11 row_mask:0xf bank_mask:0xf
	v_fmac_f32_dpp v146, v242, v24 row_newbcast:13 row_mask:0xf bank_mask:0xf
	v_fmac_f32_dpp v78, v243, v42 row_newbcast:4 row_mask:0xf bank_mask:0xf
	v_fmac_f32_dpp v79, v243, v72 row_newbcast:6 row_mask:0xf bank_mask:0xf
	s_nop 0
	v_fmac_f32_dpp v80, v246, v4 row_newbcast:4 row_mask:0xf bank_mask:0xf
	v_fmac_f32_dpp v81, v246, v8 row_newbcast:6 row_mask:0xf bank_mask:0xf
	v_fmac_f32_dpp v147, v242, v30 row_newbcast:15 row_mask:0xf bank_mask:0xf
	v_fmac_f32_dpp v146, v243, v34 row_newbcast:1 row_mask:0xf bank_mask:0xf
	v_fmac_f32_dpp v147, v243, v40 row_newbcast:3 row_mask:0xf bank_mask:0xf
	v_fmac_f32_dpp v146, v243, v46 row_newbcast:5 row_mask:0xf bank_mask:0xf
	v_fmac_f32_dpp v80, v246, v12 row_newbcast:8 row_mask:0xf bank_mask:0xf
	v_fmac_f32_dpp v81, v246, v18 row_newbcast:10 row_mask:0xf bank_mask:0xf
	v_fmac_f32_dpp v147, v243, v74 row_newbcast:7 row_mask:0xf bank_mask:0xf
	v_fmac_f32_dpp v80, v246, v22 row_newbcast:12 row_mask:0xf bank_mask:0xf
	v_fmac_f32_dpp v81, v246, v26 row_newbcast:14 row_mask:0xf bank_mask:0xf
	s_nop 0
	v_pk_add_f32 v[78:79], v[78:79], v[146:147]
	v_mul_f32_dpp v146, v246, v234 row_newbcast:1 row_mask:0xf bank_mask:0xf
	v_mul_f32_dpp v147, v246, v2 row_newbcast:3 row_mask:0xf bank_mask:0xf
	v_fmac_f32_dpp v146, v246, v6 row_newbcast:5 row_mask:0xf bank_mask:0xf
	v_fmac_f32_dpp v80, v247, v32 row_newbcast:0 row_mask:0xf bank_mask:0xf
	v_fmac_f32_dpp v81, v247, v38 row_newbcast:2 row_mask:0xf bank_mask:0xf
	v_pk_add_f32 v[78:79], v[78:79], v[78:79] op_sel:[0,1] op_sel_hi:[1,0]
	v_fmac_f32_dpp v147, v246, v10 row_newbcast:7 row_mask:0xf bank_mask:0xf
	v_fmac_f32_dpp v146, v246, v14 row_newbcast:9 row_mask:0xf bank_mask:0xf
	v_fmac_f32_dpp v80, v247, v42 row_newbcast:4 row_mask:0xf bank_mask:0xf
	v_fmac_f32_dpp v81, v247, v72 row_newbcast:6 row_mask:0xf bank_mask:0xf
	s_waitcnt lgkmcnt(0)
	v_add_u32_e32 v254, 0xa400, v208
	ds_read2_b32 v[250:251], v254 offset0:44 offset1:60
	v_fmac_f32_dpp v84, v248, v71 row_newbcast:0 row_mask:0xf bank_mask:0xf
	v_mul_f32_dpp v85, v248, v235 row_newbcast:2 row_mask:0xf bank_mask:0xf
	v_fmac_f32_dpp v147, v246, v20 row_newbcast:11 row_mask:0xf bank_mask:0xf
	v_fmac_f32_dpp v146, v246, v24 row_newbcast:13 row_mask:0xf bank_mask:0xf
	v_fmac_f32_dpp v80, v247, v78 row_newbcast:8 row_mask:0xf bank_mask:0xf
	v_add_u32_e32 v1, 0xa400, v208
	v_fmac_f32_dpp v147, v246, v30 row_newbcast:15 row_mask:0xf bank_mask:0xf
	v_fmac_f32_dpp v146, v247, v34 row_newbcast:1 row_mask:0xf bank_mask:0xf
	v_fmac_f32_dpp v84, v248, v4 row_newbcast:4 row_mask:0xf bank_mask:0xf
	v_fmac_f32_dpp v85, v248, v8 row_newbcast:6 row_mask:0xf bank_mask:0xf
	v_fmac_f32_dpp v147, v247, v40 row_newbcast:3 row_mask:0xf bank_mask:0xf
	v_fmac_f32_dpp v146, v247, v46 row_newbcast:5 row_mask:0xf bank_mask:0xf
	v_fmac_f32_dpp v84, v248, v12 row_newbcast:8 row_mask:0xf bank_mask:0xf
	v_fmac_f32_dpp v85, v248, v18 row_newbcast:10 row_mask:0xf bank_mask:0xf
	v_fmac_f32_dpp v147, v247, v74 row_newbcast:7 row_mask:0xf bank_mask:0xf
	v_fmac_f32_dpp v84, v248, v22 row_newbcast:12 row_mask:0xf bank_mask:0xf
	v_fmac_f32_dpp v85, v248, v26 row_newbcast:14 row_mask:0xf bank_mask:0xf
	s_nop 0
	v_pk_add_f32 v[80:81], v[80:81], v[146:147]
	v_mul_f32_dpp v146, v248, v234 row_newbcast:1 row_mask:0xf bank_mask:0xf
	v_fmac_f32_dpp v146, v248, v6 row_newbcast:5 row_mask:0xf bank_mask:0xf
	v_mul_f32_dpp v147, v248, v2 row_newbcast:3 row_mask:0xf bank_mask:0xf
	v_fmac_f32_dpp v84, v249, v32 row_newbcast:0 row_mask:0xf bank_mask:0xf
	v_fmac_f32_dpp v85, v249, v38 row_newbcast:2 row_mask:0xf bank_mask:0xf
	v_pk_add_f32 v[80:81], v[80:81], v[80:81] op_sel:[0,1] op_sel_hi:[1,0]
	v_fmac_f32_dpp v146, v248, v14 row_newbcast:9 row_mask:0xf bank_mask:0xf
	v_fmac_f32_dpp v147, v248, v10 row_newbcast:7 row_mask:0xf bank_mask:0xf
	v_fmac_f32_dpp v84, v249, v42 row_newbcast:4 row_mask:0xf bank_mask:0xf
	v_fmac_f32_dpp v85, v249, v72 row_newbcast:6 row_mask:0xf bank_mask:0xf
	s_waitcnt lgkmcnt(0)
	v_add_u32_e32 v254, 0xa400, v208
	ds_read2_b32 v[252:253], v254 offset0:112 offset1:128
	v_fmac_f32_dpp v86, v250, v71 row_newbcast:0 row_mask:0xf bank_mask:0xf
	v_mul_f32_dpp v87, v250, v235 row_newbcast:2 row_mask:0xf bank_mask:0xf
	v_fmac_f32_dpp v146, v248, v24 row_newbcast:13 row_mask:0xf bank_mask:0xf
	v_fmac_f32_dpp v147, v248, v20 row_newbcast:11 row_mask:0xf bank_mask:0xf
	v_fmac_f32_dpp v84, v249, v78 row_newbcast:8 row_mask:0xf bank_mask:0xf
	v_fmac_f32_dpp v146, v249, v34 row_newbcast:1 row_mask:0xf bank_mask:0xf
	v_fmac_f32_dpp v147, v248, v30 row_newbcast:15 row_mask:0xf bank_mask:0xf
	v_fmac_f32_dpp v86, v250, v4 row_newbcast:4 row_mask:0xf bank_mask:0xf
	v_fmac_f32_dpp v87, v250, v8 row_newbcast:6 row_mask:0xf bank_mask:0xf
	v_mov_b32_e32 v103, v57
	v_fmac_f32_dpp v146, v249, v46 row_newbcast:5 row_mask:0xf bank_mask:0xf
	v_fmac_f32_dpp v147, v249, v40 row_newbcast:3 row_mask:0xf bank_mask:0xf
	v_fmac_f32_dpp v86, v250, v12 row_newbcast:8 row_mask:0xf bank_mask:0xf
	v_fmac_f32_dpp v87, v250, v18 row_newbcast:10 row_mask:0xf bank_mask:0xf
	v_mov_b32_e32 v107, v57
	v_fmac_f32_dpp v146, v249, v80 row_newbcast:9 row_mask:0xf bank_mask:0xf
	v_fmac_f32_dpp v147, v249, v74 row_newbcast:7 row_mask:0xf bank_mask:0xf
	v_fmac_f32_dpp v86, v250, v22 row_newbcast:12 row_mask:0xf bank_mask:0xf
	v_fmac_f32_dpp v87, v250, v26 row_newbcast:14 row_mask:0xf bank_mask:0xf
	s_nop 0
	v_pk_add_f32 v[84:85], v[84:85], v[146:147]
	v_mul_f32_dpp v146, v250, v234 row_newbcast:1 row_mask:0xf bank_mask:0xf
	v_fmac_f32_dpp v146, v250, v6 row_newbcast:5 row_mask:0xf bank_mask:0xf
	v_mul_f32_dpp v147, v250, v2 row_newbcast:3 row_mask:0xf bank_mask:0xf
	v_fmac_f32_dpp v86, v251, v32 row_newbcast:0 row_mask:0xf bank_mask:0xf
	v_fmac_f32_dpp v87, v251, v38 row_newbcast:2 row_mask:0xf bank_mask:0xf
	v_pk_add_f32 v[84:85], v[84:85], v[84:85] op_sel:[0,1] op_sel_hi:[1,0]
	v_fmac_f32_dpp v146, v250, v14 row_newbcast:9 row_mask:0xf bank_mask:0xf
	v_fmac_f32_dpp v147, v250, v10 row_newbcast:7 row_mask:0xf bank_mask:0xf
	v_fmac_f32_dpp v86, v251, v42 row_newbcast:4 row_mask:0xf bank_mask:0xf
	v_fmac_f32_dpp v87, v251, v72 row_newbcast:6 row_mask:0xf bank_mask:0xf
	s_waitcnt lgkmcnt(0)
; #define LAS __attribute__((address_space(3)))
; __device__ __forceinline__ void dn_prep_item(const Args& a, LAS unsigned char* lds, int item, int tid, int wave, int lane, int& cwh, int next_item) {
;     ...
;         { const LAS float* lrow = Lm + (lane & 15);
; #pragma unroll
;         for (int i = 1; i < 64; ++i) { float sa[4] = { x[i], 0.f, 0.f, 0.f };
;             int lr[4];
; #pragma unroll
;             for (int g = 0; g < (i + 15) / 16; ++g) lr[g] = __float_as_int(lrow[i * 68 + 16 * g]);
; #pragma unroll
;             for (int j = 0; j < i; ++j) { fmac_rowbcast_sel(sa[j & 3], lr[j >> 4], x[j], j); }
;             x[i] = (sa[0] + sa[1]) + (sa[2] + sa[3]); } }
	v_add_u32_e32 v254, 0xa400, v208
	ds_read2_b32 v[242:243], v254 offset0:180 offset1:196
	v_fmac_f32_dpp v90, v252, v71 row_newbcast:0 row_mask:0xf bank_mask:0xf
	v_mul_f32_dpp v91, v252, v235 row_newbcast:2 row_mask:0xf bank_mask:0xf
	v_fmac_f32_dpp v146, v250, v24 row_newbcast:13 row_mask:0xf bank_mask:0xf
	v_fmac_f32_dpp v147, v250, v20 row_newbcast:11 row_mask:0xf bank_mask:0xf
	v_fmac_f32_dpp v86, v251, v78 row_newbcast:8 row_mask:0xf bank_mask:0xf
	v_fmac_f32_dpp v87, v251, v84 row_newbcast:10 row_mask:0xf bank_mask:0xf
	s_nop 0
	v_fmac_f32_dpp v90, v252, v4 row_newbcast:4 row_mask:0xf bank_mask:0xf
	v_fmac_f32_dpp v91, v252, v8 row_newbcast:6 row_mask:0xf bank_mask:0xf
	v_fmac_f32_dpp v146, v251, v34 row_newbcast:1 row_mask:0xf bank_mask:0xf
	v_fmac_f32_dpp v147, v250, v30 row_newbcast:15 row_mask:0xf bank_mask:0xf
	v_mov_b32_e32 v109, v57
	v_fmac_f32_dpp v146, v251, v46 row_newbcast:5 row_mask:0xf bank_mask:0xf
	v_fmac_f32_dpp v147, v251, v40 row_newbcast:3 row_mask:0xf bank_mask:0xf
	v_fmac_f32_dpp v90, v252, v12 row_newbcast:8 row_mask:0xf bank_mask:0xf
	v_fmac_f32_dpp v91, v252, v18 row_newbcast:10 row_mask:0xf bank_mask:0xf
	v_mov_b32_e32 v113, v57
	v_fmac_f32_dpp v146, v251, v80 row_newbcast:9 row_mask:0xf bank_mask:0xf
	v_fmac_f32_dpp v147, v251, v74 row_newbcast:7 row_mask:0xf bank_mask:0xf
	v_fmac_f32_dpp v90, v252, v22 row_newbcast:12 row_mask:0xf bank_mask:0xf
	v_fmac_f32_dpp v91, v252, v26 row_newbcast:14 row_mask:0xf bank_mask:0xf
	s_nop 0
	v_pk_add_f32 v[86:87], v[86:87], v[146:147]
	v_mul_f32_dpp v146, v252, v234 row_newbcast:1 row_mask:0xf bank_mask:0xf
	v_mul_f32_dpp v147, v252, v2 row_newbcast:3 row_mask:0xf bank_mask:0xf
	v_fmac_f32_dpp v146, v252, v6 row_newbcast:5 row_mask:0xf bank_mask:0xf
	v_fmac_f32_dpp v90, v253, v32 row_newbcast:0 row_mask:0xf bank_mask:0xf
	v_fmac_f32_dpp v91, v253, v38 row_newbcast:2 row_mask:0xf bank_mask:0xf
	v_pk_add_f32 v[86:87], v[86:87], v[86:87] op_sel:[0,1] op_sel_hi:[1,0]
	v_fmac_f32_dpp v147, v252, v10 row_newbcast:7 row_mask:0xf bank_mask:0xf
	v_fmac_f32_dpp v146, v252, v14 row_newbcast:9 row_mask:0xf bank_mask:0xf
	v_fmac_f32_dpp v90, v253, v42 row_newbcast:4 row_mask:0xf bank_mask:0xf
	v_fmac_f32_dpp v91, v253, v72 row_newbcast:6 row_mask:0xf bank_mask:0xf
	s_waitcnt lgkmcnt(0)
	v_add_u32_e32 v254, 0xa600, v208
	ds_read2_b32 v[246:247], v254 offset0:120 offset1:136
	v_fmac_f32_dpp v92, v242, v71 row_newbcast:0 row_mask:0xf bank_mask:0xf
	v_mul_f32_dpp v93, v242, v235 row_newbcast:2 row_mask:0xf bank_mask:0xf
	v_fmac_f32_dpp v147, v252, v20 row_newbcast:11 row_mask:0xf bank_mask:0xf
	v_fmac_f32_dpp v146, v252, v24 row_newbcast:13 row_mask:0xf bank_mask:0xf
	v_fmac_f32_dpp v90, v253, v78 row_newbcast:8 row_mask:0xf bank_mask:0xf
	v_fmac_f32_dpp v91, v253, v84 row_newbcast:10 row_mask:0xf bank_mask:0xf
	s_nop 0
	v_fmac_f32_dpp v92, v242, v4 row_newbcast:4 row_mask:0xf bank_mask:0xf
	v_fmac_f32_dpp v93, v242, v8 row_newbcast:6 row_mask:0xf bank_mask:0xf
	v_fmac_f32_dpp v147, v252, v30 row_newbcast:15 row_mask:0xf bank_mask:0xf
	v_fmac_f32_dpp v146, v253, v34 row_newbcast:1 row_mask:0xf bank_mask:0xf
	v_add_u32_e32 v1, 0xa600, v208
	v_fmac_f32_dpp v147, v253, v40 row_newbcast:3 row_mask:0xf bank_mask:0xf
	v_fmac_f32_dpp v146, v253, v46 row_newbcast:5 row_mask:0xf bank_mask:0xf
	v_fmac_f32_dpp v92, v242, v12 row_newbcast:8 row_mask:0xf bank_mask:0xf
	v_fmac_f32_dpp v93, v242, v18 row_newbcast:10 row_mask:0xf bank_mask:0xf
	v_mov_b32_e32 v117, v57
	v_fmac_f32_dpp v147, v253, v74 row_newbcast:7 row_mask:0xf bank_mask:0xf
	v_fmac_f32_dpp v146, v253, v80 row_newbcast:9 row_mask:0xf bank_mask:0xf
	v_fmac_f32_dpp v92, v242, v22 row_newbcast:12 row_mask:0xf bank_mask:0xf
	v_fmac_f32_dpp v93, v242, v26 row_newbcast:14 row_mask:0xf bank_mask:0xf
	v_mov_b32_e32 v119, v57
	v_fmac_f32_dpp v147, v253, v86 row_newbcast:11 row_mask:0xf bank_mask:0xf
	v_fmac_f32_dpp v92, v243, v32 row_newbcast:0 row_mask:0xf bank_mask:0xf
	v_fmac_f32_dpp v93, v243, v38 row_newbcast:2 row_mask:0xf bank_mask:0xf
	s_nop 0
	v_pk_add_f32 v[90:91], v[90:91], v[146:147]
	v_mul_f32_dpp v146, v242, v234 row_newbcast:1 row_mask:0xf bank_mask:0xf
	v_mul_f32_dpp v147, v242, v2 row_newbcast:3 row_mask:0xf bank_mask:0xf
	v_fmac_f32_dpp v146, v242, v6 row_newbcast:5 row_mask:0xf bank_mask:0xf
	v_fmac_f32_dpp v92, v243, v42 row_newbcast:4 row_mask:0xf bank_mask:0xf
	v_fmac_f32_dpp v93, v243, v72 row_newbcast:6 row_mask:0xf bank_mask:0xf
	v_pk_add_f32 v[90:91], v[90:91], v[90:91] op_sel:[0,1] op_sel_hi:[1,0]
	v_fmac_f32_dpp v147, v242, v10 row_newbcast:7 row_mask:0xf bank_mask:0xf
	v_fmac_f32_dpp v146, v242, v14 row_newbcast:9 row_mask:0xf bank_mask:0xf
	v_fmac_f32_dpp v92, v243, v78 row_newbcast:8 row_mask:0xf bank_mask:0xf
	v_fmac_f32_dpp v93, v243, v84 row_newbcast:10 row_mask:0xf bank_mask:0xf
	s_waitcnt lgkmcnt(0)
; #define LAS __attribute__((address_space(3)))
; __device__ __forceinline__ void dn_prep_item(const Args& a, LAS unsigned char* lds, int item, int tid, int wave, int lane, int& cwh, int next_item) {
;     ...
;         { const LAS float* lrow = Lm + (lane & 15);
; #pragma unroll
;         for (int i = 1; i < 64; ++i) { float sa[4] = { x[i], 0.f, 0.f, 0.f };
;             int lr[4];
; #pragma unroll
;             for (int g = 0; g < (i + 15) / 16; ++g) lr[g] = __float_as_int(lrow[i * 68 + 16 * g]);
; #pragma unroll
;             for (int j = 0; j < i; ++j) { fmac_rowbcast_sel(sa[j & 3], lr[j >> 4], x[j], j); }
;             x[i] = (sa[0] + sa[1]) + (sa[2] + sa[3]); } }
	v_add_u32_e32 v254, 0xa800, v208
	ds_read2_b32 v[248:249], v254 offset0:60 offset1:76
	v_fmac_f32_dpp v96, v246, v71 row_newbcast:0 row_mask:0xf bank_mask:0xf
	v_mul_f32_dpp v97, v246, v235 row_newbcast:2 row_mask:0xf bank_mask:0xf
	v_fmac_f32_dpp v147, v242, v20 row_newbcast:11 row_mask:0xf bank_mask:0xf
	v_fmac_f32_dpp v146, v242, v24 row_newbcast:13 row_mask:0xf bank_mask:0xf
	v_fmac_f32_dpp v92, v243, v90 row_newbcast:12 row_mask:0xf bank_mask:0xf
	v_add_u32_e32 v1, 0xa800, v208
	v_fmac_f32_dpp v147, v242, v30 row_newbcast:15 row_mask:0xf bank_mask:0xf
	v_fmac_f32_dpp v146, v243, v34 row_newbcast:1 row_mask:0xf bank_mask:0xf
	v_fmac_f32_dpp v96, v246, v4 row_newbcast:4 row_mask:0xf bank_mask:0xf
	v_fmac_f32_dpp v97, v246, v8 row_newbcast:6 row_mask:0xf bank_mask:0xf
	v_mov_b32_e32 v123, v57
	v_fmac_f32_dpp v147, v243, v40 row_newbcast:3 row_mask:0xf bank_mask:0xf
	v_fmac_f32_dpp v146, v243, v46 row_newbcast:5 row_mask:0xf bank_mask:0xf
	v_fmac_f32_dpp v96, v246, v12 row_newbcast:8 row_mask:0xf bank_mask:0xf
	v_fmac_f32_dpp v97, v246, v18 row_newbcast:10 row_mask:0xf bank_mask:0xf
	v_mov_b32_e32 v127, v57
	v_fmac_f32_dpp v147, v243, v74 row_newbcast:7 row_mask:0xf bank_mask:0xf
	v_fmac_f32_dpp v146, v243, v80 row_newbcast:9 row_mask:0xf bank_mask:0xf
	v_fmac_f32_dpp v96, v246, v22 row_newbcast:12 row_mask:0xf bank_mask:0xf
	v_fmac_f32_dpp v97, v246, v26 row_newbcast:14 row_mask:0xf bank_mask:0xf
	v_mov_b32_e32 v131, v57
	v_fmac_f32_dpp v147, v243, v86 row_newbcast:11 row_mask:0xf bank_mask:0xf
	v_fmac_f32_dpp v96, v247, v32 row_newbcast:0 row_mask:0xf bank_mask:0xf
	v_fmac_f32_dpp v97, v247, v38 row_newbcast:2 row_mask:0xf bank_mask:0xf
	s_nop 0
	v_pk_add_f32 v[92:93], v[92:93], v[146:147]
	v_mul_f32_dpp v146, v246, v234 row_newbcast:1 row_mask:0xf bank_mask:0xf
	v_fmac_f32_dpp v146, v246, v6 row_newbcast:5 row_mask:0xf bank_mask:0xf
	v_mul_f32_dpp v147, v246, v2 row_newbcast:3 row_mask:0xf bank_mask:0xf
	v_fmac_f32_dpp v96, v247, v42 row_newbcast:4 row_mask:0xf bank_mask:0xf
	v_fmac_f32_dpp v97, v247, v72 row_newbcast:6 row_mask:0xf bank_mask:0xf
	v_pk_add_f32 v[92:93], v[92:93], v[92:93] op_sel:[0,1] op_sel_hi:[1,0]
	v_fmac_f32_dpp v146, v246, v14 row_newbcast:9 row_mask:0xf bank_mask:0xf
	v_fmac_f32_dpp v147, v246, v10 row_newbcast:7 row_mask:0xf bank_mask:0xf
	v_fmac_f32_dpp v96, v247, v78 row_newbcast:8 row_mask:0xf bank_mask:0xf
	v_fmac_f32_dpp v97, v247, v84 row_newbcast:10 row_mask:0xf bank_mask:0xf
	s_waitcnt lgkmcnt(0)
	v_add_u32_e32 v254, 0xa800, v208
	ds_read2_b32 v[250:251], v254 offset0:128 offset1:144
	v_fmac_f32_dpp v98, v248, v71 row_newbcast:0 row_mask:0xf bank_mask:0xf
	v_mul_f32_dpp v99, v248, v235 row_newbcast:2 row_mask:0xf bank_mask:0xf
	v_fmac_f32_dpp v146, v246, v24 row_newbcast:13 row_mask:0xf bank_mask:0xf
	v_fmac_f32_dpp v147, v246, v20 row_newbcast:11 row_mask:0xf bank_mask:0xf
	v_fmac_f32_dpp v96, v247, v90 row_newbcast:12 row_mask:0xf bank_mask:0xf
	v_mov_b32_e32 v135, v57
	v_fmac_f32_dpp v146, v247, v34 row_newbcast:1 row_mask:0xf bank_mask:0xf
	v_fmac_f32_dpp v147, v246, v30 row_newbcast:15 row_mask:0xf bank_mask:0xf
	v_fmac_f32_dpp v98, v248, v4 row_newbcast:4 row_mask:0xf bank_mask:0xf
	v_fmac_f32_dpp v99, v248, v8 row_newbcast:6 row_mask:0xf bank_mask:0xf
	v_mov_b32_e32 v139, v57
	v_fmac_f32_dpp v146, v247, v46 row_newbcast:5 row_mask:0xf bank_mask:0xf
	v_fmac_f32_dpp v147, v247, v40 row_newbcast:3 row_mask:0xf bank_mask:0xf
	v_fmac_f32_dpp v98, v248, v12 row_newbcast:8 row_mask:0xf bank_mask:0xf
	v_fmac_f32_dpp v99, v248, v18 row_newbcast:10 row_mask:0xf bank_mask:0xf
	v_mov_b32_e32 v143, v57
	v_fmac_f32_dpp v146, v247, v80 row_newbcast:9 row_mask:0xf bank_mask:0xf
	v_fmac_f32_dpp v147, v247, v74 row_newbcast:7 row_mask:0xf bank_mask:0xf
	v_fmac_f32_dpp v98, v248, v22 row_newbcast:12 row_mask:0xf bank_mask:0xf
	v_fmac_f32_dpp v99, v248, v26 row_newbcast:14 row_mask:0xf bank_mask:0xf
	v_mov_b32_e32 v145, v57
	v_fmac_f32_dpp v146, v247, v92 row_newbcast:13 row_mask:0xf bank_mask:0xf
	v_fmac_f32_dpp v147, v247, v86 row_newbcast:11 row_mask:0xf bank_mask:0xf
	v_fmac_f32_dpp v98, v249, v32 row_newbcast:0 row_mask:0xf bank_mask:0xf
	v_fmac_f32_dpp v99, v249, v38 row_newbcast:2 row_mask:0xf bank_mask:0xf
	s_nop 0
	v_pk_add_f32 v[96:97], v[96:97], v[146:147]
	v_mul_f32_dpp v146, v248, v234 row_newbcast:1 row_mask:0xf bank_mask:0xf
	v_mul_f32_dpp v147, v248, v2 row_newbcast:3 row_mask:0xf bank_mask:0xf
	v_fmac_f32_dpp v146, v248, v6 row_newbcast:5 row_mask:0xf bank_mask:0xf
	v_fmac_f32_dpp v98, v249, v42 row_newbcast:4 row_mask:0xf bank_mask:0xf
	v_fmac_f32_dpp v99, v249, v72 row_newbcast:6 row_mask:0xf bank_mask:0xf
	v_pk_add_f32 v[96:97], v[96:97], v[96:97] op_sel:[0,1] op_sel_hi:[1,0]
	v_fmac_f32_dpp v147, v248, v10 row_newbcast:7 row_mask:0xf bank_mask:0xf
	v_fmac_f32_dpp v146, v248, v14 row_newbcast:9 row_mask:0xf bank_mask:0xf
	v_fmac_f32_dpp v98, v249, v78 row_newbcast:8 row_mask:0xf bank_mask:0xf
	v_fmac_f32_dpp v99, v249, v84 row_newbcast:10 row_mask:0xf bank_mask:0xf
	s_waitcnt lgkmcnt(0)
; #define LAS __attribute__((address_space(3)))
; __device__ __forceinline__ void dn_prep_item(const Args& a, LAS unsigned char* lds, int item, int tid, int wave, int lane, int& cwh, int next_item) {
;     ...
;         { const LAS float* lrow = Lm + (lane & 15);
; #pragma unroll
;         for (int i = 1; i < 64; ++i) { float sa[4] = { x[i], 0.f, 0.f, 0.f };
;             int lr[4];
; #pragma unroll
;             for (int g = 0; g < (i + 15) / 16; ++g) lr[g] = __float_as_int(lrow[i * 68 + 16 * g]);
; #pragma unroll
;             for (int j = 0; j < i; ++j) { fmac_rowbcast_sel(sa[j & 3], lr[j >> 4], x[j], j); }
;             x[i] = (sa[0] + sa[1]) + (sa[2] + sa[3]); } }
	v_add_u32_e32 v254, 0xa800, v208
	ds_read2_b32 v[252:253], v254 offset0:196 offset1:212
	v_fmac_f32_dpp v102, v250, v71 row_newbcast:0 row_mask:0xf bank_mask:0xf
	v_fmac_f32_dpp v103, v250, v235 row_newbcast:2 row_mask:0xf bank_mask:0xf
	v_fmac_f32_dpp v147, v248, v20 row_newbcast:11 row_mask:0xf bank_mask:0xf
	v_fmac_f32_dpp v146, v248, v24 row_newbcast:13 row_mask:0xf bank_mask:0xf
	v_fmac_f32_dpp v98, v249, v90 row_newbcast:12 row_mask:0xf bank_mask:0xf
	v_fmac_f32_dpp v99, v249, v96 row_newbcast:14 row_mask:0xf bank_mask:0xf
	s_nop 0
	v_fmac_f32_dpp v102, v250, v4 row_newbcast:4 row_mask:0xf bank_mask:0xf
	v_fmac_f32_dpp v103, v250, v8 row_newbcast:6 row_mask:0xf bank_mask:0xf
	v_fmac_f32_dpp v147, v248, v30 row_newbcast:15 row_mask:0xf bank_mask:0xf
	v_fmac_f32_dpp v146, v249, v34 row_newbcast:1 row_mask:0xf bank_mask:0xf
	v_fmac_f32_dpp v147, v249, v40 row_newbcast:3 row_mask:0xf bank_mask:0xf
	v_fmac_f32_dpp v146, v249, v46 row_newbcast:5 row_mask:0xf bank_mask:0xf
	v_fmac_f32_dpp v102, v250, v12 row_newbcast:8 row_mask:0xf bank_mask:0xf
	v_fmac_f32_dpp v103, v250, v18 row_newbcast:10 row_mask:0xf bank_mask:0xf
	v_mov_b32_e32 v141, v57
	v_fmac_f32_dpp v147, v249, v74 row_newbcast:7 row_mask:0xf bank_mask:0xf
	v_fmac_f32_dpp v146, v249, v80 row_newbcast:9 row_mask:0xf bank_mask:0xf
	v_fmac_f32_dpp v102, v250, v22 row_newbcast:12 row_mask:0xf bank_mask:0xf
	v_fmac_f32_dpp v103, v250, v26 row_newbcast:14 row_mask:0xf bank_mask:0xf
	v_mov_b32_e32 v137, v57
	v_fmac_f32_dpp v147, v249, v86 row_newbcast:11 row_mask:0xf bank_mask:0xf
	v_fmac_f32_dpp v146, v249, v92 row_newbcast:13 row_mask:0xf bank_mask:0xf
	v_fmac_f32_dpp v102, v251, v32 row_newbcast:0 row_mask:0xf bank_mask:0xf
	v_fmac_f32_dpp v103, v251, v38 row_newbcast:2 row_mask:0xf bank_mask:0xf
	v_pk_add_f32 v[98:99], v[98:99], v[146:147]
	v_mul_f32_dpp v146, v250, v234 row_newbcast:1 row_mask:0xf bank_mask:0xf
	v_mul_f32_dpp v147, v250, v2 row_newbcast:3 row_mask:0xf bank_mask:0xf
	v_fmac_f32_dpp v102, v251, v42 row_newbcast:4 row_mask:0xf bank_mask:0xf
	v_fmac_f32_dpp v103, v251, v72 row_newbcast:6 row_mask:0xf bank_mask:0xf
	v_pk_add_f32 v[98:99], v[98:99], v[98:99] op_sel:[0,1] op_sel_hi:[1,0]
	v_fmac_f32_dpp v146, v250, v6 row_newbcast:5 row_mask:0xf bank_mask:0xf
	v_fmac_f32_dpp v147, v250, v10 row_newbcast:7 row_mask:0xf bank_mask:0xf
	v_fmac_f32_dpp v102, v251, v78 row_newbcast:8 row_mask:0xf bank_mask:0xf
	v_fmac_f32_dpp v103, v251, v84 row_newbcast:10 row_mask:0xf bank_mask:0xf
	v_mov_b32_e32 v133, v57
	v_fmac_f32_dpp v146, v250, v14 row_newbcast:9 row_mask:0xf bank_mask:0xf
	v_fmac_f32_dpp v147, v250, v20 row_newbcast:11 row_mask:0xf bank_mask:0xf
	v_fmac_f32_dpp v102, v251, v90 row_newbcast:12 row_mask:0xf bank_mask:0xf
	v_fmac_f32_dpp v103, v251, v96 row_newbcast:14 row_mask:0xf bank_mask:0xf
	v_mov_b32_e32 v129, v57
	v_fmac_f32_dpp v146, v250, v24 row_newbcast:13 row_mask:0xf bank_mask:0xf
	v_fmac_f32_dpp v147, v250, v30 row_newbcast:15 row_mask:0xf bank_mask:0xf
	v_mov_b32_e32 v125, v57
	v_fmac_f32_dpp v146, v251, v34 row_newbcast:1 row_mask:0xf bank_mask:0xf
	v_fmac_f32_dpp v147, v251, v40 row_newbcast:3 row_mask:0xf bank_mask:0xf
	v_mov_b32_e32 v121, v57
	v_fmac_f32_dpp v146, v251, v46 row_newbcast:5 row_mask:0xf bank_mask:0xf
	v_fmac_f32_dpp v147, v251, v74 row_newbcast:7 row_mask:0xf bank_mask:0xf
	v_mov_b32_e32 v115, v57
	v_fmac_f32_dpp v146, v251, v80 row_newbcast:9 row_mask:0xf bank_mask:0xf
	v_fmac_f32_dpp v147, v251, v86 row_newbcast:11 row_mask:0xf bank_mask:0xf
	v_mov_b32_e32 v111, v57
	v_fmac_f32_dpp v146, v251, v92 row_newbcast:13 row_mask:0xf bank_mask:0xf
	v_fmac_f32_dpp v147, v251, v98 row_newbcast:15 row_mask:0xf bank_mask:0xf
	s_nop 0
	s_waitcnt lgkmcnt(0)
	v_add_u32_e32 v254, 0xaa00, v208
	ds_read2_b32 v[242:243], v254 offset0:100 offset1:136
	v_fmac_f32_dpp v106, v252, v71 row_newbcast:0 row_mask:0xf bank_mask:0xf
	v_mul_f32_dpp v238, v252, v234 row_newbcast:1 row_mask:0xf bank_mask:0xf
	v_fmac_f32_dpp v107, v252, v235 row_newbcast:2 row_mask:0xf bank_mask:0xf
	v_mul_f32_dpp v239, v252, v2 row_newbcast:3 row_mask:0xf bank_mask:0xf
	v_pk_add_f32 v[102:103], v[102:103], v[146:147]
	v_fmac_f32_dpp v106, v252, v4 row_newbcast:4 row_mask:0xf bank_mask:0xf
	v_fmac_f32_dpp v238, v252, v6 row_newbcast:5 row_mask:0xf bank_mask:0xf
	v_fmac_f32_dpp v107, v252, v8 row_newbcast:6 row_mask:0xf bank_mask:0xf
	v_fmac_f32_dpp v239, v252, v10 row_newbcast:7 row_mask:0xf bank_mask:0xf
	v_add_u32_e32 v1, 0xaa00, v208
	v_fmac_f32_dpp v106, v252, v12 row_newbcast:8 row_mask:0xf bank_mask:0xf
	v_fmac_f32_dpp v238, v252, v14 row_newbcast:9 row_mask:0xf bank_mask:0xf
	v_fmac_f32_dpp v107, v252, v18 row_newbcast:10 row_mask:0xf bank_mask:0xf
	v_fmac_f32_dpp v239, v252, v20 row_newbcast:11 row_mask:0xf bank_mask:0xf
	v_pk_add_f32 v[102:103], v[102:103], v[102:103] op_sel:[0,1] op_sel_hi:[1,0]
	v_fmac_f32_dpp v106, v252, v22 row_newbcast:12 row_mask:0xf bank_mask:0xf
	v_fmac_f32_dpp v238, v252, v24 row_newbcast:13 row_mask:0xf bank_mask:0xf
	v_fmac_f32_dpp v107, v252, v26 row_newbcast:14 row_mask:0xf bank_mask:0xf
	v_fmac_f32_dpp v239, v252, v30 row_newbcast:15 row_mask:0xf bank_mask:0xf
	s_nop 0
	v_fmac_f32_dpp v106, v253, v32 row_newbcast:0 row_mask:0xf bank_mask:0xf
	v_fmac_f32_dpp v238, v253, v34 row_newbcast:1 row_mask:0xf bank_mask:0xf
	v_fmac_f32_dpp v107, v253, v38 row_newbcast:2 row_mask:0xf bank_mask:0xf
	v_fmac_f32_dpp v239, v253, v40 row_newbcast:3 row_mask:0xf bank_mask:0xf
	s_waitcnt lgkmcnt(0)
; #define LAS __attribute__((address_space(3)))
; __device__ __forceinline__ void dn_prep_item(const Args& a, LAS unsigned char* lds, int item, int tid, int wave, int lane, int& cwh, int next_item) {
;     ...
;         { const LAS float* lrow = Lm + (lane & 15);
; #pragma unroll
;         for (int i = 1; i < 64; ++i) { float sa[4] = { x[i], 0.f, 0.f, 0.f };
;             int lr[4];
; #pragma unroll
;             for (int g = 0; g < (i + 15) / 16; ++g) lr[g] = __float_as_int(lrow[i * 68 + 16 * g]);
; #pragma unroll
;             for (int j = 0; j < i; ++j) { fmac_rowbcast_sel(sa[j & 3], lr[j >> 4], x[j], j); }
;             x[i] = (sa[0] + sa[1]) + (sa[2] + sa[3]); } }
	v_add_u32_e32 v254, 0xac00, v208
	ds_read2_b32 v[246:247], v254 offset0:24 offset1:40
	v_fmac_f32_dpp v108, v243, v71 row_newbcast:0 row_mask:0xf bank_mask:0xf
	v_fmac_f32_dpp v109, v243, v235 row_newbcast:2 row_mask:0xf bank_mask:0xf
	v_fmac_f32_dpp v106, v253, v42 row_newbcast:4 row_mask:0xf bank_mask:0xf
	v_fmac_f32_dpp v238, v253, v46 row_newbcast:5 row_mask:0xf bank_mask:0xf
	v_fmac_f32_dpp v107, v253, v72 row_newbcast:6 row_mask:0xf bank_mask:0xf
	v_fmac_f32_dpp v239, v253, v74 row_newbcast:7 row_mask:0xf bank_mask:0xf
	s_nop 0
	v_fmac_f32_dpp v108, v243, v4 row_newbcast:4 row_mask:0xf bank_mask:0xf
	v_fmac_f32_dpp v109, v243, v8 row_newbcast:6 row_mask:0xf bank_mask:0xf
	v_fmac_f32_dpp v106, v253, v78 row_newbcast:8 row_mask:0xf bank_mask:0xf
	v_fmac_f32_dpp v238, v253, v80 row_newbcast:9 row_mask:0xf bank_mask:0xf
	v_fmac_f32_dpp v107, v253, v84 row_newbcast:10 row_mask:0xf bank_mask:0xf
	v_fmac_f32_dpp v239, v253, v86 row_newbcast:11 row_mask:0xf bank_mask:0xf
	s_nop 0
	v_fmac_f32_dpp v108, v243, v12 row_newbcast:8 row_mask:0xf bank_mask:0xf
	v_add_u32_e32 v1, 0xac00, v208
	v_fmac_f32_dpp v106, v253, v90 row_newbcast:12 row_mask:0xf bank_mask:0xf
	v_fmac_f32_dpp v238, v253, v92 row_newbcast:13 row_mask:0xf bank_mask:0xf
	v_fmac_f32_dpp v107, v253, v96 row_newbcast:14 row_mask:0xf bank_mask:0xf
	v_fmac_f32_dpp v239, v253, v98 row_newbcast:15 row_mask:0xf bank_mask:0xf
	v_fmac_f32_dpp v109, v243, v18 row_newbcast:10 row_mask:0xf bank_mask:0xf
	v_fmac_f32_dpp v108, v243, v22 row_newbcast:12 row_mask:0xf bank_mask:0xf
	s_nop 0
	v_fmac_f32_dpp v106, v242, v102 row_newbcast:0 row_mask:0xf bank_mask:0xf
	s_nop 0
	v_pk_add_f32 v[106:107], v[106:107], v[238:239]
	v_mul_f32_dpp v238, v243, v234 row_newbcast:1 row_mask:0xf bank_mask:0xf
	v_fmac_f32_dpp v238, v243, v6 row_newbcast:5 row_mask:0xf bank_mask:0xf
	v_mul_f32_dpp v239, v243, v2 row_newbcast:3 row_mask:0xf bank_mask:0xf
	v_fmac_f32_dpp v109, v243, v26 row_newbcast:14 row_mask:0xf bank_mask:0xf
	s_waitcnt lgkmcnt(0)
	v_add_u32_e32 v254, 0xac00, v208
	ds_read2_b32 v[248:249], v254 offset0:76 offset1:92
	v_fmac_f32_dpp v108, v246, v32 row_newbcast:0 row_mask:0xf bank_mask:0xf
	v_pk_add_f32 v[106:107], v[106:107], v[106:107] op_sel:[0,1] op_sel_hi:[1,0]
	v_fmac_f32_dpp v238, v243, v14 row_newbcast:9 row_mask:0xf bank_mask:0xf
	v_fmac_f32_dpp v239, v243, v10 row_newbcast:7 row_mask:0xf bank_mask:0xf
	v_fmac_f32_dpp v109, v246, v38 row_newbcast:2 row_mask:0xf bank_mask:0xf
	v_fmac_f32_dpp v108, v246, v42 row_newbcast:4 row_mask:0xf bank_mask:0xf
	v_mov_b32_e32 v105, v57
	v_fmac_f32_dpp v238, v243, v24 row_newbcast:13 row_mask:0xf bank_mask:0xf
	v_fmac_f32_dpp v239, v243, v20 row_newbcast:11 row_mask:0xf bank_mask:0xf
	v_fmac_f32_dpp v109, v246, v72 row_newbcast:6 row_mask:0xf bank_mask:0xf
	v_fmac_f32_dpp v108, v246, v78 row_newbcast:8 row_mask:0xf bank_mask:0xf
	v_mov_b32_e32 v101, v57
	v_fmac_f32_dpp v238, v246, v34 row_newbcast:1 row_mask:0xf bank_mask:0xf
	v_fmac_f32_dpp v239, v243, v30 row_newbcast:15 row_mask:0xf bank_mask:0xf
	v_fmac_f32_dpp v109, v246, v84 row_newbcast:10 row_mask:0xf bank_mask:0xf
	v_fmac_f32_dpp v108, v246, v90 row_newbcast:12 row_mask:0xf bank_mask:0xf
	s_nop 0
	v_fmac_f32_dpp v238, v246, v46 row_newbcast:5 row_mask:0xf bank_mask:0xf
	v_fmac_f32_dpp v239, v246, v40 row_newbcast:3 row_mask:0xf bank_mask:0xf
	v_fmac_f32_dpp v109, v246, v96 row_newbcast:14 row_mask:0xf bank_mask:0xf
	v_fmac_f32_dpp v108, v247, v102 row_newbcast:0 row_mask:0xf bank_mask:0xf
	s_waitcnt lgkmcnt(0)
	v_add_u32_e32 v254, 0xac00, v208
	ds_read2_b32 v[250:251], v254 offset0:108 offset1:144
	v_fmac_f32_dpp v112, v248, v71 row_newbcast:0 row_mask:0xf bank_mask:0xf
	v_fmac_f32_dpp v113, v248, v235 row_newbcast:2 row_mask:0xf bank_mask:0xf
	v_fmac_f32_dpp v238, v246, v80 row_newbcast:9 row_mask:0xf bank_mask:0xf
	v_fmac_f32_dpp v239, v246, v74 row_newbcast:7 row_mask:0xf bank_mask:0xf
	v_mov_b32_e32 v95, v57
	v_fmac_f32_dpp v238, v246, v92 row_newbcast:13 row_mask:0xf bank_mask:0xf
	v_fmac_f32_dpp v239, v246, v86 row_newbcast:11 row_mask:0xf bank_mask:0xf
	v_fmac_f32_dpp v112, v248, v4 row_newbcast:4 row_mask:0xf bank_mask:0xf
	v_fmac_f32_dpp v113, v248, v8 row_newbcast:6 row_mask:0xf bank_mask:0xf
	v_mov_b32_e32 v89, v57
	v_fmac_f32_dpp v238, v247, v106 row_newbcast:1 row_mask:0xf bank_mask:0xf
	v_fmac_f32_dpp v239, v246, v98 row_newbcast:15 row_mask:0xf bank_mask:0xf
	v_fmac_f32_dpp v112, v248, v12 row_newbcast:8 row_mask:0xf bank_mask:0xf
	v_fmac_f32_dpp v113, v248, v18 row_newbcast:10 row_mask:0xf bank_mask:0xf
	s_nop 0
	v_pk_add_f32 v[108:109], v[108:109], v[238:239]
	v_mul_f32_dpp v238, v248, v234 row_newbcast:1 row_mask:0xf bank_mask:0xf
	v_fmac_f32_dpp v238, v248, v6 row_newbcast:5 row_mask:0xf bank_mask:0xf
	v_mul_f32_dpp v239, v248, v2 row_newbcast:3 row_mask:0xf bank_mask:0xf
	v_fmac_f32_dpp v112, v248, v22 row_newbcast:12 row_mask:0xf bank_mask:0xf
	v_fmac_f32_dpp v113, v248, v26 row_newbcast:14 row_mask:0xf bank_mask:0xf
	v_pk_add_f32 v[108:109], v[108:109], v[108:109] op_sel:[0,1] op_sel_hi:[1,0]
	v_fmac_f32_dpp v238, v248, v14 row_newbcast:9 row_mask:0xf bank_mask:0xf
	v_fmac_f32_dpp v239, v248, v10 row_newbcast:7 row_mask:0xf bank_mask:0xf
	v_fmac_f32_dpp v112, v249, v32 row_newbcast:0 row_mask:0xf bank_mask:0xf
	v_fmac_f32_dpp v113, v249, v38 row_newbcast:2 row_mask:0xf bank_mask:0xf
	s_waitcnt lgkmcnt(0)
; #define LAS __attribute__((address_space(3)))
; __device__ __forceinline__ float bf2f(unsigned short v) { return __uint_as_float(((unsigned)v) << 16); }
; __device__ __forceinline__ void dn_prep_item(const Args& a, LAS unsigned char* lds, int item, int tid, int wave, int lane, int& cwh, int next_item) {
;     ...
;           for (int i = 0; i < 64; ++i) x[i] = bf2f(*(const LAS unsigned short*)(src + i * KS_)) * fac[i]; }
;         { const LAS float* lrow = Lm + (lane & 15);
; #pragma unroll
;         for (int i = 1; i < 64; ++i) { float sa[4] = { x[i], 0.f, 0.f, 0.f };
;             int lr[4];
; #pragma unroll
;             for (int g = 0; g < (i + 15) / 16; ++g) lr[g] = __float_as_int(lrow[i * 68 + 16 * g]);
; #pragma unroll
;             for (int j = 0; j < i; ++j) { fmac_rowbcast_sel(sa[j & 3], lr[j >> 4], x[j], j); }
;             x[i] = (sa[0] + sa[1]) + (sa[2] + sa[3]); } }
	v_add_u32_e32 v254, 0xac00, v208
	ds_read2_b32 v[252:253], v254 offset0:160 offset1:176
	v_fmac_f32_dpp v116, v251, v71 row_newbcast:0 row_mask:0xf bank_mask:0xf
	v_fmac_f32_dpp v117, v251, v235 row_newbcast:2 row_mask:0xf bank_mask:0xf
	v_fmac_f32_dpp v238, v248, v24 row_newbcast:13 row_mask:0xf bank_mask:0xf
	v_fmac_f32_dpp v239, v248, v20 row_newbcast:11 row_mask:0xf bank_mask:0xf
	v_fmac_f32_dpp v112, v249, v42 row_newbcast:4 row_mask:0xf bank_mask:0xf
	v_fmac_f32_dpp v113, v249, v72 row_newbcast:6 row_mask:0xf bank_mask:0xf
	s_nop 0
	v_fmac_f32_dpp v116, v251, v4 row_newbcast:4 row_mask:0xf bank_mask:0xf
	v_fmac_f32_dpp v117, v251, v8 row_newbcast:6 row_mask:0xf bank_mask:0xf
	v_fmac_f32_dpp v238, v249, v34 row_newbcast:1 row_mask:0xf bank_mask:0xf
	v_fmac_f32_dpp v239, v248, v30 row_newbcast:15 row_mask:0xf bank_mask:0xf
	v_fmac_f32_dpp v112, v249, v78 row_newbcast:8 row_mask:0xf bank_mask:0xf
	v_fmac_f32_dpp v113, v249, v84 row_newbcast:10 row_mask:0xf bank_mask:0xf
	s_nop 0
	v_fmac_f32_dpp v116, v251, v12 row_newbcast:8 row_mask:0xf bank_mask:0xf
	v_fmac_f32_dpp v117, v251, v18 row_newbcast:10 row_mask:0xf bank_mask:0xf
	v_fmac_f32_dpp v238, v249, v46 row_newbcast:5 row_mask:0xf bank_mask:0xf
	v_fmac_f32_dpp v239, v249, v40 row_newbcast:3 row_mask:0xf bank_mask:0xf
	v_fmac_f32_dpp v112, v249, v90 row_newbcast:12 row_mask:0xf bank_mask:0xf
	v_fmac_f32_dpp v113, v249, v96 row_newbcast:14 row_mask:0xf bank_mask:0xf
	s_nop 0
	v_fmac_f32_dpp v116, v251, v22 row_newbcast:12 row_mask:0xf bank_mask:0xf
	v_fmac_f32_dpp v117, v251, v26 row_newbcast:14 row_mask:0xf bank_mask:0xf
	v_fmac_f32_dpp v238, v249, v80 row_newbcast:9 row_mask:0xf bank_mask:0xf
	v_fmac_f32_dpp v239, v249, v74 row_newbcast:7 row_mask:0xf bank_mask:0xf
	v_fmac_f32_dpp v112, v250, v102 row_newbcast:0 row_mask:0xf bank_mask:0xf
	v_fmac_f32_dpp v113, v250, v108 row_newbcast:2 row_mask:0xf bank_mask:0xf
	v_mov_b32_e32 v83, v57
	v_fmac_f32_dpp v238, v249, v92 row_newbcast:13 row_mask:0xf bank_mask:0xf
	v_fmac_f32_dpp v239, v249, v86 row_newbcast:11 row_mask:0xf bank_mask:0xf
	v_mov_b32_e32 v77, v57
	v_fmac_f32_dpp v238, v250, v106 row_newbcast:1 row_mask:0xf bank_mask:0xf
	v_fmac_f32_dpp v239, v249, v98 row_newbcast:15 row_mask:0xf bank_mask:0xf
	s_nop 0
	v_pk_add_f32 v[112:113], v[112:113], v[238:239]
	v_mul_f32_dpp v238, v251, v234 row_newbcast:1 row_mask:0xf bank_mask:0xf
	v_mul_f32_dpp v239, v251, v2 row_newbcast:3 row_mask:0xf bank_mask:0xf
	v_fmac_f32_dpp v238, v251, v6 row_newbcast:5 row_mask:0xf bank_mask:0xf
	s_waitcnt lgkmcnt(0)
	v_add_u32_e32 v254, 0xac00, v208
	ds_read2_b32 v[242:243], v254 offset0:212 offset1:228
	v_fmac_f32_dpp v116, v252, v32 row_newbcast:0 row_mask:0xf bank_mask:0xf
	v_fmac_f32_dpp v117, v252, v38 row_newbcast:2 row_mask:0xf bank_mask:0xf
	v_pk_add_f32 v[112:113], v[112:113], v[112:113] op_sel:[0,1] op_sel_hi:[1,0]
	v_fmac_f32_dpp v239, v251, v10 row_newbcast:7 row_mask:0xf bank_mask:0xf
	v_fmac_f32_dpp v238, v251, v14 row_newbcast:9 row_mask:0xf bank_mask:0xf
	v_fmac_f32_dpp v116, v252, v42 row_newbcast:4 row_mask:0xf bank_mask:0xf
	v_fmac_f32_dpp v117, v252, v72 row_newbcast:6 row_mask:0xf bank_mask:0xf
	v_mov_b32_e32 v45, v57
	v_fmac_f32_dpp v239, v251, v20 row_newbcast:11 row_mask:0xf bank_mask:0xf
	v_fmac_f32_dpp v238, v251, v24 row_newbcast:13 row_mask:0xf bank_mask:0xf
	v_fmac_f32_dpp v116, v252, v78 row_newbcast:8 row_mask:0xf bank_mask:0xf
	v_fmac_f32_dpp v117, v252, v84 row_newbcast:10 row_mask:0xf bank_mask:0xf
	v_mov_b32_e32 v37, v57
	v_fmac_f32_dpp v239, v251, v30 row_newbcast:15 row_mask:0xf bank_mask:0xf
	v_fmac_f32_dpp v238, v252, v34 row_newbcast:1 row_mask:0xf bank_mask:0xf
	v_fmac_f32_dpp v116, v252, v90 row_newbcast:12 row_mask:0xf bank_mask:0xf
	v_fmac_f32_dpp v117, v252, v96 row_newbcast:14 row_mask:0xf bank_mask:0xf
	v_mul_f32_e32 v16, v240, v0
	v_fmac_f32_dpp v239, v252, v40 row_newbcast:3 row_mask:0xf bank_mask:0xf
	v_fmac_f32_dpp v238, v252, v46 row_newbcast:5 row_mask:0xf bank_mask:0xf
	v_fmac_f32_dpp v116, v253, v102 row_newbcast:0 row_mask:0xf bank_mask:0xf
	v_fmac_f32_dpp v117, v253, v108 row_newbcast:2 row_mask:0xf bank_mask:0xf
	v_lshlrev_b32_e32 v0, 16, v17
	v_fmac_f32_dpp v239, v252, v74 row_newbcast:7 row_mask:0xf bank_mask:0xf
	v_fmac_f32_dpp v238, v252, v80 row_newbcast:9 row_mask:0xf bank_mask:0xf
	v_mul_f32_e32 v0, v241, v0
	v_fmac_f32_dpp v239, v252, v86 row_newbcast:11 row_mask:0xf bank_mask:0xf
	v_fmac_f32_dpp v238, v252, v92 row_newbcast:13 row_mask:0xf bank_mask:0xf
	v_mov_b32_e32 v29, v57
	v_fmac_f32_dpp v239, v252, v98 row_newbcast:15 row_mask:0xf bank_mask:0xf
	v_fmac_f32_dpp v238, v253, v106 row_newbcast:1 row_mask:0xf bank_mask:0xf
	v_mov_b32_e32 v17, v57
	v_fmac_f32_dpp v239, v253, v112 row_newbcast:3 row_mask:0xf bank_mask:0xf
	s_nop 0
	v_pk_add_f32 v[116:117], v[116:117], v[238:239]
	s_waitcnt lgkmcnt(0)
; #define LAS __attribute__((address_space(3)))
; __device__ __forceinline__ unsigned pk2(float lo, float hi) { const f32x2_t v = {lo, hi}; const bf16x2_t b = __builtin_convertvector(v, bf16x2_t); return __builtin_bit_cast(unsigned, b); }
; __device__ __forceinline__ void dn_prep_item(const Args& a, LAS unsigned char* lds, int item, int tid, int wave, int lane, int& cwh, int next_item) {
;     ...
;         { const LAS float* lrow = Lm + (lane & 15);
; #pragma unroll
;         for (int i = 1; i < 64; ++i) { float sa[4] = { x[i], 0.f, 0.f, 0.f };
;             int lr[4];
; #pragma unroll
;             for (int g = 0; g < (i + 15) / 16; ++g) lr[g] = __float_as_int(lrow[i * 68 + 16 * g]);
; #pragma unroll
;             for (int j = 0; j < i; ++j) { fmac_rowbcast_sel(sa[j & 3], lr[j >> 4], x[j], j); }
;             x[i] = (sa[0] + sa[1]) + (sa[2] + sa[3]); } }
;     ...
;         for (int q = 0; q < 8; ++q) { v4u w; w.x = pk2(x[8 * q], x[8 * q + 1]); w.y = pk2(x[8 * q + 2], x[8 * q + 3]); w.z = pk2(x[8 * q + 4], x[8 * q + 5]); w.w = pk2(x[8 * q + 6], x[8 * q + 7]);
	v_add_u32_e32 v254, 0xae00, v208
	ds_read2_b32 v[246:247], v254 offset0:116 offset1:152
	v_fmac_f32_dpp v118, v242, v71 row_newbcast:0 row_mask:0xf bank_mask:0xf
	v_mul_f32_dpp v238, v242, v234 row_newbcast:1 row_mask:0xf bank_mask:0xf
	v_fmac_f32_dpp v119, v242, v235 row_newbcast:2 row_mask:0xf bank_mask:0xf
	v_fmac_f32_dpp v118, v242, v4 row_newbcast:4 row_mask:0xf bank_mask:0xf
	v_mul_f32_dpp v239, v242, v2 row_newbcast:3 row_mask:0xf bank_mask:0xf
	v_fmac_f32_dpp v238, v242, v6 row_newbcast:5 row_mask:0xf bank_mask:0xf
	v_fmac_f32_dpp v119, v242, v8 row_newbcast:6 row_mask:0xf bank_mask:0xf
	v_add_u32_e32 v1, 0xae00, v208
	v_fmac_f32_dpp v118, v242, v12 row_newbcast:8 row_mask:0xf bank_mask:0xf
	v_fmac_f32_dpp v239, v242, v10 row_newbcast:7 row_mask:0xf bank_mask:0xf
	v_fmac_f32_dpp v238, v242, v14 row_newbcast:9 row_mask:0xf bank_mask:0xf
	v_fmac_f32_dpp v119, v242, v18 row_newbcast:10 row_mask:0xf bank_mask:0xf
	s_nop 0
	v_fmac_f32_dpp v118, v242, v22 row_newbcast:12 row_mask:0xf bank_mask:0xf
	v_fmac_f32_dpp v239, v242, v20 row_newbcast:11 row_mask:0xf bank_mask:0xf
	v_fmac_f32_dpp v238, v242, v24 row_newbcast:13 row_mask:0xf bank_mask:0xf
	v_fmac_f32_dpp v119, v242, v26 row_newbcast:14 row_mask:0xf bank_mask:0xf
	v_pk_add_f32 v[116:117], v[116:117], v[116:117] op_sel:[0,1] op_sel_hi:[1,0]
	v_fmac_f32_dpp v118, v243, v32 row_newbcast:0 row_mask:0xf bank_mask:0xf
	v_fmac_f32_dpp v239, v242, v30 row_newbcast:15 row_mask:0xf bank_mask:0xf
	v_fmac_f32_dpp v238, v243, v34 row_newbcast:1 row_mask:0xf bank_mask:0xf
	v_fmac_f32_dpp v119, v243, v38 row_newbcast:2 row_mask:0xf bank_mask:0xf
	s_waitcnt lgkmcnt(0)
	v_add_u32_e32 v254, 0xb000, v208
	ds_read2_b32 v[248:249], v254 offset0:40 offset1:56
	v_fmac_f32_dpp v122, v247, v71 row_newbcast:0 row_mask:0xf bank_mask:0xf
	v_fmac_f32_dpp v123, v247, v235 row_newbcast:2 row_mask:0xf bank_mask:0xf
	v_fmac_f32_dpp v118, v243, v42 row_newbcast:4 row_mask:0xf bank_mask:0xf
	v_fmac_f32_dpp v239, v243, v40 row_newbcast:3 row_mask:0xf bank_mask:0xf
	v_fmac_f32_dpp v238, v243, v46 row_newbcast:5 row_mask:0xf bank_mask:0xf
	v_fmac_f32_dpp v119, v243, v72 row_newbcast:6 row_mask:0xf bank_mask:0xf
	s_nop 0
	v_fmac_f32_dpp v122, v247, v4 row_newbcast:4 row_mask:0xf bank_mask:0xf
	v_fmac_f32_dpp v123, v247, v8 row_newbcast:6 row_mask:0xf bank_mask:0xf
	v_fmac_f32_dpp v118, v243, v78 row_newbcast:8 row_mask:0xf bank_mask:0xf
	v_fmac_f32_dpp v239, v243, v74 row_newbcast:7 row_mask:0xf bank_mask:0xf
	v_fmac_f32_dpp v238, v243, v80 row_newbcast:9 row_mask:0xf bank_mask:0xf
	v_fmac_f32_dpp v119, v243, v84 row_newbcast:10 row_mask:0xf bank_mask:0xf
	s_nop 0
	v_fmac_f32_dpp v122, v247, v12 row_newbcast:8 row_mask:0xf bank_mask:0xf
	v_add_u32_e32 v1, 0xb000, v208
	v_fmac_f32_dpp v118, v243, v90 row_newbcast:12 row_mask:0xf bank_mask:0xf
	v_fmac_f32_dpp v239, v243, v86 row_newbcast:11 row_mask:0xf bank_mask:0xf
	v_fmac_f32_dpp v238, v243, v92 row_newbcast:13 row_mask:0xf bank_mask:0xf
	v_fmac_f32_dpp v119, v243, v96 row_newbcast:14 row_mask:0xf bank_mask:0xf
	v_fmac_f32_dpp v123, v247, v18 row_newbcast:10 row_mask:0xf bank_mask:0xf
	v_fmac_f32_dpp v122, v247, v22 row_newbcast:12 row_mask:0xf bank_mask:0xf
	s_nop 0
	v_fmac_f32_dpp v118, v246, v102 row_newbcast:0 row_mask:0xf bank_mask:0xf
	v_fmac_f32_dpp v239, v243, v98 row_newbcast:15 row_mask:0xf bank_mask:0xf
	v_fmac_f32_dpp v238, v246, v106 row_newbcast:1 row_mask:0xf bank_mask:0xf
	v_fmac_f32_dpp v119, v246, v108 row_newbcast:2 row_mask:0xf bank_mask:0xf
	s_nop 0
	v_fmac_f32_dpp v118, v246, v116 row_newbcast:4 row_mask:0xf bank_mask:0xf
	v_fmac_f32_dpp v239, v246, v112 row_newbcast:3 row_mask:0xf bank_mask:0xf
	v_fmac_f32_dpp v123, v247, v26 row_newbcast:14 row_mask:0xf bank_mask:0xf
	s_waitcnt lgkmcnt(0)
	v_add_u32_e32 v254, 0xb000, v208
	ds_read2_b32 v[250:251], v254 offset0:92 offset1:108
	v_fmac_f32_dpp v122, v248, v32 row_newbcast:0 row_mask:0xf bank_mask:0xf
	v_cvt_pk_bf16_f32 v3, v8, v10
	v_pk_add_f32 v[118:119], v[118:119], v[238:239]
	v_mul_f32_dpp v238, v247, v234 row_newbcast:1 row_mask:0xf bank_mask:0xf
	v_fmac_f32_dpp v238, v247, v6 row_newbcast:5 row_mask:0xf bank_mask:0xf
	v_mul_f32_dpp v239, v247, v2 row_newbcast:3 row_mask:0xf bank_mask:0xf
	v_fmac_f32_dpp v123, v248, v38 row_newbcast:2 row_mask:0xf bank_mask:0xf
	v_fmac_f32_dpp v122, v248, v42 row_newbcast:4 row_mask:0xf bank_mask:0xf
	v_pk_add_f32 v[118:119], v[118:119], v[118:119] op_sel:[0,1] op_sel_hi:[1,0]
	v_fmac_f32_dpp v238, v247, v14 row_newbcast:9 row_mask:0xf bank_mask:0xf
	v_fmac_f32_dpp v239, v247, v10 row_newbcast:7 row_mask:0xf bank_mask:0xf
	v_fmac_f32_dpp v123, v248, v72 row_newbcast:6 row_mask:0xf bank_mask:0xf
	v_fmac_f32_dpp v122, v248, v78 row_newbcast:8 row_mask:0xf bank_mask:0xf
	s_nop 0
	v_fmac_f32_dpp v238, v247, v24 row_newbcast:13 row_mask:0xf bank_mask:0xf
	v_fmac_f32_dpp v239, v247, v20 row_newbcast:11 row_mask:0xf bank_mask:0xf
	v_fmac_f32_dpp v123, v248, v84 row_newbcast:10 row_mask:0xf bank_mask:0xf
	v_fmac_f32_dpp v122, v248, v90 row_newbcast:12 row_mask:0xf bank_mask:0xf
	s_nop 0
	v_fmac_f32_dpp v238, v248, v34 row_newbcast:1 row_mask:0xf bank_mask:0xf
	v_fmac_f32_dpp v239, v247, v30 row_newbcast:15 row_mask:0xf bank_mask:0xf
	v_fmac_f32_dpp v123, v248, v96 row_newbcast:14 row_mask:0xf bank_mask:0xf
	v_fmac_f32_dpp v122, v249, v102 row_newbcast:0 row_mask:0xf bank_mask:0xf
	s_nop 0
	v_fmac_f32_dpp v238, v248, v46 row_newbcast:5 row_mask:0xf bank_mask:0xf
	v_fmac_f32_dpp v239, v248, v40 row_newbcast:3 row_mask:0xf bank_mask:0xf
	v_fmac_f32_dpp v123, v249, v108 row_newbcast:2 row_mask:0xf bank_mask:0xf
	v_fmac_f32_dpp v122, v249, v116 row_newbcast:4 row_mask:0xf bank_mask:0xf
	s_waitcnt lgkmcnt(0)
; #define LAS __attribute__((address_space(3)))
; __device__ __forceinline__ void dn_prep_item(const Args& a, LAS unsigned char* lds, int item, int tid, int wave, int lane, int& cwh, int next_item) {
;     ...
;         { const LAS float* lrow = Lm + (lane & 15);
; #pragma unroll
;         for (int i = 1; i < 64; ++i) { float sa[4] = { x[i], 0.f, 0.f, 0.f };
;             int lr[4];
; #pragma unroll
;             for (int g = 0; g < (i + 15) / 16; ++g) lr[g] = __float_as_int(lrow[i * 68 + 16 * g]);
; #pragma unroll
;             for (int j = 0; j < i; ++j) { fmac_rowbcast_sel(sa[j & 3], lr[j >> 4], x[j], j); }
;             x[i] = (sa[0] + sa[1]) + (sa[2] + sa[3]); } }
	v_add_u32_e32 v254, 0xb000, v208
	ds_read2_b32 v[252:253], v254 offset0:124 offset1:160
	v_fmac_f32_dpp v126, v250, v71 row_newbcast:0 row_mask:0xf bank_mask:0xf
	v_fmac_f32_dpp v127, v250, v235 row_newbcast:2 row_mask:0xf bank_mask:0xf
	v_fmac_f32_dpp v238, v248, v80 row_newbcast:9 row_mask:0xf bank_mask:0xf
	v_fmac_f32_dpp v239, v248, v74 row_newbcast:7 row_mask:0xf bank_mask:0xf
	s_nop 0
	v_fmac_f32_dpp v238, v248, v92 row_newbcast:13 row_mask:0xf bank_mask:0xf
	v_fmac_f32_dpp v239, v248, v86 row_newbcast:11 row_mask:0xf bank_mask:0xf
	v_fmac_f32_dpp v126, v250, v4 row_newbcast:4 row_mask:0xf bank_mask:0xf
	v_fmac_f32_dpp v127, v250, v8 row_newbcast:6 row_mask:0xf bank_mask:0xf
	s_nop 0
	v_fmac_f32_dpp v238, v249, v106 row_newbcast:1 row_mask:0xf bank_mask:0xf
	v_fmac_f32_dpp v239, v248, v98 row_newbcast:15 row_mask:0xf bank_mask:0xf
	v_fmac_f32_dpp v126, v250, v12 row_newbcast:8 row_mask:0xf bank_mask:0xf
	v_fmac_f32_dpp v127, v250, v18 row_newbcast:10 row_mask:0xf bank_mask:0xf
	s_nop 0
	v_fmac_f32_dpp v238, v249, v118 row_newbcast:5 row_mask:0xf bank_mask:0xf
	v_fmac_f32_dpp v239, v249, v112 row_newbcast:3 row_mask:0xf bank_mask:0xf
	v_fmac_f32_dpp v126, v250, v22 row_newbcast:12 row_mask:0xf bank_mask:0xf
	v_fmac_f32_dpp v127, v250, v26 row_newbcast:14 row_mask:0xf bank_mask:0xf
	s_nop 0
	v_pk_add_f32 v[122:123], v[122:123], v[238:239]
	v_mul_f32_dpp v238, v250, v234 row_newbcast:1 row_mask:0xf bank_mask:0xf
	v_fmac_f32_dpp v238, v250, v6 row_newbcast:5 row_mask:0xf bank_mask:0xf
	v_mul_f32_dpp v239, v250, v2 row_newbcast:3 row_mask:0xf bank_mask:0xf
	v_fmac_f32_dpp v126, v251, v32 row_newbcast:0 row_mask:0xf bank_mask:0xf
	v_fmac_f32_dpp v127, v251, v38 row_newbcast:2 row_mask:0xf bank_mask:0xf
	v_pk_add_f32 v[122:123], v[122:123], v[122:123] op_sel:[0,1] op_sel_hi:[1,0]
	v_fmac_f32_dpp v238, v250, v14 row_newbcast:9 row_mask:0xf bank_mask:0xf
	v_fmac_f32_dpp v239, v250, v10 row_newbcast:7 row_mask:0xf bank_mask:0xf
	v_fmac_f32_dpp v126, v251, v42 row_newbcast:4 row_mask:0xf bank_mask:0xf
	v_fmac_f32_dpp v127, v251, v72 row_newbcast:6 row_mask:0xf bank_mask:0xf
	s_waitcnt lgkmcnt(0)
	v_add_u32_e32 v254, 0xb000, v208
	ds_read2_b32 v[242:243], v254 offset0:176 offset1:192
	v_fmac_f32_dpp v130, v253, v71 row_newbcast:0 row_mask:0xf bank_mask:0xf
	v_fmac_f32_dpp v131, v253, v235 row_newbcast:2 row_mask:0xf bank_mask:0xf
	v_fmac_f32_dpp v238, v250, v24 row_newbcast:13 row_mask:0xf bank_mask:0xf
	v_fmac_f32_dpp v239, v250, v20 row_newbcast:11 row_mask:0xf bank_mask:0xf
	v_fmac_f32_dpp v126, v251, v78 row_newbcast:8 row_mask:0xf bank_mask:0xf
	v_fmac_f32_dpp v127, v251, v84 row_newbcast:10 row_mask:0xf bank_mask:0xf
	s_nop 0
	v_fmac_f32_dpp v130, v253, v4 row_newbcast:4 row_mask:0xf bank_mask:0xf
	v_fmac_f32_dpp v131, v253, v8 row_newbcast:6 row_mask:0xf bank_mask:0xf
	v_fmac_f32_dpp v238, v251, v34 row_newbcast:1 row_mask:0xf bank_mask:0xf
	v_fmac_f32_dpp v239, v250, v30 row_newbcast:15 row_mask:0xf bank_mask:0xf
	v_fmac_f32_dpp v126, v251, v90 row_newbcast:12 row_mask:0xf bank_mask:0xf
	v_fmac_f32_dpp v127, v251, v96 row_newbcast:14 row_mask:0xf bank_mask:0xf
	s_nop 0
	v_fmac_f32_dpp v130, v253, v12 row_newbcast:8 row_mask:0xf bank_mask:0xf
	v_fmac_f32_dpp v131, v253, v18 row_newbcast:10 row_mask:0xf bank_mask:0xf
	v_fmac_f32_dpp v238, v251, v46 row_newbcast:5 row_mask:0xf bank_mask:0xf
	v_fmac_f32_dpp v239, v251, v40 row_newbcast:3 row_mask:0xf bank_mask:0xf
	v_fmac_f32_dpp v126, v252, v102 row_newbcast:0 row_mask:0xf bank_mask:0xf
	v_fmac_f32_dpp v127, v252, v108 row_newbcast:2 row_mask:0xf bank_mask:0xf
	s_nop 0
	v_fmac_f32_dpp v130, v253, v22 row_newbcast:12 row_mask:0xf bank_mask:0xf
	v_fmac_f32_dpp v131, v253, v26 row_newbcast:14 row_mask:0xf bank_mask:0xf
	v_fmac_f32_dpp v238, v251, v80 row_newbcast:9 row_mask:0xf bank_mask:0xf
	v_fmac_f32_dpp v239, v251, v74 row_newbcast:7 row_mask:0xf bank_mask:0xf
	v_fmac_f32_dpp v126, v252, v116 row_newbcast:4 row_mask:0xf bank_mask:0xf
	v_fmac_f32_dpp v127, v252, v122 row_newbcast:6 row_mask:0xf bank_mask:0xf
	s_nop 0
	v_fmac_f32_dpp v238, v251, v92 row_newbcast:13 row_mask:0xf bank_mask:0xf
	v_fmac_f32_dpp v239, v251, v86 row_newbcast:11 row_mask:0xf bank_mask:0xf
	s_nop 0
	v_fmac_f32_dpp v238, v252, v106 row_newbcast:1 row_mask:0xf bank_mask:0xf
	v_fmac_f32_dpp v239, v251, v98 row_newbcast:15 row_mask:0xf bank_mask:0xf
	s_nop 0
	v_fmac_f32_dpp v238, v252, v118 row_newbcast:5 row_mask:0xf bank_mask:0xf
	v_fmac_f32_dpp v239, v252, v112 row_newbcast:3 row_mask:0xf bank_mask:0xf
	s_waitcnt lgkmcnt(0)
	v_add_u32_e32 v254, 0xb000, v208
	ds_read2_b32 v[246:247], v254 offset0:228 offset1:244
	v_fmac_f32_dpp v130, v242, v32 row_newbcast:0 row_mask:0xf bank_mask:0xf
	v_fmac_f32_dpp v131, v242, v38 row_newbcast:2 row_mask:0xf bank_mask:0xf
	v_pk_add_f32 v[126:127], v[126:127], v[238:239]
	v_mul_f32_dpp v238, v253, v234 row_newbcast:1 row_mask:0xf bank_mask:0xf
	v_mul_f32_dpp v239, v253, v2 row_newbcast:3 row_mask:0xf bank_mask:0xf
	v_fmac_f32_dpp v238, v253, v6 row_newbcast:5 row_mask:0xf bank_mask:0xf
	v_fmac_f32_dpp v130, v242, v42 row_newbcast:4 row_mask:0xf bank_mask:0xf
	v_fmac_f32_dpp v131, v242, v72 row_newbcast:6 row_mask:0xf bank_mask:0xf
	v_pk_add_f32 v[126:127], v[126:127], v[126:127] op_sel:[0,1] op_sel_hi:[1,0]
	v_fmac_f32_dpp v239, v253, v10 row_newbcast:7 row_mask:0xf bank_mask:0xf
	v_fmac_f32_dpp v238, v253, v14 row_newbcast:9 row_mask:0xf bank_mask:0xf
	v_fmac_f32_dpp v130, v242, v78 row_newbcast:8 row_mask:0xf bank_mask:0xf
	v_fmac_f32_dpp v131, v242, v84 row_newbcast:10 row_mask:0xf bank_mask:0xf
	s_nop 0
	v_fmac_f32_dpp v239, v253, v20 row_newbcast:11 row_mask:0xf bank_mask:0xf
	v_fmac_f32_dpp v238, v253, v24 row_newbcast:13 row_mask:0xf bank_mask:0xf
	v_fmac_f32_dpp v130, v242, v90 row_newbcast:12 row_mask:0xf bank_mask:0xf
	v_fmac_f32_dpp v131, v242, v96 row_newbcast:14 row_mask:0xf bank_mask:0xf
	s_nop 0
	v_fmac_f32_dpp v239, v253, v30 row_newbcast:15 row_mask:0xf bank_mask:0xf
	v_fmac_f32_dpp v238, v242, v34 row_newbcast:1 row_mask:0xf bank_mask:0xf
	v_fmac_f32_dpp v130, v243, v102 row_newbcast:0 row_mask:0xf bank_mask:0xf
	v_fmac_f32_dpp v131, v243, v108 row_newbcast:2 row_mask:0xf bank_mask:0xf
	s_nop 0
	v_fmac_f32_dpp v239, v242, v40 row_newbcast:3 row_mask:0xf bank_mask:0xf
	v_fmac_f32_dpp v238, v242, v46 row_newbcast:5 row_mask:0xf bank_mask:0xf
	v_fmac_f32_dpp v130, v243, v116 row_newbcast:4 row_mask:0xf bank_mask:0xf
	v_fmac_f32_dpp v131, v243, v122 row_newbcast:6 row_mask:0xf bank_mask:0xf
	s_waitcnt lgkmcnt(0)
; #define LAS __attribute__((address_space(3)))
; __device__ __forceinline__ void dn_prep_item(const Args& a, LAS unsigned char* lds, int item, int tid, int wave, int lane, int& cwh, int next_item) {
;     ...
;         { const LAS float* lrow = Lm + (lane & 15);
; #pragma unroll
;         for (int i = 1; i < 64; ++i) { float sa[4] = { x[i], 0.f, 0.f, 0.f };
;             int lr[4];
; #pragma unroll
;             for (int g = 0; g < (i + 15) / 16; ++g) lr[g] = __float_as_int(lrow[i * 68 + 16 * g]);
; #pragma unroll
;             for (int j = 0; j < i; ++j) { fmac_rowbcast_sel(sa[j & 3], lr[j >> 4], x[j], j); }
;             x[i] = (sa[0] + sa[1]) + (sa[2] + sa[3]); } }
	v_add_u32_e32 v254, 0xb400, v208
	ds_read2_b32 v[248:249], v254 offset0:4 offset1:40
	v_fmac_f32_dpp v134, v246, v71 row_newbcast:0 row_mask:0xf bank_mask:0xf
	v_fmac_f32_dpp v135, v246, v235 row_newbcast:2 row_mask:0xf bank_mask:0xf
	v_fmac_f32_dpp v239, v242, v74 row_newbcast:7 row_mask:0xf bank_mask:0xf
	v_fmac_f32_dpp v238, v242, v80 row_newbcast:9 row_mask:0xf bank_mask:0xf
	v_add_u32_e32 v1, 0xb400, v208
	v_fmac_f32_dpp v239, v242, v86 row_newbcast:11 row_mask:0xf bank_mask:0xf
	v_fmac_f32_dpp v238, v242, v92 row_newbcast:13 row_mask:0xf bank_mask:0xf
	v_fmac_f32_dpp v134, v246, v4 row_newbcast:4 row_mask:0xf bank_mask:0xf
	v_fmac_f32_dpp v135, v246, v8 row_newbcast:6 row_mask:0xf bank_mask:0xf
	s_nop 0
	v_fmac_f32_dpp v239, v242, v98 row_newbcast:15 row_mask:0xf bank_mask:0xf
	v_fmac_f32_dpp v238, v243, v106 row_newbcast:1 row_mask:0xf bank_mask:0xf
	v_fmac_f32_dpp v134, v246, v12 row_newbcast:8 row_mask:0xf bank_mask:0xf
	v_fmac_f32_dpp v135, v246, v18 row_newbcast:10 row_mask:0xf bank_mask:0xf
	s_nop 0
	v_fmac_f32_dpp v239, v243, v112 row_newbcast:3 row_mask:0xf bank_mask:0xf
	v_fmac_f32_dpp v238, v243, v118 row_newbcast:5 row_mask:0xf bank_mask:0xf
	v_fmac_f32_dpp v134, v246, v22 row_newbcast:12 row_mask:0xf bank_mask:0xf
	v_fmac_f32_dpp v135, v246, v26 row_newbcast:14 row_mask:0xf bank_mask:0xf
	s_nop 0
	v_fmac_f32_dpp v239, v243, v126 row_newbcast:7 row_mask:0xf bank_mask:0xf
	v_fmac_f32_dpp v134, v247, v32 row_newbcast:0 row_mask:0xf bank_mask:0xf
	v_fmac_f32_dpp v135, v247, v38 row_newbcast:2 row_mask:0xf bank_mask:0xf
	s_nop 0
	v_pk_add_f32 v[130:131], v[130:131], v[238:239]
	v_mul_f32_dpp v238, v246, v234 row_newbcast:1 row_mask:0xf bank_mask:0xf
	v_mul_f32_dpp v239, v246, v2 row_newbcast:3 row_mask:0xf bank_mask:0xf
	v_fmac_f32_dpp v238, v246, v6 row_newbcast:5 row_mask:0xf bank_mask:0xf
	v_fmac_f32_dpp v134, v247, v42 row_newbcast:4 row_mask:0xf bank_mask:0xf
	v_fmac_f32_dpp v135, v247, v72 row_newbcast:6 row_mask:0xf bank_mask:0xf
	v_pk_add_f32 v[130:131], v[130:131], v[130:131] op_sel:[0,1] op_sel_hi:[1,0]
	v_fmac_f32_dpp v239, v246, v10 row_newbcast:7 row_mask:0xf bank_mask:0xf
	v_fmac_f32_dpp v238, v246, v14 row_newbcast:9 row_mask:0xf bank_mask:0xf
	v_fmac_f32_dpp v134, v247, v78 row_newbcast:8 row_mask:0xf bank_mask:0xf
	v_fmac_f32_dpp v135, v247, v84 row_newbcast:10 row_mask:0xf bank_mask:0xf
	s_waitcnt lgkmcnt(0)
	v_add_u32_e32 v254, 0xb400, v208
	ds_read2_b32 v[250:251], v254 offset0:56 offset1:72
	v_fmac_f32_dpp v138, v249, v71 row_newbcast:0 row_mask:0xf bank_mask:0xf
	v_fmac_f32_dpp v139, v249, v235 row_newbcast:2 row_mask:0xf bank_mask:0xf
	v_fmac_f32_dpp v239, v246, v20 row_newbcast:11 row_mask:0xf bank_mask:0xf
	v_fmac_f32_dpp v238, v246, v24 row_newbcast:13 row_mask:0xf bank_mask:0xf
	v_fmac_f32_dpp v134, v247, v90 row_newbcast:12 row_mask:0xf bank_mask:0xf
	v_fmac_f32_dpp v135, v247, v96 row_newbcast:14 row_mask:0xf bank_mask:0xf
	s_nop 0
	v_fmac_f32_dpp v138, v249, v4 row_newbcast:4 row_mask:0xf bank_mask:0xf
	v_fmac_f32_dpp v139, v249, v8 row_newbcast:6 row_mask:0xf bank_mask:0xf
	v_fmac_f32_dpp v239, v246, v30 row_newbcast:15 row_mask:0xf bank_mask:0xf
	v_fmac_f32_dpp v238, v247, v34 row_newbcast:1 row_mask:0xf bank_mask:0xf
	v_fmac_f32_dpp v134, v248, v102 row_newbcast:0 row_mask:0xf bank_mask:0xf
	v_fmac_f32_dpp v135, v248, v108 row_newbcast:2 row_mask:0xf bank_mask:0xf
	s_nop 0
	v_fmac_f32_dpp v138, v249, v12 row_newbcast:8 row_mask:0xf bank_mask:0xf
	v_fmac_f32_dpp v139, v249, v18 row_newbcast:10 row_mask:0xf bank_mask:0xf
	v_fmac_f32_dpp v239, v247, v40 row_newbcast:3 row_mask:0xf bank_mask:0xf
	v_fmac_f32_dpp v238, v247, v46 row_newbcast:5 row_mask:0xf bank_mask:0xf
	v_fmac_f32_dpp v134, v248, v116 row_newbcast:4 row_mask:0xf bank_mask:0xf
	v_fmac_f32_dpp v135, v248, v122 row_newbcast:6 row_mask:0xf bank_mask:0xf
	s_nop 0
	v_fmac_f32_dpp v138, v249, v22 row_newbcast:12 row_mask:0xf bank_mask:0xf
	v_fmac_f32_dpp v139, v249, v26 row_newbcast:14 row_mask:0xf bank_mask:0xf
	v_fmac_f32_dpp v239, v247, v74 row_newbcast:7 row_mask:0xf bank_mask:0xf
	v_fmac_f32_dpp v238, v247, v80 row_newbcast:9 row_mask:0xf bank_mask:0xf
	v_fmac_f32_dpp v134, v248, v130 row_newbcast:8 row_mask:0xf bank_mask:0xf
	s_nop 0
	v_fmac_f32_dpp v239, v247, v86 row_newbcast:11 row_mask:0xf bank_mask:0xf
	v_fmac_f32_dpp v238, v247, v92 row_newbcast:13 row_mask:0xf bank_mask:0xf
	s_nop 0
	v_fmac_f32_dpp v239, v247, v98 row_newbcast:15 row_mask:0xf bank_mask:0xf
	v_fmac_f32_dpp v238, v248, v106 row_newbcast:1 row_mask:0xf bank_mask:0xf
	s_nop 0
	v_fmac_f32_dpp v239, v248, v112 row_newbcast:3 row_mask:0xf bank_mask:0xf
	v_fmac_f32_dpp v238, v248, v118 row_newbcast:5 row_mask:0xf bank_mask:0xf
	s_waitcnt lgkmcnt(0)
; #define LAS __attribute__((address_space(3)))
; __device__ __forceinline__ void dn_prep_item(const Args& a, LAS unsigned char* lds, int item, int tid, int wave, int lane, int& cwh, int next_item) {
;     ...
;         { const LAS float* lrow = Lm + (lane & 15);
; #pragma unroll
;         for (int i = 1; i < 64; ++i) { float sa[4] = { x[i], 0.f, 0.f, 0.f };
;             int lr[4];
; #pragma unroll
;             for (int g = 0; g < (i + 15) / 16; ++g) lr[g] = __float_as_int(lrow[i * 68 + 16 * g]);
; #pragma unroll
;             for (int j = 0; j < i; ++j) { fmac_rowbcast_sel(sa[j & 3], lr[j >> 4], x[j], j); }
;             x[i] = (sa[0] + sa[1]) + (sa[2] + sa[3]); } }
	v_add_u32_e32 v254, 0xb400, v208
	ds_read2_b32 v[252:253], v254 offset0:108 offset1:124
	v_fmac_f32_dpp v138, v250, v32 row_newbcast:0 row_mask:0xf bank_mask:0xf
	v_fmac_f32_dpp v139, v250, v38 row_newbcast:2 row_mask:0xf bank_mask:0xf
	v_fmac_f32_dpp v239, v248, v126 row_newbcast:7 row_mask:0xf bank_mask:0xf
	s_nop 0
	v_fmac_f32_dpp v138, v250, v42 row_newbcast:4 row_mask:0xf bank_mask:0xf
	v_fmac_f32_dpp v139, v250, v72 row_newbcast:6 row_mask:0xf bank_mask:0xf
	v_pk_add_f32 v[134:135], v[134:135], v[238:239]
	v_mul_f32_dpp v238, v249, v234 row_newbcast:1 row_mask:0xf bank_mask:0xf
	v_fmac_f32_dpp v238, v249, v6 row_newbcast:5 row_mask:0xf bank_mask:0xf
	v_mul_f32_dpp v239, v249, v2 row_newbcast:3 row_mask:0xf bank_mask:0xf
	v_fmac_f32_dpp v138, v250, v78 row_newbcast:8 row_mask:0xf bank_mask:0xf
	v_fmac_f32_dpp v139, v250, v84 row_newbcast:10 row_mask:0xf bank_mask:0xf
	v_pk_add_f32 v[134:135], v[134:135], v[134:135] op_sel:[0,1] op_sel_hi:[1,0]
	v_fmac_f32_dpp v238, v249, v14 row_newbcast:9 row_mask:0xf bank_mask:0xf
	v_fmac_f32_dpp v239, v249, v10 row_newbcast:7 row_mask:0xf bank_mask:0xf
	v_fmac_f32_dpp v138, v250, v90 row_newbcast:12 row_mask:0xf bank_mask:0xf
	v_fmac_f32_dpp v139, v250, v96 row_newbcast:14 row_mask:0xf bank_mask:0xf
	s_nop 0
	v_fmac_f32_dpp v238, v249, v24 row_newbcast:13 row_mask:0xf bank_mask:0xf
	v_fmac_f32_dpp v239, v249, v20 row_newbcast:11 row_mask:0xf bank_mask:0xf
	v_fmac_f32_dpp v138, v251, v102 row_newbcast:0 row_mask:0xf bank_mask:0xf
	v_fmac_f32_dpp v139, v251, v108 row_newbcast:2 row_mask:0xf bank_mask:0xf
	s_nop 0
	v_fmac_f32_dpp v238, v250, v34 row_newbcast:1 row_mask:0xf bank_mask:0xf
	v_fmac_f32_dpp v239, v249, v30 row_newbcast:15 row_mask:0xf bank_mask:0xf
	v_fmac_f32_dpp v138, v251, v116 row_newbcast:4 row_mask:0xf bank_mask:0xf
	v_fmac_f32_dpp v139, v251, v122 row_newbcast:6 row_mask:0xf bank_mask:0xf
	s_nop 0
	v_fmac_f32_dpp v238, v250, v46 row_newbcast:5 row_mask:0xf bank_mask:0xf
	v_fmac_f32_dpp v239, v250, v40 row_newbcast:3 row_mask:0xf bank_mask:0xf
	v_fmac_f32_dpp v138, v251, v130 row_newbcast:8 row_mask:0xf bank_mask:0xf
	s_waitcnt lgkmcnt(0)
	v_add_u32_e32 v254, 0xb400, v208
	ds_read2_b32 v[242:243], v254 offset0:140 offset1:176
	v_fmac_f32_dpp v142, v252, v71 row_newbcast:0 row_mask:0xf bank_mask:0xf
	v_fmac_f32_dpp v143, v252, v235 row_newbcast:2 row_mask:0xf bank_mask:0xf
	v_fmac_f32_dpp v238, v250, v80 row_newbcast:9 row_mask:0xf bank_mask:0xf
	v_fmac_f32_dpp v239, v250, v74 row_newbcast:7 row_mask:0xf bank_mask:0xf
	s_nop 0
	v_fmac_f32_dpp v142, v252, v4 row_newbcast:4 row_mask:0xf bank_mask:0xf
	v_fmac_f32_dpp v143, v252, v8 row_newbcast:6 row_mask:0xf bank_mask:0xf
	v_fmac_f32_dpp v238, v250, v92 row_newbcast:13 row_mask:0xf bank_mask:0xf
	v_fmac_f32_dpp v239, v250, v86 row_newbcast:11 row_mask:0xf bank_mask:0xf
	s_nop 0
	v_fmac_f32_dpp v142, v252, v12 row_newbcast:8 row_mask:0xf bank_mask:0xf
	v_fmac_f32_dpp v143, v252, v18 row_newbcast:10 row_mask:0xf bank_mask:0xf
	v_fmac_f32_dpp v238, v251, v106 row_newbcast:1 row_mask:0xf bank_mask:0xf
	v_fmac_f32_dpp v239, v250, v98 row_newbcast:15 row_mask:0xf bank_mask:0xf
	s_nop 0
	v_fmac_f32_dpp v142, v252, v22 row_newbcast:12 row_mask:0xf bank_mask:0xf
	v_fmac_f32_dpp v143, v252, v26 row_newbcast:14 row_mask:0xf bank_mask:0xf
	v_fmac_f32_dpp v238, v251, v118 row_newbcast:5 row_mask:0xf bank_mask:0xf
	v_fmac_f32_dpp v239, v251, v112 row_newbcast:3 row_mask:0xf bank_mask:0xf
	s_nop 0
	v_fmac_f32_dpp v142, v253, v32 row_newbcast:0 row_mask:0xf bank_mask:0xf
	v_fmac_f32_dpp v143, v253, v38 row_newbcast:2 row_mask:0xf bank_mask:0xf
	v_fmac_f32_dpp v238, v251, v134 row_newbcast:9 row_mask:0xf bank_mask:0xf
	v_fmac_f32_dpp v239, v251, v126 row_newbcast:7 row_mask:0xf bank_mask:0xf
	s_nop 0
	v_fmac_f32_dpp v142, v253, v42 row_newbcast:4 row_mask:0xf bank_mask:0xf
	v_fmac_f32_dpp v143, v253, v72 row_newbcast:6 row_mask:0xf bank_mask:0xf
	s_nop 0
	v_pk_add_f32 v[138:139], v[138:139], v[238:239]
	v_mul_f32_dpp v238, v252, v234 row_newbcast:1 row_mask:0xf bank_mask:0xf
	v_fmac_f32_dpp v238, v252, v6 row_newbcast:5 row_mask:0xf bank_mask:0xf
	v_mul_f32_dpp v239, v252, v2 row_newbcast:3 row_mask:0xf bank_mask:0xf
	v_fmac_f32_dpp v142, v253, v78 row_newbcast:8 row_mask:0xf bank_mask:0xf
	v_fmac_f32_dpp v143, v253, v84 row_newbcast:10 row_mask:0xf bank_mask:0xf
	v_pk_add_f32 v[138:139], v[138:139], v[138:139] op_sel:[0,1] op_sel_hi:[1,0]
	v_fmac_f32_dpp v238, v252, v14 row_newbcast:9 row_mask:0xf bank_mask:0xf
	v_fmac_f32_dpp v239, v252, v10 row_newbcast:7 row_mask:0xf bank_mask:0xf
	v_fmac_f32_dpp v142, v253, v90 row_newbcast:12 row_mask:0xf bank_mask:0xf
	v_fmac_f32_dpp v143, v253, v96 row_newbcast:14 row_mask:0xf bank_mask:0xf
	s_waitcnt lgkmcnt(0)
; #define LAS __attribute__((address_space(3)))
; __device__ __forceinline__ void dn_prep_item(const Args& a, LAS unsigned char* lds, int item, int tid, int wave, int lane, int& cwh, int next_item) {
;     ...
;         { const LAS float* lrow = Lm + (lane & 15);
; #pragma unroll
;         for (int i = 1; i < 64; ++i) { float sa[4] = { x[i], 0.f, 0.f, 0.f };
;             int lr[4];
; #pragma unroll
;             for (int g = 0; g < (i + 15) / 16; ++g) lr[g] = __float_as_int(lrow[i * 68 + 16 * g]);
; #pragma unroll
;             for (int j = 0; j < i; ++j) { fmac_rowbcast_sel(sa[j & 3], lr[j >> 4], x[j], j); }
;             x[i] = (sa[0] + sa[1]) + (sa[2] + sa[3]); } }
	v_add_u32_e32 v254, 0xb400, v208
	ds_read2_b32 v[246:247], v254 offset0:192 offset1:208
	v_fmac_f32_dpp v144, v243, v71 row_newbcast:0 row_mask:0xf bank_mask:0xf
	v_fmac_f32_dpp v145, v243, v235 row_newbcast:2 row_mask:0xf bank_mask:0xf
	v_fmac_f32_dpp v238, v252, v24 row_newbcast:13 row_mask:0xf bank_mask:0xf
	v_fmac_f32_dpp v239, v252, v20 row_newbcast:11 row_mask:0xf bank_mask:0xf
	v_fmac_f32_dpp v142, v242, v102 row_newbcast:0 row_mask:0xf bank_mask:0xf
	v_fmac_f32_dpp v143, v242, v108 row_newbcast:2 row_mask:0xf bank_mask:0xf
	s_nop 0
	v_fmac_f32_dpp v144, v243, v4 row_newbcast:4 row_mask:0xf bank_mask:0xf
	v_fmac_f32_dpp v145, v243, v8 row_newbcast:6 row_mask:0xf bank_mask:0xf
	v_fmac_f32_dpp v238, v253, v34 row_newbcast:1 row_mask:0xf bank_mask:0xf
	v_fmac_f32_dpp v239, v252, v30 row_newbcast:15 row_mask:0xf bank_mask:0xf
	v_fmac_f32_dpp v142, v242, v116 row_newbcast:4 row_mask:0xf bank_mask:0xf
	v_fmac_f32_dpp v143, v242, v122 row_newbcast:6 row_mask:0xf bank_mask:0xf
	s_nop 0
	v_fmac_f32_dpp v144, v243, v12 row_newbcast:8 row_mask:0xf bank_mask:0xf
	v_fmac_f32_dpp v145, v243, v18 row_newbcast:10 row_mask:0xf bank_mask:0xf
	v_fmac_f32_dpp v238, v253, v46 row_newbcast:5 row_mask:0xf bank_mask:0xf
	v_fmac_f32_dpp v239, v253, v40 row_newbcast:3 row_mask:0xf bank_mask:0xf
	v_fmac_f32_dpp v142, v242, v130 row_newbcast:8 row_mask:0xf bank_mask:0xf
	v_fmac_f32_dpp v143, v242, v138 row_newbcast:10 row_mask:0xf bank_mask:0xf
	s_nop 0
	v_fmac_f32_dpp v144, v243, v22 row_newbcast:12 row_mask:0xf bank_mask:0xf
	v_fmac_f32_dpp v145, v243, v26 row_newbcast:14 row_mask:0xf bank_mask:0xf
	v_fmac_f32_dpp v238, v253, v80 row_newbcast:9 row_mask:0xf bank_mask:0xf
	v_fmac_f32_dpp v239, v253, v74 row_newbcast:7 row_mask:0xf bank_mask:0xf
	s_nop 0
	v_fmac_f32_dpp v238, v253, v92 row_newbcast:13 row_mask:0xf bank_mask:0xf
	v_fmac_f32_dpp v239, v253, v86 row_newbcast:11 row_mask:0xf bank_mask:0xf
	s_nop 0
	v_fmac_f32_dpp v238, v242, v106 row_newbcast:1 row_mask:0xf bank_mask:0xf
	v_fmac_f32_dpp v239, v253, v98 row_newbcast:15 row_mask:0xf bank_mask:0xf
	s_nop 0
	v_fmac_f32_dpp v238, v242, v118 row_newbcast:5 row_mask:0xf bank_mask:0xf
	v_fmac_f32_dpp v239, v242, v112 row_newbcast:3 row_mask:0xf bank_mask:0xf
	s_waitcnt lgkmcnt(0)
	v_add_u32_e32 v254, 0xb600, v208
	ds_read2_b32 v[248:249], v254 offset0:116 offset1:132
	v_fmac_f32_dpp v144, v246, v32 row_newbcast:0 row_mask:0xf bank_mask:0xf
	v_fmac_f32_dpp v145, v246, v38 row_newbcast:2 row_mask:0xf bank_mask:0xf
	v_add_u32_e32 v1, 0xb600, v208
	v_fmac_f32_dpp v238, v242, v134 row_newbcast:9 row_mask:0xf bank_mask:0xf
	v_fmac_f32_dpp v239, v242, v126 row_newbcast:7 row_mask:0xf bank_mask:0xf
	v_fmac_f32_dpp v144, v246, v42 row_newbcast:4 row_mask:0xf bank_mask:0xf
	v_fmac_f32_dpp v145, v246, v72 row_newbcast:6 row_mask:0xf bank_mask:0xf
	s_nop 0
	v_pk_add_f32 v[142:143], v[142:143], v[238:239]
	v_mul_f32_dpp v238, v243, v234 row_newbcast:1 row_mask:0xf bank_mask:0xf
	v_mul_f32_dpp v239, v243, v2 row_newbcast:3 row_mask:0xf bank_mask:0xf
	v_fmac_f32_dpp v238, v243, v6 row_newbcast:5 row_mask:0xf bank_mask:0xf
	v_fmac_f32_dpp v144, v246, v78 row_newbcast:8 row_mask:0xf bank_mask:0xf
	v_fmac_f32_dpp v145, v246, v84 row_newbcast:10 row_mask:0xf bank_mask:0xf
	v_pk_add_f32 v[142:143], v[142:143], v[142:143] op_sel:[0,1] op_sel_hi:[1,0]
	v_fmac_f32_dpp v239, v243, v10 row_newbcast:7 row_mask:0xf bank_mask:0xf
	v_fmac_f32_dpp v238, v243, v14 row_newbcast:9 row_mask:0xf bank_mask:0xf
	v_fmac_f32_dpp v144, v246, v90 row_newbcast:12 row_mask:0xf bank_mask:0xf
	v_fmac_f32_dpp v145, v246, v96 row_newbcast:14 row_mask:0xf bank_mask:0xf
	s_nop 0
	v_fmac_f32_dpp v239, v243, v20 row_newbcast:11 row_mask:0xf bank_mask:0xf
	v_fmac_f32_dpp v238, v243, v24 row_newbcast:13 row_mask:0xf bank_mask:0xf
	v_fmac_f32_dpp v144, v247, v102 row_newbcast:0 row_mask:0xf bank_mask:0xf
	v_fmac_f32_dpp v145, v247, v108 row_newbcast:2 row_mask:0xf bank_mask:0xf
	s_nop 0
	v_fmac_f32_dpp v239, v243, v30 row_newbcast:15 row_mask:0xf bank_mask:0xf
	v_fmac_f32_dpp v238, v246, v34 row_newbcast:1 row_mask:0xf bank_mask:0xf
	v_fmac_f32_dpp v144, v247, v116 row_newbcast:4 row_mask:0xf bank_mask:0xf
	v_fmac_f32_dpp v145, v247, v122 row_newbcast:6 row_mask:0xf bank_mask:0xf
	s_nop 0
	v_fmac_f32_dpp v239, v246, v40 row_newbcast:3 row_mask:0xf bank_mask:0xf
	v_fmac_f32_dpp v238, v246, v46 row_newbcast:5 row_mask:0xf bank_mask:0xf
	v_fmac_f32_dpp v144, v247, v130 row_newbcast:8 row_mask:0xf bank_mask:0xf
	v_fmac_f32_dpp v145, v247, v138 row_newbcast:10 row_mask:0xf bank_mask:0xf
	s_waitcnt lgkmcnt(0)
; #define LAS __attribute__((address_space(3)))
; __device__ __forceinline__ void dn_prep_item(const Args& a, LAS unsigned char* lds, int item, int tid, int wave, int lane, int& cwh, int next_item) {
;     ...
;         { const LAS float* lrow = Lm + (lane & 15);
; #pragma unroll
;         for (int i = 1; i < 64; ++i) { float sa[4] = { x[i], 0.f, 0.f, 0.f };
;             int lr[4];
; #pragma unroll
;             for (int g = 0; g < (i + 15) / 16; ++g) lr[g] = __float_as_int(lrow[i * 68 + 16 * g]);
; #pragma unroll
;             for (int j = 0; j < i; ++j) { fmac_rowbcast_sel(sa[j & 3], lr[j >> 4], x[j], j); }
;             x[i] = (sa[0] + sa[1]) + (sa[2] + sa[3]); } }
	v_add_u32_e32 v254, 0xb800, v208
	ds_read2_b32 v[250:251], v254 offset0:20 offset1:56
	v_fmac_f32_dpp v140, v248, v71 row_newbcast:0 row_mask:0xf bank_mask:0xf
	v_fmac_f32_dpp v141, v248, v235 row_newbcast:2 row_mask:0xf bank_mask:0xf
	v_fmac_f32_dpp v239, v246, v74 row_newbcast:7 row_mask:0xf bank_mask:0xf
	v_fmac_f32_dpp v238, v246, v80 row_newbcast:9 row_mask:0xf bank_mask:0xf
	v_add_u32_e32 v1, 0xb800, v208
	v_fmac_f32_dpp v239, v246, v86 row_newbcast:11 row_mask:0xf bank_mask:0xf
	v_fmac_f32_dpp v238, v246, v92 row_newbcast:13 row_mask:0xf bank_mask:0xf
	v_fmac_f32_dpp v140, v248, v4 row_newbcast:4 row_mask:0xf bank_mask:0xf
	v_fmac_f32_dpp v141, v248, v8 row_newbcast:6 row_mask:0xf bank_mask:0xf
	s_nop 0
	v_fmac_f32_dpp v239, v246, v98 row_newbcast:15 row_mask:0xf bank_mask:0xf
	v_fmac_f32_dpp v238, v247, v106 row_newbcast:1 row_mask:0xf bank_mask:0xf
	v_fmac_f32_dpp v140, v248, v12 row_newbcast:8 row_mask:0xf bank_mask:0xf
	v_fmac_f32_dpp v141, v248, v18 row_newbcast:10 row_mask:0xf bank_mask:0xf
	s_nop 0
	v_fmac_f32_dpp v239, v247, v112 row_newbcast:3 row_mask:0xf bank_mask:0xf
	v_fmac_f32_dpp v238, v247, v118 row_newbcast:5 row_mask:0xf bank_mask:0xf
	v_fmac_f32_dpp v140, v248, v22 row_newbcast:12 row_mask:0xf bank_mask:0xf
	v_fmac_f32_dpp v141, v248, v26 row_newbcast:14 row_mask:0xf bank_mask:0xf
	s_nop 0
	v_fmac_f32_dpp v239, v247, v126 row_newbcast:7 row_mask:0xf bank_mask:0xf
	v_fmac_f32_dpp v238, v247, v134 row_newbcast:9 row_mask:0xf bank_mask:0xf
	v_fmac_f32_dpp v140, v249, v32 row_newbcast:0 row_mask:0xf bank_mask:0xf
	v_fmac_f32_dpp v141, v249, v38 row_newbcast:2 row_mask:0xf bank_mask:0xf
	s_nop 0
	v_fmac_f32_dpp v239, v247, v142 row_newbcast:11 row_mask:0xf bank_mask:0xf
	v_fmac_f32_dpp v140, v249, v42 row_newbcast:4 row_mask:0xf bank_mask:0xf
	v_fmac_f32_dpp v141, v249, v72 row_newbcast:6 row_mask:0xf bank_mask:0xf
	s_nop 0
	v_pk_add_f32 v[144:145], v[144:145], v[238:239]
	v_mul_f32_dpp v238, v248, v234 row_newbcast:1 row_mask:0xf bank_mask:0xf
	v_mul_f32_dpp v239, v248, v2 row_newbcast:3 row_mask:0xf bank_mask:0xf
	v_fmac_f32_dpp v238, v248, v6 row_newbcast:5 row_mask:0xf bank_mask:0xf
	v_fmac_f32_dpp v140, v249, v78 row_newbcast:8 row_mask:0xf bank_mask:0xf
	v_fmac_f32_dpp v141, v249, v84 row_newbcast:10 row_mask:0xf bank_mask:0xf
	v_pk_add_f32 v[144:145], v[144:145], v[144:145] op_sel:[0,1] op_sel_hi:[1,0]
	v_fmac_f32_dpp v239, v248, v10 row_newbcast:7 row_mask:0xf bank_mask:0xf
	v_fmac_f32_dpp v238, v248, v14 row_newbcast:9 row_mask:0xf bank_mask:0xf
	v_fmac_f32_dpp v140, v249, v90 row_newbcast:12 row_mask:0xf bank_mask:0xf
	v_fmac_f32_dpp v141, v249, v96 row_newbcast:14 row_mask:0xf bank_mask:0xf
	s_waitcnt lgkmcnt(0)
	v_add_u32_e32 v254, 0xb800, v208
	ds_read2_b32 v[252:253], v254 offset0:72 offset1:88
	v_fmac_f32_dpp v136, v251, v71 row_newbcast:0 row_mask:0xf bank_mask:0xf
	v_fmac_f32_dpp v137, v251, v235 row_newbcast:2 row_mask:0xf bank_mask:0xf
	v_fmac_f32_dpp v239, v248, v20 row_newbcast:11 row_mask:0xf bank_mask:0xf
	v_fmac_f32_dpp v238, v248, v24 row_newbcast:13 row_mask:0xf bank_mask:0xf
	v_fmac_f32_dpp v140, v250, v102 row_newbcast:0 row_mask:0xf bank_mask:0xf
	v_fmac_f32_dpp v141, v250, v108 row_newbcast:2 row_mask:0xf bank_mask:0xf
	s_nop 0
	v_fmac_f32_dpp v136, v251, v4 row_newbcast:4 row_mask:0xf bank_mask:0xf
	v_fmac_f32_dpp v137, v251, v8 row_newbcast:6 row_mask:0xf bank_mask:0xf
	v_fmac_f32_dpp v239, v248, v30 row_newbcast:15 row_mask:0xf bank_mask:0xf
	v_fmac_f32_dpp v238, v249, v34 row_newbcast:1 row_mask:0xf bank_mask:0xf
	v_fmac_f32_dpp v140, v250, v116 row_newbcast:4 row_mask:0xf bank_mask:0xf
	v_fmac_f32_dpp v141, v250, v122 row_newbcast:6 row_mask:0xf bank_mask:0xf
	s_nop 0
	v_fmac_f32_dpp v136, v251, v12 row_newbcast:8 row_mask:0xf bank_mask:0xf
	v_fmac_f32_dpp v137, v251, v18 row_newbcast:10 row_mask:0xf bank_mask:0xf
	v_fmac_f32_dpp v239, v249, v40 row_newbcast:3 row_mask:0xf bank_mask:0xf
	v_fmac_f32_dpp v238, v249, v46 row_newbcast:5 row_mask:0xf bank_mask:0xf
	v_fmac_f32_dpp v140, v250, v130 row_newbcast:8 row_mask:0xf bank_mask:0xf
	v_fmac_f32_dpp v141, v250, v138 row_newbcast:10 row_mask:0xf bank_mask:0xf
	s_nop 0
	v_fmac_f32_dpp v136, v251, v22 row_newbcast:12 row_mask:0xf bank_mask:0xf
	v_fmac_f32_dpp v137, v251, v26 row_newbcast:14 row_mask:0xf bank_mask:0xf
	v_fmac_f32_dpp v239, v249, v74 row_newbcast:7 row_mask:0xf bank_mask:0xf
	v_fmac_f32_dpp v238, v249, v80 row_newbcast:9 row_mask:0xf bank_mask:0xf
	v_fmac_f32_dpp v140, v250, v144 row_newbcast:12 row_mask:0xf bank_mask:0xf
	s_nop 0
	v_fmac_f32_dpp v239, v249, v86 row_newbcast:11 row_mask:0xf bank_mask:0xf
	v_fmac_f32_dpp v238, v249, v92 row_newbcast:13 row_mask:0xf bank_mask:0xf
	s_nop 0
	v_fmac_f32_dpp v239, v249, v98 row_newbcast:15 row_mask:0xf bank_mask:0xf
	v_fmac_f32_dpp v238, v250, v106 row_newbcast:1 row_mask:0xf bank_mask:0xf
	s_nop 0
	v_fmac_f32_dpp v239, v250, v112 row_newbcast:3 row_mask:0xf bank_mask:0xf
	v_fmac_f32_dpp v238, v250, v118 row_newbcast:5 row_mask:0xf bank_mask:0xf
	s_waitcnt lgkmcnt(0)
; #define LAS __attribute__((address_space(3)))
; __device__ __forceinline__ void dn_prep_item(const Args& a, LAS unsigned char* lds, int item, int tid, int wave, int lane, int& cwh, int next_item) {
;     ...
;         { const LAS float* lrow = Lm + (lane & 15);
; #pragma unroll
;         for (int i = 1; i < 64; ++i) { float sa[4] = { x[i], 0.f, 0.f, 0.f };
;             int lr[4];
; #pragma unroll
;             for (int g = 0; g < (i + 15) / 16; ++g) lr[g] = __float_as_int(lrow[i * 68 + 16 * g]);
; #pragma unroll
;             for (int j = 0; j < i; ++j) { fmac_rowbcast_sel(sa[j & 3], lr[j >> 4], x[j], j); }
;             x[i] = (sa[0] + sa[1]) + (sa[2] + sa[3]); } }
	v_add_u32_e32 v254, 0xb800, v208
	ds_read2_b32 v[242:243], v254 offset0:124 offset1:140
	v_fmac_f32_dpp v136, v252, v32 row_newbcast:0 row_mask:0xf bank_mask:0xf
	v_fmac_f32_dpp v137, v252, v38 row_newbcast:2 row_mask:0xf bank_mask:0xf
	v_fmac_f32_dpp v239, v250, v126 row_newbcast:7 row_mask:0xf bank_mask:0xf
	v_fmac_f32_dpp v238, v250, v134 row_newbcast:9 row_mask:0xf bank_mask:0xf
	s_nop 0
	v_fmac_f32_dpp v136, v252, v42 row_newbcast:4 row_mask:0xf bank_mask:0xf
	v_fmac_f32_dpp v137, v252, v72 row_newbcast:6 row_mask:0xf bank_mask:0xf
	v_fmac_f32_dpp v239, v250, v142 row_newbcast:11 row_mask:0xf bank_mask:0xf
	s_nop 0
	v_fmac_f32_dpp v136, v252, v78 row_newbcast:8 row_mask:0xf bank_mask:0xf
	v_fmac_f32_dpp v137, v252, v84 row_newbcast:10 row_mask:0xf bank_mask:0xf
	v_pk_add_f32 v[140:141], v[140:141], v[238:239]
	v_mul_f32_dpp v238, v251, v234 row_newbcast:1 row_mask:0xf bank_mask:0xf
	v_fmac_f32_dpp v238, v251, v6 row_newbcast:5 row_mask:0xf bank_mask:0xf
	v_mul_f32_dpp v239, v251, v2 row_newbcast:3 row_mask:0xf bank_mask:0xf
	v_fmac_f32_dpp v136, v252, v90 row_newbcast:12 row_mask:0xf bank_mask:0xf
	v_fmac_f32_dpp v137, v252, v96 row_newbcast:14 row_mask:0xf bank_mask:0xf
	v_pk_add_f32 v[140:141], v[140:141], v[140:141] op_sel:[0,1] op_sel_hi:[1,0]
	v_fmac_f32_dpp v238, v251, v14 row_newbcast:9 row_mask:0xf bank_mask:0xf
	v_fmac_f32_dpp v239, v251, v10 row_newbcast:7 row_mask:0xf bank_mask:0xf
	v_fmac_f32_dpp v136, v253, v102 row_newbcast:0 row_mask:0xf bank_mask:0xf
	v_fmac_f32_dpp v137, v253, v108 row_newbcast:2 row_mask:0xf bank_mask:0xf
	s_nop 0
	v_fmac_f32_dpp v238, v251, v24 row_newbcast:13 row_mask:0xf bank_mask:0xf
	v_fmac_f32_dpp v239, v251, v20 row_newbcast:11 row_mask:0xf bank_mask:0xf
	v_fmac_f32_dpp v136, v253, v116 row_newbcast:4 row_mask:0xf bank_mask:0xf
	v_fmac_f32_dpp v137, v253, v122 row_newbcast:6 row_mask:0xf bank_mask:0xf
	s_nop 0
	v_fmac_f32_dpp v238, v252, v34 row_newbcast:1 row_mask:0xf bank_mask:0xf
	v_fmac_f32_dpp v239, v251, v30 row_newbcast:15 row_mask:0xf bank_mask:0xf
	v_fmac_f32_dpp v136, v253, v130 row_newbcast:8 row_mask:0xf bank_mask:0xf
	v_fmac_f32_dpp v137, v253, v138 row_newbcast:10 row_mask:0xf bank_mask:0xf
	s_nop 0
	v_fmac_f32_dpp v238, v252, v46 row_newbcast:5 row_mask:0xf bank_mask:0xf
	v_fmac_f32_dpp v239, v252, v40 row_newbcast:3 row_mask:0xf bank_mask:0xf
	v_fmac_f32_dpp v136, v253, v144 row_newbcast:12 row_mask:0xf bank_mask:0xf
	s_waitcnt lgkmcnt(0)
	v_add_u32_e32 v254, 0xb800, v208
	ds_read2_b32 v[246:247], v254 offset0:156 offset1:192
	v_fmac_f32_dpp v132, v242, v71 row_newbcast:0 row_mask:0xf bank_mask:0xf
	v_fmac_f32_dpp v133, v242, v235 row_newbcast:2 row_mask:0xf bank_mask:0xf
	v_fmac_f32_dpp v238, v252, v80 row_newbcast:9 row_mask:0xf bank_mask:0xf
	v_fmac_f32_dpp v239, v252, v74 row_newbcast:7 row_mask:0xf bank_mask:0xf
	s_nop 0
	v_fmac_f32_dpp v132, v242, v4 row_newbcast:4 row_mask:0xf bank_mask:0xf
	v_fmac_f32_dpp v133, v242, v8 row_newbcast:6 row_mask:0xf bank_mask:0xf
	v_fmac_f32_dpp v238, v252, v92 row_newbcast:13 row_mask:0xf bank_mask:0xf
	v_fmac_f32_dpp v239, v252, v86 row_newbcast:11 row_mask:0xf bank_mask:0xf
	s_nop 0
	v_fmac_f32_dpp v132, v242, v12 row_newbcast:8 row_mask:0xf bank_mask:0xf
	v_fmac_f32_dpp v133, v242, v18 row_newbcast:10 row_mask:0xf bank_mask:0xf
	v_fmac_f32_dpp v238, v253, v106 row_newbcast:1 row_mask:0xf bank_mask:0xf
	v_fmac_f32_dpp v239, v252, v98 row_newbcast:15 row_mask:0xf bank_mask:0xf
	s_nop 0
	v_fmac_f32_dpp v132, v242, v22 row_newbcast:12 row_mask:0xf bank_mask:0xf
	v_fmac_f32_dpp v133, v242, v26 row_newbcast:14 row_mask:0xf bank_mask:0xf
	v_fmac_f32_dpp v238, v253, v118 row_newbcast:5 row_mask:0xf bank_mask:0xf
	v_fmac_f32_dpp v239, v253, v112 row_newbcast:3 row_mask:0xf bank_mask:0xf
	s_nop 0
	v_fmac_f32_dpp v132, v243, v32 row_newbcast:0 row_mask:0xf bank_mask:0xf
	v_fmac_f32_dpp v133, v243, v38 row_newbcast:2 row_mask:0xf bank_mask:0xf
	v_fmac_f32_dpp v238, v253, v134 row_newbcast:9 row_mask:0xf bank_mask:0xf
	v_fmac_f32_dpp v239, v253, v126 row_newbcast:7 row_mask:0xf bank_mask:0xf
	s_nop 0
	v_fmac_f32_dpp v132, v243, v42 row_newbcast:4 row_mask:0xf bank_mask:0xf
	v_fmac_f32_dpp v133, v243, v72 row_newbcast:6 row_mask:0xf bank_mask:0xf
	v_fmac_f32_dpp v238, v253, v140 row_newbcast:13 row_mask:0xf bank_mask:0xf
	v_fmac_f32_dpp v239, v253, v142 row_newbcast:11 row_mask:0xf bank_mask:0xf
	s_nop 0
	v_fmac_f32_dpp v132, v243, v78 row_newbcast:8 row_mask:0xf bank_mask:0xf
	v_fmac_f32_dpp v133, v243, v84 row_newbcast:10 row_mask:0xf bank_mask:0xf
	s_nop 0
	v_pk_add_f32 v[136:137], v[136:137], v[238:239]
	v_mul_f32_dpp v238, v242, v234 row_newbcast:1 row_mask:0xf bank_mask:0xf
	v_fmac_f32_dpp v238, v242, v6 row_newbcast:5 row_mask:0xf bank_mask:0xf
	v_mul_f32_dpp v239, v242, v2 row_newbcast:3 row_mask:0xf bank_mask:0xf
	v_fmac_f32_dpp v132, v243, v90 row_newbcast:12 row_mask:0xf bank_mask:0xf
	v_fmac_f32_dpp v133, v243, v96 row_newbcast:14 row_mask:0xf bank_mask:0xf
	v_pk_add_f32 v[136:137], v[136:137], v[136:137] op_sel:[0,1] op_sel_hi:[1,0]
	v_fmac_f32_dpp v238, v242, v14 row_newbcast:9 row_mask:0xf bank_mask:0xf
	v_fmac_f32_dpp v239, v242, v10 row_newbcast:7 row_mask:0xf bank_mask:0xf
	s_waitcnt lgkmcnt(0)
; #define LAS __attribute__((address_space(3)))
; __device__ __forceinline__ void dn_prep_item(const Args& a, LAS unsigned char* lds, int item, int tid, int wave, int lane, int& cwh, int next_item) {
;     ...
;         { const LAS float* lrow = Lm + (lane & 15);
; #pragma unroll
;         for (int i = 1; i < 64; ++i) { float sa[4] = { x[i], 0.f, 0.f, 0.f };
;             int lr[4];
; #pragma unroll
;             for (int g = 0; g < (i + 15) / 16; ++g) lr[g] = __float_as_int(lrow[i * 68 + 16 * g]);
; #pragma unroll
;             for (int j = 0; j < i; ++j) { fmac_rowbcast_sel(sa[j & 3], lr[j >> 4], x[j], j); }
;             x[i] = (sa[0] + sa[1]) + (sa[2] + sa[3]); } }
	v_add_u32_e32 v254, 0xb800, v208
	ds_read2_b32 v[248:249], v254 offset0:208 offset1:224
	v_fmac_f32_dpp v132, v246, v102 row_newbcast:0 row_mask:0xf bank_mask:0xf
	v_fmac_f32_dpp v133, v246, v108 row_newbcast:2 row_mask:0xf bank_mask:0xf
	v_fmac_f32_dpp v128, v247, v71 row_newbcast:0 row_mask:0xf bank_mask:0xf
	v_fmac_f32_dpp v129, v247, v235 row_newbcast:2 row_mask:0xf bank_mask:0xf
	v_fmac_f32_dpp v238, v242, v24 row_newbcast:13 row_mask:0xf bank_mask:0xf
	v_fmac_f32_dpp v239, v242, v20 row_newbcast:11 row_mask:0xf bank_mask:0xf
	s_nop 0
	v_fmac_f32_dpp v132, v246, v116 row_newbcast:4 row_mask:0xf bank_mask:0xf
	v_fmac_f32_dpp v133, v246, v122 row_newbcast:6 row_mask:0xf bank_mask:0xf
	v_fmac_f32_dpp v128, v247, v4 row_newbcast:4 row_mask:0xf bank_mask:0xf
	v_fmac_f32_dpp v129, v247, v8 row_newbcast:6 row_mask:0xf bank_mask:0xf
	v_fmac_f32_dpp v238, v243, v34 row_newbcast:1 row_mask:0xf bank_mask:0xf
	v_fmac_f32_dpp v239, v242, v30 row_newbcast:15 row_mask:0xf bank_mask:0xf
	s_nop 0
	v_fmac_f32_dpp v132, v246, v130 row_newbcast:8 row_mask:0xf bank_mask:0xf
	v_fmac_f32_dpp v133, v246, v138 row_newbcast:10 row_mask:0xf bank_mask:0xf
	v_fmac_f32_dpp v128, v247, v12 row_newbcast:8 row_mask:0xf bank_mask:0xf
	v_fmac_f32_dpp v129, v247, v18 row_newbcast:10 row_mask:0xf bank_mask:0xf
	v_fmac_f32_dpp v238, v243, v46 row_newbcast:5 row_mask:0xf bank_mask:0xf
	v_fmac_f32_dpp v239, v243, v40 row_newbcast:3 row_mask:0xf bank_mask:0xf
	s_nop 0
	v_fmac_f32_dpp v132, v246, v144 row_newbcast:12 row_mask:0xf bank_mask:0xf
	v_fmac_f32_dpp v133, v246, v136 row_newbcast:14 row_mask:0xf bank_mask:0xf
	v_fmac_f32_dpp v128, v247, v22 row_newbcast:12 row_mask:0xf bank_mask:0xf
	v_fmac_f32_dpp v129, v247, v26 row_newbcast:14 row_mask:0xf bank_mask:0xf
	v_fmac_f32_dpp v238, v243, v80 row_newbcast:9 row_mask:0xf bank_mask:0xf
	v_fmac_f32_dpp v239, v243, v74 row_newbcast:7 row_mask:0xf bank_mask:0xf
	s_nop 0
	v_fmac_f32_dpp v238, v243, v92 row_newbcast:13 row_mask:0xf bank_mask:0xf
	v_fmac_f32_dpp v239, v243, v86 row_newbcast:11 row_mask:0xf bank_mask:0xf
	s_nop 0
	v_fmac_f32_dpp v238, v246, v106 row_newbcast:1 row_mask:0xf bank_mask:0xf
	v_fmac_f32_dpp v239, v243, v98 row_newbcast:15 row_mask:0xf bank_mask:0xf
	s_nop 0
	v_fmac_f32_dpp v238, v246, v118 row_newbcast:5 row_mask:0xf bank_mask:0xf
	v_fmac_f32_dpp v239, v246, v112 row_newbcast:3 row_mask:0xf bank_mask:0xf
	s_waitcnt lgkmcnt(0)
	v_add_u32_e32 v254, 0xbc00, v208
	ds_read2_b32 v[250:251], v254 offset0:4 offset1:20
	v_fmac_f32_dpp v128, v248, v32 row_newbcast:0 row_mask:0xf bank_mask:0xf
	v_fmac_f32_dpp v129, v248, v38 row_newbcast:2 row_mask:0xf bank_mask:0xf
	v_add_u32_e32 v1, 0xbc00, v208
	v_fmac_f32_dpp v238, v246, v134 row_newbcast:9 row_mask:0xf bank_mask:0xf
	v_fmac_f32_dpp v239, v246, v126 row_newbcast:7 row_mask:0xf bank_mask:0xf
	v_fmac_f32_dpp v128, v248, v42 row_newbcast:4 row_mask:0xf bank_mask:0xf
	v_fmac_f32_dpp v129, v248, v72 row_newbcast:6 row_mask:0xf bank_mask:0xf
	s_nop 0
	v_fmac_f32_dpp v238, v246, v140 row_newbcast:13 row_mask:0xf bank_mask:0xf
	v_fmac_f32_dpp v239, v246, v142 row_newbcast:11 row_mask:0xf bank_mask:0xf
	v_fmac_f32_dpp v128, v248, v78 row_newbcast:8 row_mask:0xf bank_mask:0xf
	v_fmac_f32_dpp v129, v248, v84 row_newbcast:10 row_mask:0xf bank_mask:0xf
	s_nop 0
	v_pk_add_f32 v[132:133], v[132:133], v[238:239]
	v_mul_f32_dpp v238, v247, v234 row_newbcast:1 row_mask:0xf bank_mask:0xf
	v_mul_f32_dpp v239, v247, v2 row_newbcast:3 row_mask:0xf bank_mask:0xf
	v_fmac_f32_dpp v238, v247, v6 row_newbcast:5 row_mask:0xf bank_mask:0xf
	v_fmac_f32_dpp v128, v248, v90 row_newbcast:12 row_mask:0xf bank_mask:0xf
	v_fmac_f32_dpp v129, v248, v96 row_newbcast:14 row_mask:0xf bank_mask:0xf
	v_pk_add_f32 v[132:133], v[132:133], v[132:133] op_sel:[0,1] op_sel_hi:[1,0]
	v_fmac_f32_dpp v239, v247, v10 row_newbcast:7 row_mask:0xf bank_mask:0xf
	v_fmac_f32_dpp v238, v247, v14 row_newbcast:9 row_mask:0xf bank_mask:0xf
	v_fmac_f32_dpp v128, v249, v102 row_newbcast:0 row_mask:0xf bank_mask:0xf
	v_fmac_f32_dpp v129, v249, v108 row_newbcast:2 row_mask:0xf bank_mask:0xf
	s_nop 0
	v_fmac_f32_dpp v239, v247, v20 row_newbcast:11 row_mask:0xf bank_mask:0xf
	v_fmac_f32_dpp v238, v247, v24 row_newbcast:13 row_mask:0xf bank_mask:0xf
	v_fmac_f32_dpp v128, v249, v116 row_newbcast:4 row_mask:0xf bank_mask:0xf
	v_fmac_f32_dpp v129, v249, v122 row_newbcast:6 row_mask:0xf bank_mask:0xf
	s_nop 0
	v_fmac_f32_dpp v239, v247, v30 row_newbcast:15 row_mask:0xf bank_mask:0xf
	v_fmac_f32_dpp v238, v248, v34 row_newbcast:1 row_mask:0xf bank_mask:0xf
	v_fmac_f32_dpp v128, v249, v130 row_newbcast:8 row_mask:0xf bank_mask:0xf
	v_fmac_f32_dpp v129, v249, v138 row_newbcast:10 row_mask:0xf bank_mask:0xf
	s_nop 0
	v_fmac_f32_dpp v239, v248, v40 row_newbcast:3 row_mask:0xf bank_mask:0xf
	v_fmac_f32_dpp v238, v248, v46 row_newbcast:5 row_mask:0xf bank_mask:0xf
	v_fmac_f32_dpp v128, v249, v144 row_newbcast:12 row_mask:0xf bank_mask:0xf
	v_fmac_f32_dpp v129, v249, v136 row_newbcast:14 row_mask:0xf bank_mask:0xf
	s_waitcnt lgkmcnt(0)
; #define LAS __attribute__((address_space(3)))
; __device__ __forceinline__ void dn_prep_item(const Args& a, LAS unsigned char* lds, int item, int tid, int wave, int lane, int& cwh, int next_item) {
;     ...
;         { const LAS float* lrow = Lm + (lane & 15);
; #pragma unroll
;         for (int i = 1; i < 64; ++i) { float sa[4] = { x[i], 0.f, 0.f, 0.f };
;             int lr[4];
; #pragma unroll
;             for (int g = 0; g < (i + 15) / 16; ++g) lr[g] = __float_as_int(lrow[i * 68 + 16 * g]);
; #pragma unroll
;             for (int j = 0; j < i; ++j) { fmac_rowbcast_sel(sa[j & 3], lr[j >> 4], x[j], j); }
;             x[i] = (sa[0] + sa[1]) + (sa[2] + sa[3]); } }
	v_add_u32_e32 v254, 0xbc00, v208
	ds_read2_b32 v[252:253], v254 offset0:36 offset1:52
	v_fmac_f32_dpp v124, v250, v71 row_newbcast:0 row_mask:0xf bank_mask:0xf
	v_fmac_f32_dpp v125, v250, v235 row_newbcast:2 row_mask:0xf bank_mask:0xf
	v_fmac_f32_dpp v239, v248, v74 row_newbcast:7 row_mask:0xf bank_mask:0xf
	v_fmac_f32_dpp v238, v248, v80 row_newbcast:9 row_mask:0xf bank_mask:0xf
	s_nop 0
	v_fmac_f32_dpp v239, v248, v86 row_newbcast:11 row_mask:0xf bank_mask:0xf
	v_fmac_f32_dpp v238, v248, v92 row_newbcast:13 row_mask:0xf bank_mask:0xf
	v_fmac_f32_dpp v124, v250, v4 row_newbcast:4 row_mask:0xf bank_mask:0xf
	v_fmac_f32_dpp v125, v250, v8 row_newbcast:6 row_mask:0xf bank_mask:0xf
	s_nop 0
	v_fmac_f32_dpp v239, v248, v98 row_newbcast:15 row_mask:0xf bank_mask:0xf
	v_fmac_f32_dpp v238, v249, v106 row_newbcast:1 row_mask:0xf bank_mask:0xf
	v_fmac_f32_dpp v124, v250, v12 row_newbcast:8 row_mask:0xf bank_mask:0xf
	v_fmac_f32_dpp v125, v250, v18 row_newbcast:10 row_mask:0xf bank_mask:0xf
	s_nop 0
	v_fmac_f32_dpp v239, v249, v112 row_newbcast:3 row_mask:0xf bank_mask:0xf
	v_fmac_f32_dpp v238, v249, v118 row_newbcast:5 row_mask:0xf bank_mask:0xf
	v_fmac_f32_dpp v124, v250, v22 row_newbcast:12 row_mask:0xf bank_mask:0xf
	v_fmac_f32_dpp v125, v250, v26 row_newbcast:14 row_mask:0xf bank_mask:0xf
	s_nop 0
	v_fmac_f32_dpp v239, v249, v126 row_newbcast:7 row_mask:0xf bank_mask:0xf
	v_fmac_f32_dpp v238, v249, v134 row_newbcast:9 row_mask:0xf bank_mask:0xf
	v_fmac_f32_dpp v124, v251, v32 row_newbcast:0 row_mask:0xf bank_mask:0xf
	v_fmac_f32_dpp v125, v251, v38 row_newbcast:2 row_mask:0xf bank_mask:0xf
	s_nop 0
	v_fmac_f32_dpp v239, v249, v142 row_newbcast:11 row_mask:0xf bank_mask:0xf
	v_fmac_f32_dpp v238, v249, v140 row_newbcast:13 row_mask:0xf bank_mask:0xf
	v_fmac_f32_dpp v124, v251, v42 row_newbcast:4 row_mask:0xf bank_mask:0xf
	v_fmac_f32_dpp v125, v251, v72 row_newbcast:6 row_mask:0xf bank_mask:0xf
	s_nop 0
	v_fmac_f32_dpp v239, v249, v132 row_newbcast:15 row_mask:0xf bank_mask:0xf
	v_fmac_f32_dpp v124, v251, v78 row_newbcast:8 row_mask:0xf bank_mask:0xf
	v_fmac_f32_dpp v125, v251, v84 row_newbcast:10 row_mask:0xf bank_mask:0xf
	s_nop 0
	v_pk_add_f32 v[128:129], v[128:129], v[238:239]
	v_mul_f32_dpp v238, v250, v234 row_newbcast:1 row_mask:0xf bank_mask:0xf
	v_mul_f32_dpp v239, v250, v2 row_newbcast:3 row_mask:0xf bank_mask:0xf
	v_fmac_f32_dpp v238, v250, v6 row_newbcast:5 row_mask:0xf bank_mask:0xf
	v_fmac_f32_dpp v124, v251, v90 row_newbcast:12 row_mask:0xf bank_mask:0xf
	v_fmac_f32_dpp v125, v251, v96 row_newbcast:14 row_mask:0xf bank_mask:0xf
	v_pk_add_f32 v[128:129], v[128:129], v[128:129] op_sel:[0,1] op_sel_hi:[1,0]
	v_fmac_f32_dpp v239, v250, v10 row_newbcast:7 row_mask:0xf bank_mask:0xf
	v_fmac_f32_dpp v238, v250, v14 row_newbcast:9 row_mask:0xf bank_mask:0xf
	s_waitcnt lgkmcnt(0)
	v_add_u32_e32 v254, 0xbc00, v208
	ds_read2_b32 v[242:243], v254 offset0:72 offset1:88
	v_fmac_f32_dpp v124, v252, v102 row_newbcast:0 row_mask:0xf bank_mask:0xf
	v_fmac_f32_dpp v125, v252, v108 row_newbcast:2 row_mask:0xf bank_mask:0xf
	v_fmac_f32_dpp v239, v250, v20 row_newbcast:11 row_mask:0xf bank_mask:0xf
	v_fmac_f32_dpp v238, v250, v24 row_newbcast:13 row_mask:0xf bank_mask:0xf
	s_nop 0
	v_fmac_f32_dpp v124, v252, v116 row_newbcast:4 row_mask:0xf bank_mask:0xf
	v_fmac_f32_dpp v125, v252, v122 row_newbcast:6 row_mask:0xf bank_mask:0xf
	v_fmac_f32_dpp v239, v250, v30 row_newbcast:15 row_mask:0xf bank_mask:0xf
	v_fmac_f32_dpp v238, v251, v34 row_newbcast:1 row_mask:0xf bank_mask:0xf
	s_nop 0
	v_fmac_f32_dpp v124, v252, v130 row_newbcast:8 row_mask:0xf bank_mask:0xf
	v_fmac_f32_dpp v125, v252, v138 row_newbcast:10 row_mask:0xf bank_mask:0xf
	v_fmac_f32_dpp v239, v251, v40 row_newbcast:3 row_mask:0xf bank_mask:0xf
	v_fmac_f32_dpp v238, v251, v46 row_newbcast:5 row_mask:0xf bank_mask:0xf
	s_nop 0
	v_fmac_f32_dpp v124, v252, v144 row_newbcast:12 row_mask:0xf bank_mask:0xf
	v_fmac_f32_dpp v125, v252, v136 row_newbcast:14 row_mask:0xf bank_mask:0xf
	v_fmac_f32_dpp v239, v251, v74 row_newbcast:7 row_mask:0xf bank_mask:0xf
	v_fmac_f32_dpp v238, v251, v80 row_newbcast:9 row_mask:0xf bank_mask:0xf
	s_nop 0
	v_fmac_f32_dpp v124, v253, v128 row_newbcast:0 row_mask:0xf bank_mask:0xf
	v_fmac_f32_dpp v239, v251, v86 row_newbcast:11 row_mask:0xf bank_mask:0xf
	v_fmac_f32_dpp v238, v251, v92 row_newbcast:13 row_mask:0xf bank_mask:0xf
	s_nop 0
	v_fmac_f32_dpp v239, v251, v98 row_newbcast:15 row_mask:0xf bank_mask:0xf
	v_fmac_f32_dpp v238, v252, v106 row_newbcast:1 row_mask:0xf bank_mask:0xf
	s_nop 0
	v_fmac_f32_dpp v239, v252, v112 row_newbcast:3 row_mask:0xf bank_mask:0xf
	v_fmac_f32_dpp v238, v252, v118 row_newbcast:5 row_mask:0xf bank_mask:0xf
	s_waitcnt lgkmcnt(0)
; #define LAS __attribute__((address_space(3)))
; __device__ __forceinline__ void dn_prep_item(const Args& a, LAS unsigned char* lds, int item, int tid, int wave, int lane, int& cwh, int next_item) {
;     ...
;         { const LAS float* lrow = Lm + (lane & 15);
; #pragma unroll
;         for (int i = 1; i < 64; ++i) { float sa[4] = { x[i], 0.f, 0.f, 0.f };
;             int lr[4];
; #pragma unroll
;             for (int g = 0; g < (i + 15) / 16; ++g) lr[g] = __float_as_int(lrow[i * 68 + 16 * g]);
; #pragma unroll
;             for (int j = 0; j < i; ++j) { fmac_rowbcast_sel(sa[j & 3], lr[j >> 4], x[j], j); }
;             x[i] = (sa[0] + sa[1]) + (sa[2] + sa[3]); } }
	v_add_u32_e32 v254, 0xbc00, v208
	ds_read2_b32 v[246:247], v254 offset0:104 offset1:120
	v_fmac_f32_dpp v120, v242, v71 row_newbcast:0 row_mask:0xf bank_mask:0xf
	v_fmac_f32_dpp v121, v242, v235 row_newbcast:2 row_mask:0xf bank_mask:0xf
	v_fmac_f32_dpp v239, v252, v126 row_newbcast:7 row_mask:0xf bank_mask:0xf
	v_fmac_f32_dpp v238, v252, v134 row_newbcast:9 row_mask:0xf bank_mask:0xf
	s_nop 0
	v_fmac_f32_dpp v120, v242, v4 row_newbcast:4 row_mask:0xf bank_mask:0xf
	v_fmac_f32_dpp v121, v242, v8 row_newbcast:6 row_mask:0xf bank_mask:0xf
	v_fmac_f32_dpp v239, v252, v142 row_newbcast:11 row_mask:0xf bank_mask:0xf
	v_fmac_f32_dpp v238, v252, v140 row_newbcast:13 row_mask:0xf bank_mask:0xf
	s_nop 0
	v_fmac_f32_dpp v120, v242, v12 row_newbcast:8 row_mask:0xf bank_mask:0xf
	v_fmac_f32_dpp v121, v242, v18 row_newbcast:10 row_mask:0xf bank_mask:0xf
	v_fmac_f32_dpp v239, v252, v132 row_newbcast:15 row_mask:0xf bank_mask:0xf
	s_nop 0
	v_fmac_f32_dpp v120, v242, v22 row_newbcast:12 row_mask:0xf bank_mask:0xf
	v_fmac_f32_dpp v121, v242, v26 row_newbcast:14 row_mask:0xf bank_mask:0xf
	s_nop 0
	v_pk_add_f32 v[124:125], v[124:125], v[238:239]
	v_mul_f32_dpp v238, v242, v234 row_newbcast:1 row_mask:0xf bank_mask:0xf
	v_fmac_f32_dpp v238, v242, v6 row_newbcast:5 row_mask:0xf bank_mask:0xf
	v_mul_f32_dpp v239, v242, v2 row_newbcast:3 row_mask:0xf bank_mask:0xf
	v_fmac_f32_dpp v120, v243, v32 row_newbcast:0 row_mask:0xf bank_mask:0xf
	v_fmac_f32_dpp v121, v243, v38 row_newbcast:2 row_mask:0xf bank_mask:0xf
	v_pk_add_f32 v[124:125], v[124:125], v[124:125] op_sel:[0,1] op_sel_hi:[1,0]
	v_fmac_f32_dpp v238, v242, v14 row_newbcast:9 row_mask:0xf bank_mask:0xf
	v_fmac_f32_dpp v239, v242, v10 row_newbcast:7 row_mask:0xf bank_mask:0xf
	v_fmac_f32_dpp v120, v243, v42 row_newbcast:4 row_mask:0xf bank_mask:0xf
	v_fmac_f32_dpp v121, v243, v72 row_newbcast:6 row_mask:0xf bank_mask:0xf
	s_nop 0
	v_fmac_f32_dpp v238, v242, v24 row_newbcast:13 row_mask:0xf bank_mask:0xf
	v_fmac_f32_dpp v239, v242, v20 row_newbcast:11 row_mask:0xf bank_mask:0xf
	v_fmac_f32_dpp v120, v243, v78 row_newbcast:8 row_mask:0xf bank_mask:0xf
	v_fmac_f32_dpp v121, v243, v84 row_newbcast:10 row_mask:0xf bank_mask:0xf
	s_nop 0
	v_fmac_f32_dpp v238, v243, v34 row_newbcast:1 row_mask:0xf bank_mask:0xf
	v_fmac_f32_dpp v239, v242, v30 row_newbcast:15 row_mask:0xf bank_mask:0xf
	v_fmac_f32_dpp v120, v243, v90 row_newbcast:12 row_mask:0xf bank_mask:0xf
	v_fmac_f32_dpp v121, v243, v96 row_newbcast:14 row_mask:0xf bank_mask:0xf
	s_nop 0
	v_fmac_f32_dpp v238, v243, v46 row_newbcast:5 row_mask:0xf bank_mask:0xf
	v_fmac_f32_dpp v239, v243, v40 row_newbcast:3 row_mask:0xf bank_mask:0xf
	s_waitcnt lgkmcnt(0)
	v_add_u32_e32 v254, 0xbc00, v208
	ds_read2_b32 v[248:249], v254 offset0:140 offset1:156
	v_fmac_f32_dpp v120, v246, v102 row_newbcast:0 row_mask:0xf bank_mask:0xf
	v_fmac_f32_dpp v121, v246, v108 row_newbcast:2 row_mask:0xf bank_mask:0xf
	v_fmac_f32_dpp v238, v243, v80 row_newbcast:9 row_mask:0xf bank_mask:0xf
	v_fmac_f32_dpp v239, v243, v74 row_newbcast:7 row_mask:0xf bank_mask:0xf
	s_nop 0
	v_fmac_f32_dpp v120, v246, v116 row_newbcast:4 row_mask:0xf bank_mask:0xf
	v_fmac_f32_dpp v121, v246, v122 row_newbcast:6 row_mask:0xf bank_mask:0xf
	v_fmac_f32_dpp v238, v243, v92 row_newbcast:13 row_mask:0xf bank_mask:0xf
	v_fmac_f32_dpp v239, v243, v86 row_newbcast:11 row_mask:0xf bank_mask:0xf
	s_nop 0
	v_fmac_f32_dpp v120, v246, v130 row_newbcast:8 row_mask:0xf bank_mask:0xf
	v_fmac_f32_dpp v121, v246, v138 row_newbcast:10 row_mask:0xf bank_mask:0xf
	v_fmac_f32_dpp v238, v246, v106 row_newbcast:1 row_mask:0xf bank_mask:0xf
	v_fmac_f32_dpp v239, v243, v98 row_newbcast:15 row_mask:0xf bank_mask:0xf
	s_nop 0
	v_fmac_f32_dpp v120, v246, v144 row_newbcast:12 row_mask:0xf bank_mask:0xf
	v_fmac_f32_dpp v121, v246, v136 row_newbcast:14 row_mask:0xf bank_mask:0xf
	s_nop 0
	v_fmac_f32_dpp v238, v246, v118 row_newbcast:5 row_mask:0xf bank_mask:0xf
	v_fmac_f32_dpp v239, v246, v112 row_newbcast:3 row_mask:0xf bank_mask:0xf
	v_fmac_f32_dpp v120, v247, v128 row_newbcast:0 row_mask:0xf bank_mask:0xf
	s_waitcnt lgkmcnt(0)
	v_add_u32_e32 v254, 0xbc00, v208
	ds_read2_b32 v[250:251], v254 offset0:172 offset1:188
	v_fmac_f32_dpp v114, v248, v71 row_newbcast:0 row_mask:0xf bank_mask:0xf
	v_fmac_f32_dpp v115, v248, v235 row_newbcast:2 row_mask:0xf bank_mask:0xf
	v_fmac_f32_dpp v238, v246, v134 row_newbcast:9 row_mask:0xf bank_mask:0xf
	v_fmac_f32_dpp v239, v246, v126 row_newbcast:7 row_mask:0xf bank_mask:0xf
	s_nop 0
	v_fmac_f32_dpp v114, v248, v4 row_newbcast:4 row_mask:0xf bank_mask:0xf
	v_fmac_f32_dpp v115, v248, v8 row_newbcast:6 row_mask:0xf bank_mask:0xf
	v_fmac_f32_dpp v238, v246, v140 row_newbcast:13 row_mask:0xf bank_mask:0xf
	v_fmac_f32_dpp v239, v246, v142 row_newbcast:11 row_mask:0xf bank_mask:0xf
	s_nop 0
	v_fmac_f32_dpp v114, v248, v12 row_newbcast:8 row_mask:0xf bank_mask:0xf
	v_fmac_f32_dpp v115, v248, v18 row_newbcast:10 row_mask:0xf bank_mask:0xf
	v_fmac_f32_dpp v238, v247, v124 row_newbcast:1 row_mask:0xf bank_mask:0xf
	v_fmac_f32_dpp v239, v246, v132 row_newbcast:15 row_mask:0xf bank_mask:0xf
	s_nop 0
	v_fmac_f32_dpp v114, v248, v22 row_newbcast:12 row_mask:0xf bank_mask:0xf
	v_fmac_f32_dpp v115, v248, v26 row_newbcast:14 row_mask:0xf bank_mask:0xf
	s_nop 0
	v_pk_add_f32 v[120:121], v[120:121], v[238:239]
	v_mul_f32_dpp v238, v248, v234 row_newbcast:1 row_mask:0xf bank_mask:0xf
	v_fmac_f32_dpp v238, v248, v6 row_newbcast:5 row_mask:0xf bank_mask:0xf
	v_mul_f32_dpp v239, v248, v2 row_newbcast:3 row_mask:0xf bank_mask:0xf
	v_fmac_f32_dpp v114, v249, v32 row_newbcast:0 row_mask:0xf bank_mask:0xf
	v_fmac_f32_dpp v115, v249, v38 row_newbcast:2 row_mask:0xf bank_mask:0xf
	v_pk_add_f32 v[120:121], v[120:121], v[120:121] op_sel:[0,1] op_sel_hi:[1,0]
	v_fmac_f32_dpp v238, v248, v14 row_newbcast:9 row_mask:0xf bank_mask:0xf
	v_fmac_f32_dpp v239, v248, v10 row_newbcast:7 row_mask:0xf bank_mask:0xf
	v_fmac_f32_dpp v114, v249, v42 row_newbcast:4 row_mask:0xf bank_mask:0xf
	v_fmac_f32_dpp v115, v249, v72 row_newbcast:6 row_mask:0xf bank_mask:0xf
	s_nop 0
	v_fmac_f32_dpp v238, v248, v24 row_newbcast:13 row_mask:0xf bank_mask:0xf
	v_fmac_f32_dpp v239, v248, v20 row_newbcast:11 row_mask:0xf bank_mask:0xf
	v_fmac_f32_dpp v114, v249, v78 row_newbcast:8 row_mask:0xf bank_mask:0xf
	v_fmac_f32_dpp v115, v249, v84 row_newbcast:10 row_mask:0xf bank_mask:0xf
	s_nop 0
	v_fmac_f32_dpp v238, v249, v34 row_newbcast:1 row_mask:0xf bank_mask:0xf
	v_fmac_f32_dpp v239, v248, v30 row_newbcast:15 row_mask:0xf bank_mask:0xf
	v_fmac_f32_dpp v114, v249, v90 row_newbcast:12 row_mask:0xf bank_mask:0xf
	v_fmac_f32_dpp v115, v249, v96 row_newbcast:14 row_mask:0xf bank_mask:0xf
	s_nop 0
	v_fmac_f32_dpp v238, v249, v46 row_newbcast:5 row_mask:0xf bank_mask:0xf
	v_fmac_f32_dpp v239, v249, v40 row_newbcast:3 row_mask:0xf bank_mask:0xf
	s_waitcnt lgkmcnt(0)
; #define LAS __attribute__((address_space(3)))
; __device__ __forceinline__ void dn_prep_item(const Args& a, LAS unsigned char* lds, int item, int tid, int wave, int lane, int& cwh, int next_item) {
;     ...
;         { const LAS float* lrow = Lm + (lane & 15);
; #pragma unroll
;         for (int i = 1; i < 64; ++i) { float sa[4] = { x[i], 0.f, 0.f, 0.f };
;             int lr[4];
; #pragma unroll
;             for (int g = 0; g < (i + 15) / 16; ++g) lr[g] = __float_as_int(lrow[i * 68 + 16 * g]);
; #pragma unroll
;             for (int j = 0; j < i; ++j) { fmac_rowbcast_sel(sa[j & 3], lr[j >> 4], x[j], j); }
;             x[i] = (sa[0] + sa[1]) + (sa[2] + sa[3]); } }
	v_add_u32_e32 v254, 0xbc00, v208
	ds_read2_b32 v[252:253], v254 offset0:208 offset1:224
	v_fmac_f32_dpp v114, v250, v102 row_newbcast:0 row_mask:0xf bank_mask:0xf
	v_fmac_f32_dpp v115, v250, v108 row_newbcast:2 row_mask:0xf bank_mask:0xf
	v_fmac_f32_dpp v238, v249, v80 row_newbcast:9 row_mask:0xf bank_mask:0xf
	v_fmac_f32_dpp v239, v249, v74 row_newbcast:7 row_mask:0xf bank_mask:0xf
	s_nop 0
	v_fmac_f32_dpp v114, v250, v116 row_newbcast:4 row_mask:0xf bank_mask:0xf
	v_fmac_f32_dpp v115, v250, v122 row_newbcast:6 row_mask:0xf bank_mask:0xf
	v_fmac_f32_dpp v238, v249, v92 row_newbcast:13 row_mask:0xf bank_mask:0xf
	v_fmac_f32_dpp v239, v249, v86 row_newbcast:11 row_mask:0xf bank_mask:0xf
	s_nop 0
	v_fmac_f32_dpp v114, v250, v130 row_newbcast:8 row_mask:0xf bank_mask:0xf
	v_fmac_f32_dpp v115, v250, v138 row_newbcast:10 row_mask:0xf bank_mask:0xf
	v_fmac_f32_dpp v238, v250, v106 row_newbcast:1 row_mask:0xf bank_mask:0xf
	v_fmac_f32_dpp v239, v249, v98 row_newbcast:15 row_mask:0xf bank_mask:0xf
	s_nop 0
	v_fmac_f32_dpp v114, v250, v144 row_newbcast:12 row_mask:0xf bank_mask:0xf
	v_fmac_f32_dpp v115, v250, v136 row_newbcast:14 row_mask:0xf bank_mask:0xf
	s_nop 0
	v_fmac_f32_dpp v238, v250, v118 row_newbcast:5 row_mask:0xf bank_mask:0xf
	v_fmac_f32_dpp v239, v250, v112 row_newbcast:3 row_mask:0xf bank_mask:0xf
	v_fmac_f32_dpp v114, v251, v128 row_newbcast:0 row_mask:0xf bank_mask:0xf
	v_fmac_f32_dpp v115, v251, v120 row_newbcast:2 row_mask:0xf bank_mask:0xf
	s_waitcnt lgkmcnt(0)
	v_add_u32_e32 v254, 0xbe00, v208
	ds_read2_b32 v[242:243], v254 offset0:112 offset1:128
	v_fmac_f32_dpp v110, v252, v71 row_newbcast:0 row_mask:0xf bank_mask:0xf
	v_fmac_f32_dpp v111, v252, v235 row_newbcast:2 row_mask:0xf bank_mask:0xf
	v_fmac_f32_dpp v238, v250, v134 row_newbcast:9 row_mask:0xf bank_mask:0xf
	v_fmac_f32_dpp v239, v250, v126 row_newbcast:7 row_mask:0xf bank_mask:0xf
	v_add_u32_e32 v1, 0xbe00, v208
	v_fmac_f32_dpp v238, v250, v140 row_newbcast:13 row_mask:0xf bank_mask:0xf
	v_fmac_f32_dpp v239, v250, v142 row_newbcast:11 row_mask:0xf bank_mask:0xf
	v_fmac_f32_dpp v110, v252, v4 row_newbcast:4 row_mask:0xf bank_mask:0xf
	v_fmac_f32_dpp v111, v252, v8 row_newbcast:6 row_mask:0xf bank_mask:0xf
	s_nop 0
	v_fmac_f32_dpp v238, v251, v124 row_newbcast:1 row_mask:0xf bank_mask:0xf
	v_fmac_f32_dpp v239, v250, v132 row_newbcast:15 row_mask:0xf bank_mask:0xf
	v_fmac_f32_dpp v110, v252, v12 row_newbcast:8 row_mask:0xf bank_mask:0xf
	v_fmac_f32_dpp v111, v252, v18 row_newbcast:10 row_mask:0xf bank_mask:0xf
	s_nop 0
	v_pk_add_f32 v[114:115], v[114:115], v[238:239]
	v_mul_f32_dpp v238, v252, v234 row_newbcast:1 row_mask:0xf bank_mask:0xf
	v_mul_f32_dpp v239, v252, v2 row_newbcast:3 row_mask:0xf bank_mask:0xf
	v_fmac_f32_dpp v238, v252, v6 row_newbcast:5 row_mask:0xf bank_mask:0xf
	v_fmac_f32_dpp v110, v252, v22 row_newbcast:12 row_mask:0xf bank_mask:0xf
	v_fmac_f32_dpp v111, v252, v26 row_newbcast:14 row_mask:0xf bank_mask:0xf
	v_add_u32_e32 v1, 0xc000, v208
	v_fmac_f32_dpp v239, v252, v10 row_newbcast:7 row_mask:0xf bank_mask:0xf
	v_fmac_f32_dpp v238, v252, v14 row_newbcast:9 row_mask:0xf bank_mask:0xf
	v_fmac_f32_dpp v110, v253, v32 row_newbcast:0 row_mask:0xf bank_mask:0xf
	v_fmac_f32_dpp v111, v253, v38 row_newbcast:2 row_mask:0xf bank_mask:0xf
	v_pk_add_f32 v[114:115], v[114:115], v[114:115] op_sel:[0,1] op_sel_hi:[1,0]
	v_fmac_f32_dpp v239, v252, v20 row_newbcast:11 row_mask:0xf bank_mask:0xf
	v_fmac_f32_dpp v238, v252, v24 row_newbcast:13 row_mask:0xf bank_mask:0xf
	v_fmac_f32_dpp v110, v253, v42 row_newbcast:4 row_mask:0xf bank_mask:0xf
	v_fmac_f32_dpp v111, v253, v72 row_newbcast:6 row_mask:0xf bank_mask:0xf
	s_nop 0
	v_fmac_f32_dpp v239, v252, v30 row_newbcast:15 row_mask:0xf bank_mask:0xf
	v_fmac_f32_dpp v238, v253, v34 row_newbcast:1 row_mask:0xf bank_mask:0xf
	v_fmac_f32_dpp v110, v253, v78 row_newbcast:8 row_mask:0xf bank_mask:0xf
	v_fmac_f32_dpp v111, v253, v84 row_newbcast:10 row_mask:0xf bank_mask:0xf
	s_nop 0
	v_fmac_f32_dpp v239, v253, v40 row_newbcast:3 row_mask:0xf bank_mask:0xf
	v_fmac_f32_dpp v238, v253, v46 row_newbcast:5 row_mask:0xf bank_mask:0xf
	v_fmac_f32_dpp v110, v253, v90 row_newbcast:12 row_mask:0xf bank_mask:0xf
	v_fmac_f32_dpp v111, v253, v96 row_newbcast:14 row_mask:0xf bank_mask:0xf
	s_nop 0
	v_fmac_f32_dpp v239, v253, v74 row_newbcast:7 row_mask:0xf bank_mask:0xf
	v_fmac_f32_dpp v238, v253, v80 row_newbcast:9 row_mask:0xf bank_mask:0xf
	s_waitcnt lgkmcnt(0)
	v_add_u32_e32 v254, 0xc000, v208
	ds_read2_b32 v[246:247], v254 offset0:20 offset1:36
	v_fmac_f32_dpp v110, v242, v102 row_newbcast:0 row_mask:0xf bank_mask:0xf
	v_fmac_f32_dpp v111, v242, v108 row_newbcast:2 row_mask:0xf bank_mask:0xf
	v_fmac_f32_dpp v239, v253, v86 row_newbcast:11 row_mask:0xf bank_mask:0xf
	v_fmac_f32_dpp v238, v253, v92 row_newbcast:13 row_mask:0xf bank_mask:0xf
	s_nop 0
	v_fmac_f32_dpp v110, v242, v116 row_newbcast:4 row_mask:0xf bank_mask:0xf
	v_fmac_f32_dpp v111, v242, v122 row_newbcast:6 row_mask:0xf bank_mask:0xf
	v_fmac_f32_dpp v239, v253, v98 row_newbcast:15 row_mask:0xf bank_mask:0xf
	v_fmac_f32_dpp v238, v242, v106 row_newbcast:1 row_mask:0xf bank_mask:0xf
	s_nop 0
	v_fmac_f32_dpp v110, v242, v130 row_newbcast:8 row_mask:0xf bank_mask:0xf
	v_fmac_f32_dpp v111, v242, v138 row_newbcast:10 row_mask:0xf bank_mask:0xf
	s_nop 0
	v_fmac_f32_dpp v239, v242, v112 row_newbcast:3 row_mask:0xf bank_mask:0xf
	v_fmac_f32_dpp v238, v242, v118 row_newbcast:5 row_mask:0xf bank_mask:0xf
	v_fmac_f32_dpp v110, v242, v144 row_newbcast:12 row_mask:0xf bank_mask:0xf
	v_fmac_f32_dpp v111, v242, v136 row_newbcast:14 row_mask:0xf bank_mask:0xf
	s_waitcnt lgkmcnt(0)
; #define LAS __attribute__((address_space(3)))
; __device__ __forceinline__ void dn_prep_item(const Args& a, LAS unsigned char* lds, int item, int tid, int wave, int lane, int& cwh, int next_item) {
;     ...
;         { const LAS float* lrow = Lm + (lane & 15);
; #pragma unroll
;         for (int i = 1; i < 64; ++i) { float sa[4] = { x[i], 0.f, 0.f, 0.f };
;             int lr[4];
; #pragma unroll
;             for (int g = 0; g < (i + 15) / 16; ++g) lr[g] = __float_as_int(lrow[i * 68 + 16 * g]);
; #pragma unroll
;             for (int j = 0; j < i; ++j) { fmac_rowbcast_sel(sa[j & 3], lr[j >> 4], x[j], j); }
;             x[i] = (sa[0] + sa[1]) + (sa[2] + sa[3]); } }
	v_add_u32_e32 v254, 0xc000, v208
	ds_read2_b32 v[248:249], v254 offset0:52 offset1:68
	v_fmac_f32_dpp v104, v246, v71 row_newbcast:0 row_mask:0xf bank_mask:0xf
	v_fmac_f32_dpp v105, v246, v235 row_newbcast:2 row_mask:0xf bank_mask:0xf
	v_fmac_f32_dpp v239, v242, v126 row_newbcast:7 row_mask:0xf bank_mask:0xf
	v_fmac_f32_dpp v238, v242, v134 row_newbcast:9 row_mask:0xf bank_mask:0xf
	v_fmac_f32_dpp v110, v243, v128 row_newbcast:0 row_mask:0xf bank_mask:0xf
	v_fmac_f32_dpp v111, v243, v120 row_newbcast:2 row_mask:0xf bank_mask:0xf
	s_nop 0
	v_fmac_f32_dpp v104, v246, v4 row_newbcast:4 row_mask:0xf bank_mask:0xf
	v_fmac_f32_dpp v105, v246, v8 row_newbcast:6 row_mask:0xf bank_mask:0xf
	v_fmac_f32_dpp v239, v242, v142 row_newbcast:11 row_mask:0xf bank_mask:0xf
	v_fmac_f32_dpp v238, v242, v140 row_newbcast:13 row_mask:0xf bank_mask:0xf
	s_nop 0
	v_fmac_f32_dpp v239, v242, v132 row_newbcast:15 row_mask:0xf bank_mask:0xf
	v_fmac_f32_dpp v238, v243, v124 row_newbcast:1 row_mask:0xf bank_mask:0xf
	v_fmac_f32_dpp v104, v246, v12 row_newbcast:8 row_mask:0xf bank_mask:0xf
	v_fmac_f32_dpp v105, v246, v18 row_newbcast:10 row_mask:0xf bank_mask:0xf
	s_nop 0
	v_fmac_f32_dpp v239, v243, v114 row_newbcast:3 row_mask:0xf bank_mask:0xf
	v_fmac_f32_dpp v104, v246, v22 row_newbcast:12 row_mask:0xf bank_mask:0xf
	v_fmac_f32_dpp v105, v246, v26 row_newbcast:14 row_mask:0xf bank_mask:0xf
	s_nop 0
	v_pk_add_f32 v[110:111], v[110:111], v[238:239]
	v_mul_f32_dpp v238, v246, v234 row_newbcast:1 row_mask:0xf bank_mask:0xf
	v_mul_f32_dpp v239, v246, v2 row_newbcast:3 row_mask:0xf bank_mask:0xf
	v_fmac_f32_dpp v238, v246, v6 row_newbcast:5 row_mask:0xf bank_mask:0xf
	v_fmac_f32_dpp v104, v247, v32 row_newbcast:0 row_mask:0xf bank_mask:0xf
	v_fmac_f32_dpp v105, v247, v38 row_newbcast:2 row_mask:0xf bank_mask:0xf
	v_pk_add_f32 v[110:111], v[110:111], v[110:111] op_sel:[0,1] op_sel_hi:[1,0]
	v_fmac_f32_dpp v239, v246, v10 row_newbcast:7 row_mask:0xf bank_mask:0xf
	v_fmac_f32_dpp v238, v246, v14 row_newbcast:9 row_mask:0xf bank_mask:0xf
	v_fmac_f32_dpp v104, v247, v42 row_newbcast:4 row_mask:0xf bank_mask:0xf
	v_fmac_f32_dpp v105, v247, v72 row_newbcast:6 row_mask:0xf bank_mask:0xf
	s_nop 0
	v_fmac_f32_dpp v239, v246, v20 row_newbcast:11 row_mask:0xf bank_mask:0xf
	v_fmac_f32_dpp v238, v246, v24 row_newbcast:13 row_mask:0xf bank_mask:0xf
	v_fmac_f32_dpp v104, v247, v78 row_newbcast:8 row_mask:0xf bank_mask:0xf
	v_fmac_f32_dpp v105, v247, v84 row_newbcast:10 row_mask:0xf bank_mask:0xf
	s_nop 0
	v_fmac_f32_dpp v239, v246, v30 row_newbcast:15 row_mask:0xf bank_mask:0xf
	v_fmac_f32_dpp v238, v247, v34 row_newbcast:1 row_mask:0xf bank_mask:0xf
	v_fmac_f32_dpp v104, v247, v90 row_newbcast:12 row_mask:0xf bank_mask:0xf
	v_fmac_f32_dpp v105, v247, v96 row_newbcast:14 row_mask:0xf bank_mask:0xf
	s_nop 0
	v_fmac_f32_dpp v239, v247, v40 row_newbcast:3 row_mask:0xf bank_mask:0xf
	v_fmac_f32_dpp v238, v247, v46 row_newbcast:5 row_mask:0xf bank_mask:0xf
	s_waitcnt lgkmcnt(0)
	v_add_u32_e32 v254, 0xc000, v208
	ds_read2_b32 v[250:251], v254 offset0:88 offset1:104
	v_fmac_f32_dpp v104, v248, v102 row_newbcast:0 row_mask:0xf bank_mask:0xf
	v_fmac_f32_dpp v105, v248, v108 row_newbcast:2 row_mask:0xf bank_mask:0xf
	v_fmac_f32_dpp v239, v247, v74 row_newbcast:7 row_mask:0xf bank_mask:0xf
	v_fmac_f32_dpp v238, v247, v80 row_newbcast:9 row_mask:0xf bank_mask:0xf
	s_nop 0
	v_fmac_f32_dpp v104, v248, v116 row_newbcast:4 row_mask:0xf bank_mask:0xf
	v_fmac_f32_dpp v105, v248, v122 row_newbcast:6 row_mask:0xf bank_mask:0xf
	v_fmac_f32_dpp v239, v247, v86 row_newbcast:11 row_mask:0xf bank_mask:0xf
	v_fmac_f32_dpp v238, v247, v92 row_newbcast:13 row_mask:0xf bank_mask:0xf
	s_nop 0
	v_fmac_f32_dpp v104, v248, v130 row_newbcast:8 row_mask:0xf bank_mask:0xf
	v_fmac_f32_dpp v105, v248, v138 row_newbcast:10 row_mask:0xf bank_mask:0xf
	v_fmac_f32_dpp v239, v247, v98 row_newbcast:15 row_mask:0xf bank_mask:0xf
	v_fmac_f32_dpp v238, v248, v106 row_newbcast:1 row_mask:0xf bank_mask:0xf
	s_nop 0
	v_fmac_f32_dpp v104, v248, v144 row_newbcast:12 row_mask:0xf bank_mask:0xf
	v_fmac_f32_dpp v105, v248, v136 row_newbcast:14 row_mask:0xf bank_mask:0xf
	s_nop 0
	v_fmac_f32_dpp v239, v248, v112 row_newbcast:3 row_mask:0xf bank_mask:0xf
	v_fmac_f32_dpp v238, v248, v118 row_newbcast:5 row_mask:0xf bank_mask:0xf
	v_fmac_f32_dpp v104, v249, v128 row_newbcast:0 row_mask:0xf bank_mask:0xf
	v_fmac_f32_dpp v105, v249, v120 row_newbcast:2 row_mask:0xf bank_mask:0xf
	s_waitcnt lgkmcnt(0)
; #define LAS __attribute__((address_space(3)))
; __device__ __forceinline__ void dn_prep_item(const Args& a, LAS unsigned char* lds, int item, int tid, int wave, int lane, int& cwh, int next_item) {
;     ...
;         { const LAS float* lrow = Lm + (lane & 15);
; #pragma unroll
;         for (int i = 1; i < 64; ++i) { float sa[4] = { x[i], 0.f, 0.f, 0.f };
;             int lr[4];
; #pragma unroll
;             for (int g = 0; g < (i + 15) / 16; ++g) lr[g] = __float_as_int(lrow[i * 68 + 16 * g]);
; #pragma unroll
;             for (int j = 0; j < i; ++j) { fmac_rowbcast_sel(sa[j & 3], lr[j >> 4], x[j], j); }
;             x[i] = (sa[0] + sa[1]) + (sa[2] + sa[3]); } }
	v_add_u32_e32 v254, 0xc000, v208
	ds_read2_b32 v[252:253], v254 offset0:120 offset1:136
	v_fmac_f32_dpp v100, v250, v71 row_newbcast:0 row_mask:0xf bank_mask:0xf
	v_fmac_f32_dpp v101, v250, v235 row_newbcast:2 row_mask:0xf bank_mask:0xf
	v_fmac_f32_dpp v239, v248, v126 row_newbcast:7 row_mask:0xf bank_mask:0xf
	v_fmac_f32_dpp v238, v248, v134 row_newbcast:9 row_mask:0xf bank_mask:0xf
	v_fmac_f32_dpp v104, v249, v110 row_newbcast:4 row_mask:0xf bank_mask:0xf
	s_nop 0
	v_fmac_f32_dpp v239, v248, v142 row_newbcast:11 row_mask:0xf bank_mask:0xf
	v_fmac_f32_dpp v238, v248, v140 row_newbcast:13 row_mask:0xf bank_mask:0xf
	v_fmac_f32_dpp v100, v250, v4 row_newbcast:4 row_mask:0xf bank_mask:0xf
	v_fmac_f32_dpp v101, v250, v8 row_newbcast:6 row_mask:0xf bank_mask:0xf
	s_nop 0
	v_fmac_f32_dpp v239, v248, v132 row_newbcast:15 row_mask:0xf bank_mask:0xf
	v_fmac_f32_dpp v238, v249, v124 row_newbcast:1 row_mask:0xf bank_mask:0xf
	v_fmac_f32_dpp v100, v250, v12 row_newbcast:8 row_mask:0xf bank_mask:0xf
	v_fmac_f32_dpp v101, v250, v18 row_newbcast:10 row_mask:0xf bank_mask:0xf
	s_nop 0
	v_fmac_f32_dpp v239, v249, v114 row_newbcast:3 row_mask:0xf bank_mask:0xf
	v_fmac_f32_dpp v100, v250, v22 row_newbcast:12 row_mask:0xf bank_mask:0xf
	v_fmac_f32_dpp v101, v250, v26 row_newbcast:14 row_mask:0xf bank_mask:0xf
	s_nop 0
	v_pk_add_f32 v[104:105], v[104:105], v[238:239]
	v_mul_f32_dpp v238, v250, v234 row_newbcast:1 row_mask:0xf bank_mask:0xf
	v_fmac_f32_dpp v238, v250, v6 row_newbcast:5 row_mask:0xf bank_mask:0xf
	v_mul_f32_dpp v239, v250, v2 row_newbcast:3 row_mask:0xf bank_mask:0xf
	v_fmac_f32_dpp v100, v251, v32 row_newbcast:0 row_mask:0xf bank_mask:0xf
	v_fmac_f32_dpp v101, v251, v38 row_newbcast:2 row_mask:0xf bank_mask:0xf
	v_pk_add_f32 v[104:105], v[104:105], v[104:105] op_sel:[0,1] op_sel_hi:[1,0]
	v_fmac_f32_dpp v238, v250, v14 row_newbcast:9 row_mask:0xf bank_mask:0xf
	v_fmac_f32_dpp v239, v250, v10 row_newbcast:7 row_mask:0xf bank_mask:0xf
	v_fmac_f32_dpp v100, v251, v42 row_newbcast:4 row_mask:0xf bank_mask:0xf
	v_fmac_f32_dpp v101, v251, v72 row_newbcast:6 row_mask:0xf bank_mask:0xf
	s_nop 0
	v_fmac_f32_dpp v238, v250, v24 row_newbcast:13 row_mask:0xf bank_mask:0xf
	v_fmac_f32_dpp v239, v250, v20 row_newbcast:11 row_mask:0xf bank_mask:0xf
	v_fmac_f32_dpp v100, v251, v78 row_newbcast:8 row_mask:0xf bank_mask:0xf
	v_fmac_f32_dpp v101, v251, v84 row_newbcast:10 row_mask:0xf bank_mask:0xf
	s_nop 0
	v_fmac_f32_dpp v238, v251, v34 row_newbcast:1 row_mask:0xf bank_mask:0xf
	v_fmac_f32_dpp v239, v250, v30 row_newbcast:15 row_mask:0xf bank_mask:0xf
	v_fmac_f32_dpp v100, v251, v90 row_newbcast:12 row_mask:0xf bank_mask:0xf
	v_fmac_f32_dpp v101, v251, v96 row_newbcast:14 row_mask:0xf bank_mask:0xf
	s_nop 0
	v_fmac_f32_dpp v238, v251, v46 row_newbcast:5 row_mask:0xf bank_mask:0xf
	v_fmac_f32_dpp v239, v251, v40 row_newbcast:3 row_mask:0xf bank_mask:0xf
	s_waitcnt lgkmcnt(0)
	v_add_u32_e32 v254, 0xc000, v208
	ds_read2_b32 v[242:243], v254 offset0:156 offset1:172
	v_fmac_f32_dpp v100, v252, v102 row_newbcast:0 row_mask:0xf bank_mask:0xf
	v_fmac_f32_dpp v101, v252, v108 row_newbcast:2 row_mask:0xf bank_mask:0xf
	v_fmac_f32_dpp v238, v251, v80 row_newbcast:9 row_mask:0xf bank_mask:0xf
	v_fmac_f32_dpp v239, v251, v74 row_newbcast:7 row_mask:0xf bank_mask:0xf
	s_nop 0
	v_fmac_f32_dpp v100, v252, v116 row_newbcast:4 row_mask:0xf bank_mask:0xf
	v_fmac_f32_dpp v101, v252, v122 row_newbcast:6 row_mask:0xf bank_mask:0xf
	v_fmac_f32_dpp v238, v251, v92 row_newbcast:13 row_mask:0xf bank_mask:0xf
	v_fmac_f32_dpp v239, v251, v86 row_newbcast:11 row_mask:0xf bank_mask:0xf
	s_nop 0
	v_fmac_f32_dpp v100, v252, v130 row_newbcast:8 row_mask:0xf bank_mask:0xf
	v_fmac_f32_dpp v101, v252, v138 row_newbcast:10 row_mask:0xf bank_mask:0xf
	v_fmac_f32_dpp v238, v252, v106 row_newbcast:1 row_mask:0xf bank_mask:0xf
	v_fmac_f32_dpp v239, v251, v98 row_newbcast:15 row_mask:0xf bank_mask:0xf
	s_nop 0
	v_fmac_f32_dpp v100, v252, v144 row_newbcast:12 row_mask:0xf bank_mask:0xf
	v_fmac_f32_dpp v101, v252, v136 row_newbcast:14 row_mask:0xf bank_mask:0xf
	s_nop 0
	v_fmac_f32_dpp v238, v252, v118 row_newbcast:5 row_mask:0xf bank_mask:0xf
	v_fmac_f32_dpp v239, v252, v112 row_newbcast:3 row_mask:0xf bank_mask:0xf
	v_fmac_f32_dpp v100, v253, v128 row_newbcast:0 row_mask:0xf bank_mask:0xf
	v_fmac_f32_dpp v101, v253, v120 row_newbcast:2 row_mask:0xf bank_mask:0xf
	s_waitcnt lgkmcnt(0)
; #define LAS __attribute__((address_space(3)))
; __device__ __forceinline__ void dn_prep_item(const Args& a, LAS unsigned char* lds, int item, int tid, int wave, int lane, int& cwh, int next_item) {
;     ...
;         { const LAS float* lrow = Lm + (lane & 15);
; #pragma unroll
;         for (int i = 1; i < 64; ++i) { float sa[4] = { x[i], 0.f, 0.f, 0.f };
;             int lr[4];
; #pragma unroll
;             for (int g = 0; g < (i + 15) / 16; ++g) lr[g] = __float_as_int(lrow[i * 68 + 16 * g]);
; #pragma unroll
;             for (int j = 0; j < i; ++j) { fmac_rowbcast_sel(sa[j & 3], lr[j >> 4], x[j], j); }
;             x[i] = (sa[0] + sa[1]) + (sa[2] + sa[3]); } }
	v_add_u32_e32 v254, 0xc000, v208
	ds_read2_b32 v[246:247], v254 offset0:188 offset1:204
	v_fmac_f32_dpp v94, v242, v71 row_newbcast:0 row_mask:0xf bank_mask:0xf
	v_fmac_f32_dpp v95, v242, v235 row_newbcast:2 row_mask:0xf bank_mask:0xf
	v_fmac_f32_dpp v238, v252, v134 row_newbcast:9 row_mask:0xf bank_mask:0xf
	v_fmac_f32_dpp v239, v252, v126 row_newbcast:7 row_mask:0xf bank_mask:0xf
	v_fmac_f32_dpp v100, v253, v110 row_newbcast:4 row_mask:0xf bank_mask:0xf
	s_nop 0
	v_fmac_f32_dpp v238, v252, v140 row_newbcast:13 row_mask:0xf bank_mask:0xf
	v_fmac_f32_dpp v239, v252, v142 row_newbcast:11 row_mask:0xf bank_mask:0xf
	v_fmac_f32_dpp v94, v242, v4 row_newbcast:4 row_mask:0xf bank_mask:0xf
	v_fmac_f32_dpp v95, v242, v8 row_newbcast:6 row_mask:0xf bank_mask:0xf
	s_nop 0
	v_fmac_f32_dpp v238, v253, v124 row_newbcast:1 row_mask:0xf bank_mask:0xf
	v_fmac_f32_dpp v239, v252, v132 row_newbcast:15 row_mask:0xf bank_mask:0xf
	v_fmac_f32_dpp v94, v242, v12 row_newbcast:8 row_mask:0xf bank_mask:0xf
	v_fmac_f32_dpp v95, v242, v18 row_newbcast:10 row_mask:0xf bank_mask:0xf
	s_nop 0
	v_fmac_f32_dpp v238, v253, v104 row_newbcast:5 row_mask:0xf bank_mask:0xf
	v_fmac_f32_dpp v239, v253, v114 row_newbcast:3 row_mask:0xf bank_mask:0xf
	v_fmac_f32_dpp v94, v242, v22 row_newbcast:12 row_mask:0xf bank_mask:0xf
	v_fmac_f32_dpp v95, v242, v26 row_newbcast:14 row_mask:0xf bank_mask:0xf
	s_nop 0
	v_pk_add_f32 v[100:101], v[100:101], v[238:239]
	v_mul_f32_dpp v238, v242, v234 row_newbcast:1 row_mask:0xf bank_mask:0xf
	v_fmac_f32_dpp v238, v242, v6 row_newbcast:5 row_mask:0xf bank_mask:0xf
	v_mul_f32_dpp v239, v242, v2 row_newbcast:3 row_mask:0xf bank_mask:0xf
	v_fmac_f32_dpp v94, v243, v32 row_newbcast:0 row_mask:0xf bank_mask:0xf
	v_fmac_f32_dpp v95, v243, v38 row_newbcast:2 row_mask:0xf bank_mask:0xf
	v_pk_add_f32 v[100:101], v[100:101], v[100:101] op_sel:[0,1] op_sel_hi:[1,0]
	v_fmac_f32_dpp v238, v242, v14 row_newbcast:9 row_mask:0xf bank_mask:0xf
	v_fmac_f32_dpp v239, v242, v10 row_newbcast:7 row_mask:0xf bank_mask:0xf
	v_fmac_f32_dpp v94, v243, v42 row_newbcast:4 row_mask:0xf bank_mask:0xf
	v_fmac_f32_dpp v95, v243, v72 row_newbcast:6 row_mask:0xf bank_mask:0xf
	s_nop 0
	v_fmac_f32_dpp v238, v242, v24 row_newbcast:13 row_mask:0xf bank_mask:0xf
	v_fmac_f32_dpp v239, v242, v20 row_newbcast:11 row_mask:0xf bank_mask:0xf
	v_fmac_f32_dpp v94, v243, v78 row_newbcast:8 row_mask:0xf bank_mask:0xf
	v_fmac_f32_dpp v95, v243, v84 row_newbcast:10 row_mask:0xf bank_mask:0xf
	s_nop 0
	v_fmac_f32_dpp v238, v243, v34 row_newbcast:1 row_mask:0xf bank_mask:0xf
	v_fmac_f32_dpp v239, v242, v30 row_newbcast:15 row_mask:0xf bank_mask:0xf
	v_fmac_f32_dpp v94, v243, v90 row_newbcast:12 row_mask:0xf bank_mask:0xf
	v_fmac_f32_dpp v95, v243, v96 row_newbcast:14 row_mask:0xf bank_mask:0xf
	s_nop 0
	v_fmac_f32_dpp v238, v243, v46 row_newbcast:5 row_mask:0xf bank_mask:0xf
	v_fmac_f32_dpp v239, v243, v40 row_newbcast:3 row_mask:0xf bank_mask:0xf
	s_waitcnt lgkmcnt(0)
	v_add_u32_e32 v254, 0xc000, v208
	ds_read2_b32 v[248:249], v254 offset0:224 offset1:240
	v_fmac_f32_dpp v94, v246, v102 row_newbcast:0 row_mask:0xf bank_mask:0xf
	v_fmac_f32_dpp v95, v246, v108 row_newbcast:2 row_mask:0xf bank_mask:0xf
	v_fmac_f32_dpp v238, v243, v80 row_newbcast:9 row_mask:0xf bank_mask:0xf
	v_fmac_f32_dpp v239, v243, v74 row_newbcast:7 row_mask:0xf bank_mask:0xf
	s_nop 0
	v_fmac_f32_dpp v94, v246, v116 row_newbcast:4 row_mask:0xf bank_mask:0xf
	v_fmac_f32_dpp v95, v246, v122 row_newbcast:6 row_mask:0xf bank_mask:0xf
	v_fmac_f32_dpp v238, v243, v92 row_newbcast:13 row_mask:0xf bank_mask:0xf
	v_fmac_f32_dpp v239, v243, v86 row_newbcast:11 row_mask:0xf bank_mask:0xf
	s_nop 0
	v_fmac_f32_dpp v94, v246, v130 row_newbcast:8 row_mask:0xf bank_mask:0xf
	v_fmac_f32_dpp v95, v246, v138 row_newbcast:10 row_mask:0xf bank_mask:0xf
	v_fmac_f32_dpp v238, v246, v106 row_newbcast:1 row_mask:0xf bank_mask:0xf
	v_fmac_f32_dpp v239, v243, v98 row_newbcast:15 row_mask:0xf bank_mask:0xf
	s_nop 0
	v_fmac_f32_dpp v94, v246, v144 row_newbcast:12 row_mask:0xf bank_mask:0xf
	v_fmac_f32_dpp v95, v246, v136 row_newbcast:14 row_mask:0xf bank_mask:0xf
	s_nop 0
	v_fmac_f32_dpp v238, v246, v118 row_newbcast:5 row_mask:0xf bank_mask:0xf
	v_fmac_f32_dpp v239, v246, v112 row_newbcast:3 row_mask:0xf bank_mask:0xf
	v_fmac_f32_dpp v94, v247, v128 row_newbcast:0 row_mask:0xf bank_mask:0xf
	v_fmac_f32_dpp v95, v247, v120 row_newbcast:2 row_mask:0xf bank_mask:0xf
	s_waitcnt lgkmcnt(0)
; #define LAS __attribute__((address_space(3)))
; __device__ __forceinline__ void dn_prep_item(const Args& a, LAS unsigned char* lds, int item, int tid, int wave, int lane, int& cwh, int next_item) {
;     ...
;         { const LAS float* lrow = Lm + (lane & 15);
; #pragma unroll
;         for (int i = 1; i < 64; ++i) { float sa[4] = { x[i], 0.f, 0.f, 0.f };
;             int lr[4];
; #pragma unroll
;             for (int g = 0; g < (i + 15) / 16; ++g) lr[g] = __float_as_int(lrow[i * 68 + 16 * g]);
; #pragma unroll
;             for (int j = 0; j < i; ++j) { fmac_rowbcast_sel(sa[j & 3], lr[j >> 4], x[j], j); }
;             x[i] = (sa[0] + sa[1]) + (sa[2] + sa[3]); } }
	v_add_u32_e32 v254, 0xc400, v208
	ds_read2_b32 v[250:251], v254 offset1:16
	v_fmac_f32_dpp v88, v248, v71 row_newbcast:0 row_mask:0xf bank_mask:0xf
	v_fmac_f32_dpp v89, v248, v235 row_newbcast:2 row_mask:0xf bank_mask:0xf
	v_fmac_f32_dpp v238, v246, v134 row_newbcast:9 row_mask:0xf bank_mask:0xf
	v_fmac_f32_dpp v239, v246, v126 row_newbcast:7 row_mask:0xf bank_mask:0xf
	v_fmac_f32_dpp v94, v247, v110 row_newbcast:4 row_mask:0xf bank_mask:0xf
	v_fmac_f32_dpp v95, v247, v100 row_newbcast:6 row_mask:0xf bank_mask:0xf
	s_nop 0
	v_fmac_f32_dpp v88, v248, v4 row_newbcast:4 row_mask:0xf bank_mask:0xf
	v_fmac_f32_dpp v89, v248, v8 row_newbcast:6 row_mask:0xf bank_mask:0xf
	v_fmac_f32_dpp v238, v246, v140 row_newbcast:13 row_mask:0xf bank_mask:0xf
	v_fmac_f32_dpp v239, v246, v142 row_newbcast:11 row_mask:0xf bank_mask:0xf
	v_add_u32_e32 v1, 0xc400, v208
	v_fmac_f32_dpp v238, v247, v124 row_newbcast:1 row_mask:0xf bank_mask:0xf
	v_fmac_f32_dpp v239, v246, v132 row_newbcast:15 row_mask:0xf bank_mask:0xf
	v_fmac_f32_dpp v88, v248, v12 row_newbcast:8 row_mask:0xf bank_mask:0xf
	v_fmac_f32_dpp v89, v248, v18 row_newbcast:10 row_mask:0xf bank_mask:0xf
	s_nop 0
	v_fmac_f32_dpp v238, v247, v104 row_newbcast:5 row_mask:0xf bank_mask:0xf
	v_fmac_f32_dpp v239, v247, v114 row_newbcast:3 row_mask:0xf bank_mask:0xf
	v_fmac_f32_dpp v88, v248, v22 row_newbcast:12 row_mask:0xf bank_mask:0xf
	v_fmac_f32_dpp v89, v248, v26 row_newbcast:14 row_mask:0xf bank_mask:0xf
	s_nop 0
	v_pk_add_f32 v[94:95], v[94:95], v[238:239]
	v_mul_f32_dpp v238, v248, v234 row_newbcast:1 row_mask:0xf bank_mask:0xf
	v_mul_f32_dpp v239, v248, v2 row_newbcast:3 row_mask:0xf bank_mask:0xf
	v_fmac_f32_dpp v238, v248, v6 row_newbcast:5 row_mask:0xf bank_mask:0xf
	v_fmac_f32_dpp v88, v249, v32 row_newbcast:0 row_mask:0xf bank_mask:0xf
	v_fmac_f32_dpp v89, v249, v38 row_newbcast:2 row_mask:0xf bank_mask:0xf
	v_pk_add_f32 v[94:95], v[94:95], v[94:95] op_sel:[0,1] op_sel_hi:[1,0]
	v_fmac_f32_dpp v239, v248, v10 row_newbcast:7 row_mask:0xf bank_mask:0xf
	v_fmac_f32_dpp v238, v248, v14 row_newbcast:9 row_mask:0xf bank_mask:0xf
	v_fmac_f32_dpp v88, v249, v42 row_newbcast:4 row_mask:0xf bank_mask:0xf
	v_fmac_f32_dpp v89, v249, v72 row_newbcast:6 row_mask:0xf bank_mask:0xf
	s_nop 0
	v_fmac_f32_dpp v239, v248, v20 row_newbcast:11 row_mask:0xf bank_mask:0xf
	v_fmac_f32_dpp v238, v248, v24 row_newbcast:13 row_mask:0xf bank_mask:0xf
	v_fmac_f32_dpp v88, v249, v78 row_newbcast:8 row_mask:0xf bank_mask:0xf
	v_fmac_f32_dpp v89, v249, v84 row_newbcast:10 row_mask:0xf bank_mask:0xf
	s_nop 0
	v_fmac_f32_dpp v239, v248, v30 row_newbcast:15 row_mask:0xf bank_mask:0xf
	v_fmac_f32_dpp v238, v249, v34 row_newbcast:1 row_mask:0xf bank_mask:0xf
	v_fmac_f32_dpp v88, v249, v90 row_newbcast:12 row_mask:0xf bank_mask:0xf
	v_fmac_f32_dpp v89, v249, v96 row_newbcast:14 row_mask:0xf bank_mask:0xf
	s_nop 0
	v_fmac_f32_dpp v239, v249, v40 row_newbcast:3 row_mask:0xf bank_mask:0xf
	v_fmac_f32_dpp v238, v249, v46 row_newbcast:5 row_mask:0xf bank_mask:0xf
	s_waitcnt lgkmcnt(0)
	v_add_u32_e32 v254, 0xc400, v208
	ds_read2_b32 v[252:253], v254 offset0:36 offset1:52
	v_fmac_f32_dpp v88, v250, v102 row_newbcast:0 row_mask:0xf bank_mask:0xf
	v_fmac_f32_dpp v89, v250, v108 row_newbcast:2 row_mask:0xf bank_mask:0xf
	v_fmac_f32_dpp v239, v249, v74 row_newbcast:7 row_mask:0xf bank_mask:0xf
	v_fmac_f32_dpp v238, v249, v80 row_newbcast:9 row_mask:0xf bank_mask:0xf
	s_nop 0
	v_fmac_f32_dpp v88, v250, v116 row_newbcast:4 row_mask:0xf bank_mask:0xf
	v_fmac_f32_dpp v89, v250, v122 row_newbcast:6 row_mask:0xf bank_mask:0xf
	v_fmac_f32_dpp v239, v249, v86 row_newbcast:11 row_mask:0xf bank_mask:0xf
	v_fmac_f32_dpp v238, v249, v92 row_newbcast:13 row_mask:0xf bank_mask:0xf
	s_nop 0
	v_fmac_f32_dpp v88, v250, v130 row_newbcast:8 row_mask:0xf bank_mask:0xf
	v_fmac_f32_dpp v89, v250, v138 row_newbcast:10 row_mask:0xf bank_mask:0xf
	v_fmac_f32_dpp v239, v249, v98 row_newbcast:15 row_mask:0xf bank_mask:0xf
	v_fmac_f32_dpp v238, v250, v106 row_newbcast:1 row_mask:0xf bank_mask:0xf
	s_nop 0
	v_fmac_f32_dpp v88, v250, v144 row_newbcast:12 row_mask:0xf bank_mask:0xf
	v_fmac_f32_dpp v89, v250, v136 row_newbcast:14 row_mask:0xf bank_mask:0xf
	s_nop 0
	v_fmac_f32_dpp v239, v250, v112 row_newbcast:3 row_mask:0xf bank_mask:0xf
	v_fmac_f32_dpp v238, v250, v118 row_newbcast:5 row_mask:0xf bank_mask:0xf
	v_fmac_f32_dpp v88, v251, v128 row_newbcast:0 row_mask:0xf bank_mask:0xf
	v_fmac_f32_dpp v89, v251, v120 row_newbcast:2 row_mask:0xf bank_mask:0xf
	s_waitcnt lgkmcnt(0)
; #define LAS __attribute__((address_space(3)))
; __device__ __forceinline__ void dn_prep_item(const Args& a, LAS unsigned char* lds, int item, int tid, int wave, int lane, int& cwh, int next_item) {
;     ...
;         { const LAS float* lrow = Lm + (lane & 15);
; #pragma unroll
;         for (int i = 1; i < 64; ++i) { float sa[4] = { x[i], 0.f, 0.f, 0.f };
;             int lr[4];
; #pragma unroll
;             for (int g = 0; g < (i + 15) / 16; ++g) lr[g] = __float_as_int(lrow[i * 68 + 16 * g]);
; #pragma unroll
;             for (int j = 0; j < i; ++j) { fmac_rowbcast_sel(sa[j & 3], lr[j >> 4], x[j], j); }
;             x[i] = (sa[0] + sa[1]) + (sa[2] + sa[3]); } }
	v_add_u32_e32 v254, 0xc400, v208
	ds_read2_b32 v[242:243], v254 offset0:68 offset1:84
	v_fmac_f32_dpp v82, v252, v71 row_newbcast:0 row_mask:0xf bank_mask:0xf
	v_fmac_f32_dpp v83, v252, v235 row_newbcast:2 row_mask:0xf bank_mask:0xf
	v_fmac_f32_dpp v239, v250, v126 row_newbcast:7 row_mask:0xf bank_mask:0xf
	v_fmac_f32_dpp v238, v250, v134 row_newbcast:9 row_mask:0xf bank_mask:0xf
	v_fmac_f32_dpp v88, v251, v110 row_newbcast:4 row_mask:0xf bank_mask:0xf
	v_fmac_f32_dpp v89, v251, v100 row_newbcast:6 row_mask:0xf bank_mask:0xf
	s_nop 0
	v_fmac_f32_dpp v82, v252, v4 row_newbcast:4 row_mask:0xf bank_mask:0xf
	v_fmac_f32_dpp v83, v252, v8 row_newbcast:6 row_mask:0xf bank_mask:0xf
	v_fmac_f32_dpp v239, v250, v142 row_newbcast:11 row_mask:0xf bank_mask:0xf
	v_fmac_f32_dpp v238, v250, v140 row_newbcast:13 row_mask:0xf bank_mask:0xf
	s_nop 0
	v_fmac_f32_dpp v239, v250, v132 row_newbcast:15 row_mask:0xf bank_mask:0xf
	v_fmac_f32_dpp v238, v251, v124 row_newbcast:1 row_mask:0xf bank_mask:0xf
	v_fmac_f32_dpp v82, v252, v12 row_newbcast:8 row_mask:0xf bank_mask:0xf
	v_fmac_f32_dpp v83, v252, v18 row_newbcast:10 row_mask:0xf bank_mask:0xf
	s_nop 0
	v_fmac_f32_dpp v239, v251, v114 row_newbcast:3 row_mask:0xf bank_mask:0xf
	v_fmac_f32_dpp v238, v251, v104 row_newbcast:5 row_mask:0xf bank_mask:0xf
	v_fmac_f32_dpp v82, v252, v22 row_newbcast:12 row_mask:0xf bank_mask:0xf
	v_fmac_f32_dpp v83, v252, v26 row_newbcast:14 row_mask:0xf bank_mask:0xf
	s_nop 0
	v_fmac_f32_dpp v239, v251, v94 row_newbcast:7 row_mask:0xf bank_mask:0xf
	v_fmac_f32_dpp v82, v253, v32 row_newbcast:0 row_mask:0xf bank_mask:0xf
	v_fmac_f32_dpp v83, v253, v38 row_newbcast:2 row_mask:0xf bank_mask:0xf
	s_nop 0
	v_pk_add_f32 v[88:89], v[88:89], v[238:239]
	v_mul_f32_dpp v238, v252, v234 row_newbcast:1 row_mask:0xf bank_mask:0xf
	v_mul_f32_dpp v239, v252, v2 row_newbcast:3 row_mask:0xf bank_mask:0xf
	v_fmac_f32_dpp v238, v252, v6 row_newbcast:5 row_mask:0xf bank_mask:0xf
	v_fmac_f32_dpp v82, v253, v42 row_newbcast:4 row_mask:0xf bank_mask:0xf
	v_fmac_f32_dpp v83, v253, v72 row_newbcast:6 row_mask:0xf bank_mask:0xf
	v_pk_add_f32 v[88:89], v[88:89], v[88:89] op_sel:[0,1] op_sel_hi:[1,0]
	v_fmac_f32_dpp v239, v252, v10 row_newbcast:7 row_mask:0xf bank_mask:0xf
	v_fmac_f32_dpp v238, v252, v14 row_newbcast:9 row_mask:0xf bank_mask:0xf
	v_fmac_f32_dpp v82, v253, v78 row_newbcast:8 row_mask:0xf bank_mask:0xf
	v_fmac_f32_dpp v83, v253, v84 row_newbcast:10 row_mask:0xf bank_mask:0xf
	s_nop 0
	v_fmac_f32_dpp v239, v252, v20 row_newbcast:11 row_mask:0xf bank_mask:0xf
	v_fmac_f32_dpp v238, v252, v24 row_newbcast:13 row_mask:0xf bank_mask:0xf
	v_fmac_f32_dpp v82, v253, v90 row_newbcast:12 row_mask:0xf bank_mask:0xf
	v_fmac_f32_dpp v83, v253, v96 row_newbcast:14 row_mask:0xf bank_mask:0xf
	s_nop 0
	v_fmac_f32_dpp v239, v252, v30 row_newbcast:15 row_mask:0xf bank_mask:0xf
	v_fmac_f32_dpp v238, v253, v34 row_newbcast:1 row_mask:0xf bank_mask:0xf
	s_waitcnt lgkmcnt(0)
	v_add_u32_e32 v254, 0xc400, v208
	ds_read2_b32 v[246:247], v254 offset0:104 offset1:120
	v_fmac_f32_dpp v82, v242, v102 row_newbcast:0 row_mask:0xf bank_mask:0xf
	v_fmac_f32_dpp v83, v242, v108 row_newbcast:2 row_mask:0xf bank_mask:0xf
	v_fmac_f32_dpp v239, v253, v40 row_newbcast:3 row_mask:0xf bank_mask:0xf
	v_fmac_f32_dpp v238, v253, v46 row_newbcast:5 row_mask:0xf bank_mask:0xf
	s_nop 0
	v_fmac_f32_dpp v82, v242, v116 row_newbcast:4 row_mask:0xf bank_mask:0xf
	v_fmac_f32_dpp v83, v242, v122 row_newbcast:6 row_mask:0xf bank_mask:0xf
	v_fmac_f32_dpp v239, v253, v74 row_newbcast:7 row_mask:0xf bank_mask:0xf
	v_fmac_f32_dpp v238, v253, v80 row_newbcast:9 row_mask:0xf bank_mask:0xf
	s_nop 0
	v_fmac_f32_dpp v82, v242, v130 row_newbcast:8 row_mask:0xf bank_mask:0xf
	v_fmac_f32_dpp v83, v242, v138 row_newbcast:10 row_mask:0xf bank_mask:0xf
	v_fmac_f32_dpp v239, v253, v86 row_newbcast:11 row_mask:0xf bank_mask:0xf
	v_fmac_f32_dpp v238, v253, v92 row_newbcast:13 row_mask:0xf bank_mask:0xf
	s_nop 0
	v_fmac_f32_dpp v82, v242, v144 row_newbcast:12 row_mask:0xf bank_mask:0xf
	v_fmac_f32_dpp v83, v242, v136 row_newbcast:14 row_mask:0xf bank_mask:0xf
	v_fmac_f32_dpp v239, v253, v98 row_newbcast:15 row_mask:0xf bank_mask:0xf
	v_fmac_f32_dpp v238, v242, v106 row_newbcast:1 row_mask:0xf bank_mask:0xf
	s_nop 0
	v_fmac_f32_dpp v82, v243, v128 row_newbcast:0 row_mask:0xf bank_mask:0xf
	v_fmac_f32_dpp v83, v243, v120 row_newbcast:2 row_mask:0xf bank_mask:0xf
	s_nop 0
	v_fmac_f32_dpp v239, v242, v112 row_newbcast:3 row_mask:0xf bank_mask:0xf
	v_fmac_f32_dpp v238, v242, v118 row_newbcast:5 row_mask:0xf bank_mask:0xf
	v_fmac_f32_dpp v82, v243, v110 row_newbcast:4 row_mask:0xf bank_mask:0xf
	v_fmac_f32_dpp v83, v243, v100 row_newbcast:6 row_mask:0xf bank_mask:0xf
	s_waitcnt lgkmcnt(0)
; #define LAS __attribute__((address_space(3)))
; __device__ __forceinline__ void dn_prep_item(const Args& a, LAS unsigned char* lds, int item, int tid, int wave, int lane, int& cwh, int next_item) {
;     ...
;         { const LAS float* lrow = Lm + (lane & 15);
; #pragma unroll
;         for (int i = 1; i < 64; ++i) { float sa[4] = { x[i], 0.f, 0.f, 0.f };
;             int lr[4];
; #pragma unroll
;             for (int g = 0; g < (i + 15) / 16; ++g) lr[g] = __float_as_int(lrow[i * 68 + 16 * g]);
; #pragma unroll
;             for (int j = 0; j < i; ++j) { fmac_rowbcast_sel(sa[j & 3], lr[j >> 4], x[j], j); }
;             x[i] = (sa[0] + sa[1]) + (sa[2] + sa[3]); } }
	v_add_u32_e32 v254, 0xc400, v208
	ds_read2_b32 v[248:249], v254 offset0:136 offset1:152
	v_fmac_f32_dpp v76, v246, v71 row_newbcast:0 row_mask:0xf bank_mask:0xf
	v_fmac_f32_dpp v77, v246, v235 row_newbcast:2 row_mask:0xf bank_mask:0xf
	v_fmac_f32_dpp v239, v242, v126 row_newbcast:7 row_mask:0xf bank_mask:0xf
	v_fmac_f32_dpp v238, v242, v134 row_newbcast:9 row_mask:0xf bank_mask:0xf
	v_fmac_f32_dpp v82, v243, v88 row_newbcast:8 row_mask:0xf bank_mask:0xf
	s_nop 0
	v_fmac_f32_dpp v239, v242, v142 row_newbcast:11 row_mask:0xf bank_mask:0xf
	v_fmac_f32_dpp v238, v242, v140 row_newbcast:13 row_mask:0xf bank_mask:0xf
	v_fmac_f32_dpp v76, v246, v4 row_newbcast:4 row_mask:0xf bank_mask:0xf
	v_fmac_f32_dpp v77, v246, v8 row_newbcast:6 row_mask:0xf bank_mask:0xf
	s_nop 0
	v_fmac_f32_dpp v239, v242, v132 row_newbcast:15 row_mask:0xf bank_mask:0xf
	v_fmac_f32_dpp v238, v243, v124 row_newbcast:1 row_mask:0xf bank_mask:0xf
	v_fmac_f32_dpp v76, v246, v12 row_newbcast:8 row_mask:0xf bank_mask:0xf
	v_fmac_f32_dpp v77, v246, v18 row_newbcast:10 row_mask:0xf bank_mask:0xf
	s_nop 0
	v_fmac_f32_dpp v239, v243, v114 row_newbcast:3 row_mask:0xf bank_mask:0xf
	v_fmac_f32_dpp v238, v243, v104 row_newbcast:5 row_mask:0xf bank_mask:0xf
	v_fmac_f32_dpp v76, v246, v22 row_newbcast:12 row_mask:0xf bank_mask:0xf
	v_fmac_f32_dpp v77, v246, v26 row_newbcast:14 row_mask:0xf bank_mask:0xf
	s_nop 0
	v_fmac_f32_dpp v239, v243, v94 row_newbcast:7 row_mask:0xf bank_mask:0xf
	v_fmac_f32_dpp v76, v247, v32 row_newbcast:0 row_mask:0xf bank_mask:0xf
	v_fmac_f32_dpp v77, v247, v38 row_newbcast:2 row_mask:0xf bank_mask:0xf
	s_nop 0
	v_pk_add_f32 v[82:83], v[82:83], v[238:239]
	v_mul_f32_dpp v238, v246, v234 row_newbcast:1 row_mask:0xf bank_mask:0xf
	v_fmac_f32_dpp v238, v246, v6 row_newbcast:5 row_mask:0xf bank_mask:0xf
	v_mul_f32_dpp v239, v246, v2 row_newbcast:3 row_mask:0xf bank_mask:0xf
	v_fmac_f32_dpp v76, v247, v42 row_newbcast:4 row_mask:0xf bank_mask:0xf
	v_fmac_f32_dpp v77, v247, v72 row_newbcast:6 row_mask:0xf bank_mask:0xf
	v_pk_add_f32 v[82:83], v[82:83], v[82:83] op_sel:[0,1] op_sel_hi:[1,0]
	v_fmac_f32_dpp v238, v246, v14 row_newbcast:9 row_mask:0xf bank_mask:0xf
	v_fmac_f32_dpp v239, v246, v10 row_newbcast:7 row_mask:0xf bank_mask:0xf
	v_fmac_f32_dpp v76, v247, v78 row_newbcast:8 row_mask:0xf bank_mask:0xf
	v_fmac_f32_dpp v77, v247, v84 row_newbcast:10 row_mask:0xf bank_mask:0xf
	s_nop 0
	v_fmac_f32_dpp v238, v246, v24 row_newbcast:13 row_mask:0xf bank_mask:0xf
	v_fmac_f32_dpp v239, v246, v20 row_newbcast:11 row_mask:0xf bank_mask:0xf
	v_fmac_f32_dpp v76, v247, v90 row_newbcast:12 row_mask:0xf bank_mask:0xf
	v_fmac_f32_dpp v77, v247, v96 row_newbcast:14 row_mask:0xf bank_mask:0xf
	s_nop 0
	v_fmac_f32_dpp v238, v247, v34 row_newbcast:1 row_mask:0xf bank_mask:0xf
	v_fmac_f32_dpp v239, v246, v30 row_newbcast:15 row_mask:0xf bank_mask:0xf
	s_waitcnt lgkmcnt(0)
	v_add_u32_e32 v254, 0xc400, v208
	ds_read2_b32 v[250:251], v254 offset0:172 offset1:188
	v_fmac_f32_dpp v76, v248, v102 row_newbcast:0 row_mask:0xf bank_mask:0xf
	v_fmac_f32_dpp v77, v248, v108 row_newbcast:2 row_mask:0xf bank_mask:0xf
	v_fmac_f32_dpp v238, v247, v46 row_newbcast:5 row_mask:0xf bank_mask:0xf
	v_fmac_f32_dpp v239, v247, v40 row_newbcast:3 row_mask:0xf bank_mask:0xf
	s_nop 0
	v_fmac_f32_dpp v76, v248, v116 row_newbcast:4 row_mask:0xf bank_mask:0xf
	v_fmac_f32_dpp v77, v248, v122 row_newbcast:6 row_mask:0xf bank_mask:0xf
	v_fmac_f32_dpp v238, v247, v80 row_newbcast:9 row_mask:0xf bank_mask:0xf
	v_fmac_f32_dpp v239, v247, v74 row_newbcast:7 row_mask:0xf bank_mask:0xf
	s_nop 0
	v_fmac_f32_dpp v76, v248, v130 row_newbcast:8 row_mask:0xf bank_mask:0xf
	v_fmac_f32_dpp v77, v248, v138 row_newbcast:10 row_mask:0xf bank_mask:0xf
	v_fmac_f32_dpp v238, v247, v92 row_newbcast:13 row_mask:0xf bank_mask:0xf
	v_fmac_f32_dpp v239, v247, v86 row_newbcast:11 row_mask:0xf bank_mask:0xf
	s_nop 0
	v_fmac_f32_dpp v76, v248, v144 row_newbcast:12 row_mask:0xf bank_mask:0xf
	v_fmac_f32_dpp v77, v248, v136 row_newbcast:14 row_mask:0xf bank_mask:0xf
	v_fmac_f32_dpp v238, v248, v106 row_newbcast:1 row_mask:0xf bank_mask:0xf
	v_fmac_f32_dpp v239, v247, v98 row_newbcast:15 row_mask:0xf bank_mask:0xf
	s_nop 0
	v_fmac_f32_dpp v76, v249, v128 row_newbcast:0 row_mask:0xf bank_mask:0xf
	v_fmac_f32_dpp v77, v249, v120 row_newbcast:2 row_mask:0xf bank_mask:0xf
	s_nop 0
	v_fmac_f32_dpp v238, v248, v118 row_newbcast:5 row_mask:0xf bank_mask:0xf
	v_fmac_f32_dpp v239, v248, v112 row_newbcast:3 row_mask:0xf bank_mask:0xf
	v_fmac_f32_dpp v76, v249, v110 row_newbcast:4 row_mask:0xf bank_mask:0xf
	v_fmac_f32_dpp v77, v249, v100 row_newbcast:6 row_mask:0xf bank_mask:0xf
	s_waitcnt lgkmcnt(0)
; #define LAS __attribute__((address_space(3)))
; __device__ __forceinline__ void dn_prep_item(const Args& a, LAS unsigned char* lds, int item, int tid, int wave, int lane, int& cwh, int next_item) {
;     ...
;         { const LAS float* lrow = Lm + (lane & 15);
; #pragma unroll
;         for (int i = 1; i < 64; ++i) { float sa[4] = { x[i], 0.f, 0.f, 0.f };
;             int lr[4];
; #pragma unroll
;             for (int g = 0; g < (i + 15) / 16; ++g) lr[g] = __float_as_int(lrow[i * 68 + 16 * g]);
; #pragma unroll
;             for (int j = 0; j < i; ++j) { fmac_rowbcast_sel(sa[j & 3], lr[j >> 4], x[j], j); }
;             x[i] = (sa[0] + sa[1]) + (sa[2] + sa[3]); } }
	v_add_u32_e32 v254, 0xc400, v208
	ds_read2_b32 v[252:253], v254 offset0:204 offset1:220
	v_fmac_f32_dpp v44, v250, v71 row_newbcast:0 row_mask:0xf bank_mask:0xf
	v_fmac_f32_dpp v45, v250, v235 row_newbcast:2 row_mask:0xf bank_mask:0xf
	v_fmac_f32_dpp v238, v248, v134 row_newbcast:9 row_mask:0xf bank_mask:0xf
	v_fmac_f32_dpp v239, v248, v126 row_newbcast:7 row_mask:0xf bank_mask:0xf
	v_fmac_f32_dpp v76, v249, v88 row_newbcast:8 row_mask:0xf bank_mask:0xf
	s_nop 0
	v_fmac_f32_dpp v238, v248, v140 row_newbcast:13 row_mask:0xf bank_mask:0xf
	v_fmac_f32_dpp v239, v248, v142 row_newbcast:11 row_mask:0xf bank_mask:0xf
	v_fmac_f32_dpp v44, v250, v4 row_newbcast:4 row_mask:0xf bank_mask:0xf
	v_fmac_f32_dpp v45, v250, v8 row_newbcast:6 row_mask:0xf bank_mask:0xf
	s_nop 0
	v_fmac_f32_dpp v238, v249, v124 row_newbcast:1 row_mask:0xf bank_mask:0xf
	v_fmac_f32_dpp v239, v248, v132 row_newbcast:15 row_mask:0xf bank_mask:0xf
	v_fmac_f32_dpp v44, v250, v12 row_newbcast:8 row_mask:0xf bank_mask:0xf
	v_fmac_f32_dpp v45, v250, v18 row_newbcast:10 row_mask:0xf bank_mask:0xf
	s_nop 0
	v_fmac_f32_dpp v238, v249, v104 row_newbcast:5 row_mask:0xf bank_mask:0xf
	v_fmac_f32_dpp v239, v249, v114 row_newbcast:3 row_mask:0xf bank_mask:0xf
	v_fmac_f32_dpp v44, v250, v22 row_newbcast:12 row_mask:0xf bank_mask:0xf
	v_fmac_f32_dpp v45, v250, v26 row_newbcast:14 row_mask:0xf bank_mask:0xf
	s_nop 0
	v_fmac_f32_dpp v238, v249, v82 row_newbcast:9 row_mask:0xf bank_mask:0xf
	v_fmac_f32_dpp v239, v249, v94 row_newbcast:7 row_mask:0xf bank_mask:0xf
	v_fmac_f32_dpp v44, v251, v32 row_newbcast:0 row_mask:0xf bank_mask:0xf
	v_fmac_f32_dpp v45, v251, v38 row_newbcast:2 row_mask:0xf bank_mask:0xf
	s_nop 0
	v_pk_add_f32 v[76:77], v[76:77], v[238:239]
	v_mul_f32_dpp v238, v250, v234 row_newbcast:1 row_mask:0xf bank_mask:0xf
	v_mul_f32_dpp v239, v250, v2 row_newbcast:3 row_mask:0xf bank_mask:0xf
	v_fmac_f32_dpp v238, v250, v6 row_newbcast:5 row_mask:0xf bank_mask:0xf
	v_fmac_f32_dpp v44, v251, v42 row_newbcast:4 row_mask:0xf bank_mask:0xf
	v_fmac_f32_dpp v45, v251, v72 row_newbcast:6 row_mask:0xf bank_mask:0xf
	v_pk_add_f32 v[76:77], v[76:77], v[76:77] op_sel:[0,1] op_sel_hi:[1,0]
	v_fmac_f32_dpp v239, v250, v10 row_newbcast:7 row_mask:0xf bank_mask:0xf
	v_fmac_f32_dpp v238, v250, v14 row_newbcast:9 row_mask:0xf bank_mask:0xf
	v_fmac_f32_dpp v44, v251, v78 row_newbcast:8 row_mask:0xf bank_mask:0xf
	v_fmac_f32_dpp v45, v251, v84 row_newbcast:10 row_mask:0xf bank_mask:0xf
	v_add_u32_e32 v1, 0xc600, v208
	v_fmac_f32_dpp v239, v250, v20 row_newbcast:11 row_mask:0xf bank_mask:0xf
	v_fmac_f32_dpp v238, v250, v24 row_newbcast:13 row_mask:0xf bank_mask:0xf
	v_fmac_f32_dpp v44, v251, v90 row_newbcast:12 row_mask:0xf bank_mask:0xf
	v_fmac_f32_dpp v45, v251, v96 row_newbcast:14 row_mask:0xf bank_mask:0xf
	s_nop 0
	v_fmac_f32_dpp v239, v250, v30 row_newbcast:15 row_mask:0xf bank_mask:0xf
	v_fmac_f32_dpp v238, v251, v34 row_newbcast:1 row_mask:0xf bank_mask:0xf
	s_waitcnt lgkmcnt(0)
	v_add_u32_e32 v254, 0xc600, v208
	ds_read2_b32 v[242:243], v254 offset0:112 offset1:128
	v_fmac_f32_dpp v44, v252, v102 row_newbcast:0 row_mask:0xf bank_mask:0xf
	v_fmac_f32_dpp v45, v252, v108 row_newbcast:2 row_mask:0xf bank_mask:0xf
	v_fmac_f32_dpp v239, v251, v40 row_newbcast:3 row_mask:0xf bank_mask:0xf
	v_fmac_f32_dpp v238, v251, v46 row_newbcast:5 row_mask:0xf bank_mask:0xf
	s_nop 0
	v_fmac_f32_dpp v44, v252, v116 row_newbcast:4 row_mask:0xf bank_mask:0xf
	v_fmac_f32_dpp v45, v252, v122 row_newbcast:6 row_mask:0xf bank_mask:0xf
	v_fmac_f32_dpp v239, v251, v74 row_newbcast:7 row_mask:0xf bank_mask:0xf
	v_fmac_f32_dpp v238, v251, v80 row_newbcast:9 row_mask:0xf bank_mask:0xf
	s_nop 0
	v_fmac_f32_dpp v44, v252, v130 row_newbcast:8 row_mask:0xf bank_mask:0xf
	v_fmac_f32_dpp v45, v252, v138 row_newbcast:10 row_mask:0xf bank_mask:0xf
	v_fmac_f32_dpp v239, v251, v86 row_newbcast:11 row_mask:0xf bank_mask:0xf
	v_fmac_f32_dpp v238, v251, v92 row_newbcast:13 row_mask:0xf bank_mask:0xf
	s_nop 0
	v_fmac_f32_dpp v44, v252, v144 row_newbcast:12 row_mask:0xf bank_mask:0xf
	v_fmac_f32_dpp v45, v252, v136 row_newbcast:14 row_mask:0xf bank_mask:0xf
	v_fmac_f32_dpp v239, v251, v98 row_newbcast:15 row_mask:0xf bank_mask:0xf
	v_fmac_f32_dpp v238, v252, v106 row_newbcast:1 row_mask:0xf bank_mask:0xf
	s_nop 0
	v_fmac_f32_dpp v44, v253, v128 row_newbcast:0 row_mask:0xf bank_mask:0xf
	v_fmac_f32_dpp v45, v253, v120 row_newbcast:2 row_mask:0xf bank_mask:0xf
	s_nop 0
	v_fmac_f32_dpp v239, v252, v112 row_newbcast:3 row_mask:0xf bank_mask:0xf
	v_fmac_f32_dpp v238, v252, v118 row_newbcast:5 row_mask:0xf bank_mask:0xf
	v_fmac_f32_dpp v44, v253, v110 row_newbcast:4 row_mask:0xf bank_mask:0xf
	v_fmac_f32_dpp v45, v253, v100 row_newbcast:6 row_mask:0xf bank_mask:0xf
	s_waitcnt lgkmcnt(0)
	v_add_u32_e32 v254, 0xc800, v208
	ds_read2_b32 v[246:247], v254 offset0:52 offset1:68
	v_fmac_f32_dpp v36, v242, v71 row_newbcast:0 row_mask:0xf bank_mask:0xf
	v_fmac_f32_dpp v37, v242, v235 row_newbcast:2 row_mask:0xf bank_mask:0xf
	v_fmac_f32_dpp v239, v252, v126 row_newbcast:7 row_mask:0xf bank_mask:0xf
	v_fmac_f32_dpp v238, v252, v134 row_newbcast:9 row_mask:0xf bank_mask:0xf
	v_fmac_f32_dpp v44, v253, v88 row_newbcast:8 row_mask:0xf bank_mask:0xf
	v_fmac_f32_dpp v45, v253, v76 row_newbcast:10 row_mask:0xf bank_mask:0xf
	s_nop 0
	v_fmac_f32_dpp v36, v242, v4 row_newbcast:4 row_mask:0xf bank_mask:0xf
	v_fmac_f32_dpp v37, v242, v8 row_newbcast:6 row_mask:0xf bank_mask:0xf
	v_fmac_f32_dpp v239, v252, v142 row_newbcast:11 row_mask:0xf bank_mask:0xf
	v_fmac_f32_dpp v238, v252, v140 row_newbcast:13 row_mask:0xf bank_mask:0xf
	v_add_u32_e32 v1, 0xc800, v208
	v_fmac_f32_dpp v239, v252, v132 row_newbcast:15 row_mask:0xf bank_mask:0xf
	v_fmac_f32_dpp v238, v253, v124 row_newbcast:1 row_mask:0xf bank_mask:0xf
	v_fmac_f32_dpp v36, v242, v12 row_newbcast:8 row_mask:0xf bank_mask:0xf
	v_fmac_f32_dpp v37, v242, v18 row_newbcast:10 row_mask:0xf bank_mask:0xf
	s_nop 0
	v_fmac_f32_dpp v239, v253, v114 row_newbcast:3 row_mask:0xf bank_mask:0xf
	v_fmac_f32_dpp v238, v253, v104 row_newbcast:5 row_mask:0xf bank_mask:0xf
	v_fmac_f32_dpp v36, v242, v22 row_newbcast:12 row_mask:0xf bank_mask:0xf
	v_fmac_f32_dpp v37, v242, v26 row_newbcast:14 row_mask:0xf bank_mask:0xf
	s_waitcnt lgkmcnt(0)
; #define LAS __attribute__((address_space(3)))
; __device__ __forceinline__ void dn_prep_item(const Args& a, LAS unsigned char* lds, int item, int tid, int wave, int lane, int& cwh, int next_item) {
;     ...
;         { const LAS float* lrow = Lm + (lane & 15);
; #pragma unroll
;         for (int i = 1; i < 64; ++i) { float sa[4] = { x[i], 0.f, 0.f, 0.f };
;             int lr[4];
; #pragma unroll
;             for (int g = 0; g < (i + 15) / 16; ++g) lr[g] = __float_as_int(lrow[i * 68 + 16 * g]);
; #pragma unroll
;             for (int j = 0; j < i; ++j) { fmac_rowbcast_sel(sa[j & 3], lr[j >> 4], x[j], j); }
;             x[i] = (sa[0] + sa[1]) + (sa[2] + sa[3]); } }
	v_add_u32_e32 v254, 0xc800, v208
	ds_read2_b32 v[248:249], v254 offset0:16 offset1:32
	v_fmac_f32_dpp v28, v246, v71 row_newbcast:0 row_mask:0xf bank_mask:0xf
	v_fmac_f32_dpp v29, v246, v235 row_newbcast:2 row_mask:0xf bank_mask:0xf
	v_fmac_f32_dpp v239, v253, v94 row_newbcast:7 row_mask:0xf bank_mask:0xf
	v_fmac_f32_dpp v238, v253, v82 row_newbcast:9 row_mask:0xf bank_mask:0xf
	v_fmac_f32_dpp v36, v243, v32 row_newbcast:0 row_mask:0xf bank_mask:0xf
	v_fmac_f32_dpp v37, v243, v38 row_newbcast:2 row_mask:0xf bank_mask:0xf
	s_nop 0
	v_pk_add_f32 v[44:45], v[44:45], v[238:239]
	v_mul_f32_dpp v238, v242, v234 row_newbcast:1 row_mask:0xf bank_mask:0xf
	v_mul_f32_dpp v239, v242, v2 row_newbcast:3 row_mask:0xf bank_mask:0xf
	v_fmac_f32_dpp v36, v243, v42 row_newbcast:4 row_mask:0xf bank_mask:0xf
	v_fmac_f32_dpp v37, v243, v72 row_newbcast:6 row_mask:0xf bank_mask:0xf
	v_pk_add_f32 v[44:45], v[44:45], v[44:45] op_sel:[0,1] op_sel_hi:[1,0]
	v_fmac_f32_dpp v238, v242, v6 row_newbcast:5 row_mask:0xf bank_mask:0xf
	v_fmac_f32_dpp v239, v242, v10 row_newbcast:7 row_mask:0xf bank_mask:0xf
	v_fmac_f32_dpp v36, v243, v78 row_newbcast:8 row_mask:0xf bank_mask:0xf
	v_fmac_f32_dpp v37, v243, v84 row_newbcast:10 row_mask:0xf bank_mask:0xf
	v_fmac_f32_dpp v28, v246, v4 row_newbcast:4 row_mask:0xf bank_mask:0xf
	v_fmac_f32_dpp v29, v246, v8 row_newbcast:6 row_mask:0xf bank_mask:0xf
	s_nop 0
	v_fmac_f32_dpp v238, v242, v14 row_newbcast:9 row_mask:0xf bank_mask:0xf
	v_fmac_f32_dpp v239, v242, v20 row_newbcast:11 row_mask:0xf bank_mask:0xf
	v_fmac_f32_dpp v36, v243, v90 row_newbcast:12 row_mask:0xf bank_mask:0xf
	v_fmac_f32_dpp v37, v243, v96 row_newbcast:14 row_mask:0xf bank_mask:0xf
	v_fmac_f32_dpp v28, v246, v12 row_newbcast:8 row_mask:0xf bank_mask:0xf
	v_fmac_f32_dpp v29, v246, v18 row_newbcast:10 row_mask:0xf bank_mask:0xf
	s_nop 0
	v_fmac_f32_dpp v238, v242, v24 row_newbcast:13 row_mask:0xf bank_mask:0xf
	v_fmac_f32_dpp v239, v242, v30 row_newbcast:15 row_mask:0xf bank_mask:0xf
	s_waitcnt lgkmcnt(0)
	v_add_u32_e32 v254, 0xc800, v208
	ds_read2_b32 v[250:251], v254 offset0:84 offset1:100
	v_fmac_f32_dpp v36, v248, v102 row_newbcast:0 row_mask:0xf bank_mask:0xf
	v_fmac_f32_dpp v37, v248, v108 row_newbcast:2 row_mask:0xf bank_mask:0xf
	v_fmac_f32_dpp v28, v246, v22 row_newbcast:12 row_mask:0xf bank_mask:0xf
	v_fmac_f32_dpp v29, v246, v26 row_newbcast:14 row_mask:0xf bank_mask:0xf
	v_fmac_f32_dpp v238, v243, v34 row_newbcast:1 row_mask:0xf bank_mask:0xf
	v_fmac_f32_dpp v239, v243, v40 row_newbcast:3 row_mask:0xf bank_mask:0xf
	s_nop 0
	v_fmac_f32_dpp v36, v248, v116 row_newbcast:4 row_mask:0xf bank_mask:0xf
	v_fmac_f32_dpp v37, v248, v122 row_newbcast:6 row_mask:0xf bank_mask:0xf
	v_fmac_f32_dpp v28, v247, v32 row_newbcast:0 row_mask:0xf bank_mask:0xf
	v_fmac_f32_dpp v29, v247, v38 row_newbcast:2 row_mask:0xf bank_mask:0xf
	v_fmac_f32_dpp v238, v243, v46 row_newbcast:5 row_mask:0xf bank_mask:0xf
	v_fmac_f32_dpp v239, v243, v74 row_newbcast:7 row_mask:0xf bank_mask:0xf
	s_nop 0
	v_fmac_f32_dpp v36, v248, v130 row_newbcast:8 row_mask:0xf bank_mask:0xf
	v_fmac_f32_dpp v37, v248, v138 row_newbcast:10 row_mask:0xf bank_mask:0xf
	v_fmac_f32_dpp v28, v247, v42 row_newbcast:4 row_mask:0xf bank_mask:0xf
	v_fmac_f32_dpp v29, v247, v72 row_newbcast:6 row_mask:0xf bank_mask:0xf
	v_fmac_f32_dpp v238, v243, v80 row_newbcast:9 row_mask:0xf bank_mask:0xf
	v_fmac_f32_dpp v239, v243, v86 row_newbcast:11 row_mask:0xf bank_mask:0xf
	s_nop 0
	v_fmac_f32_dpp v36, v248, v144 row_newbcast:12 row_mask:0xf bank_mask:0xf
	v_fmac_f32_dpp v37, v248, v136 row_newbcast:14 row_mask:0xf bank_mask:0xf
	v_fmac_f32_dpp v28, v247, v78 row_newbcast:8 row_mask:0xf bank_mask:0xf
	v_fmac_f32_dpp v29, v247, v84 row_newbcast:10 row_mask:0xf bank_mask:0xf
	v_fmac_f32_dpp v238, v243, v92 row_newbcast:13 row_mask:0xf bank_mask:0xf
	v_fmac_f32_dpp v239, v243, v98 row_newbcast:15 row_mask:0xf bank_mask:0xf
	s_nop 0
	v_fmac_f32_dpp v36, v249, v128 row_newbcast:0 row_mask:0xf bank_mask:0xf
	v_fmac_f32_dpp v37, v249, v120 row_newbcast:2 row_mask:0xf bank_mask:0xf
	v_fmac_f32_dpp v28, v247, v90 row_newbcast:12 row_mask:0xf bank_mask:0xf
	s_nop 0
	v_fmac_f32_dpp v238, v248, v106 row_newbcast:1 row_mask:0xf bank_mask:0xf
	v_fmac_f32_dpp v239, v248, v112 row_newbcast:3 row_mask:0xf bank_mask:0xf
	v_fmac_f32_dpp v36, v249, v110 row_newbcast:4 row_mask:0xf bank_mask:0xf
	v_fmac_f32_dpp v37, v249, v100 row_newbcast:6 row_mask:0xf bank_mask:0xf
	v_fmac_f32_dpp v29, v247, v96 row_newbcast:14 row_mask:0xf bank_mask:0xf
	s_waitcnt lgkmcnt(0)
; #define LAS __attribute__((address_space(3)))
; __device__ __forceinline__ void dn_prep_item(const Args& a, LAS unsigned char* lds, int item, int tid, int wave, int lane, int& cwh, int next_item) {
;     ...
;         { const LAS float* lrow = Lm + (lane & 15);
; #pragma unroll
;         for (int i = 1; i < 64; ++i) { float sa[4] = { x[i], 0.f, 0.f, 0.f };
;             int lr[4];
; #pragma unroll
;             for (int g = 0; g < (i + 15) / 16; ++g) lr[g] = __float_as_int(lrow[i * 68 + 16 * g]);
; #pragma unroll
;             for (int j = 0; j < i; ++j) { fmac_rowbcast_sel(sa[j & 3], lr[j >> 4], x[j], j); }
;             x[i] = (sa[0] + sa[1]) + (sa[2] + sa[3]); } }
	v_add_u32_e32 v254, 0xc800, v208
	ds_read2_b32 v[252:253], v254 offset0:120 offset1:136
	v_fmac_f32_dpp v28, v250, v102 row_newbcast:0 row_mask:0xf bank_mask:0xf
	v_fmac_f32_dpp v238, v248, v118 row_newbcast:5 row_mask:0xf bank_mask:0xf
	v_fmac_f32_dpp v239, v248, v126 row_newbcast:7 row_mask:0xf bank_mask:0xf
	v_fmac_f32_dpp v36, v249, v88 row_newbcast:8 row_mask:0xf bank_mask:0xf
	v_fmac_f32_dpp v37, v249, v76 row_newbcast:10 row_mask:0xf bank_mask:0xf
	v_fmac_f32_dpp v29, v250, v108 row_newbcast:2 row_mask:0xf bank_mask:0xf
	s_nop 0
	v_fmac_f32_dpp v28, v250, v116 row_newbcast:4 row_mask:0xf bank_mask:0xf
	v_fmac_f32_dpp v238, v248, v134 row_newbcast:9 row_mask:0xf bank_mask:0xf
	v_fmac_f32_dpp v239, v248, v142 row_newbcast:11 row_mask:0xf bank_mask:0xf
	s_nop 0
	v_fmac_f32_dpp v238, v248, v140 row_newbcast:13 row_mask:0xf bank_mask:0xf
	v_fmac_f32_dpp v239, v248, v132 row_newbcast:15 row_mask:0xf bank_mask:0xf
	v_fmac_f32_dpp v238, v249, v124 row_newbcast:1 row_mask:0xf bank_mask:0xf
	v_fmac_f32_dpp v239, v249, v114 row_newbcast:3 row_mask:0xf bank_mask:0xf
	v_mul_f32_dpp v236, v246, v234 row_newbcast:1 row_mask:0xf bank_mask:0xf
	v_fmac_f32_dpp v29, v250, v122 row_newbcast:6 row_mask:0xf bank_mask:0xf
	v_fmac_f32_dpp v28, v250, v130 row_newbcast:8 row_mask:0xf bank_mask:0xf
	s_nop 0
	v_fmac_f32_dpp v238, v249, v104 row_newbcast:5 row_mask:0xf bank_mask:0xf
	v_fmac_f32_dpp v239, v249, v94 row_newbcast:7 row_mask:0xf bank_mask:0xf
	v_fmac_f32_dpp v236, v246, v6 row_newbcast:5 row_mask:0xf bank_mask:0xf
	v_fmac_f32_dpp v29, v250, v138 row_newbcast:10 row_mask:0xf bank_mask:0xf
	v_fmac_f32_dpp v28, v250, v144 row_newbcast:12 row_mask:0xf bank_mask:0xf
	s_nop 0
	v_fmac_f32_dpp v238, v249, v82 row_newbcast:9 row_mask:0xf bank_mask:0xf
	v_fmac_f32_dpp v239, v249, v44 row_newbcast:11 row_mask:0xf bank_mask:0xf
	v_mul_f32_dpp v237, v246, v2 row_newbcast:3 row_mask:0xf bank_mask:0xf
	v_fmac_f32_dpp v236, v246, v14 row_newbcast:9 row_mask:0xf bank_mask:0xf
	v_fmac_f32_dpp v29, v250, v136 row_newbcast:14 row_mask:0xf bank_mask:0xf
	v_fmac_f32_dpp v28, v251, v128 row_newbcast:0 row_mask:0xf bank_mask:0xf
	v_pk_add_f32 v[36:37], v[36:37], v[238:239]
	v_fmac_f32_dpp v237, v246, v10 row_newbcast:7 row_mask:0xf bank_mask:0xf
	v_fmac_f32_dpp v236, v246, v24 row_newbcast:13 row_mask:0xf bank_mask:0xf
	v_fmac_f32_dpp v29, v251, v120 row_newbcast:2 row_mask:0xf bank_mask:0xf
	v_fmac_f32_dpp v28, v251, v110 row_newbcast:4 row_mask:0xf bank_mask:0xf
	s_nop 0
	v_fmac_f32_dpp v237, v246, v20 row_newbcast:11 row_mask:0xf bank_mask:0xf
	v_fmac_f32_dpp v236, v247, v34 row_newbcast:1 row_mask:0xf bank_mask:0xf
	v_fmac_f32_dpp v29, v251, v100 row_newbcast:6 row_mask:0xf bank_mask:0xf
	v_fmac_f32_dpp v28, v251, v88 row_newbcast:8 row_mask:0xf bank_mask:0xf
	v_pk_add_f32 v[36:37], v[36:37], v[36:37] op_sel:[0,1] op_sel_hi:[1,0]
	v_fmac_f32_dpp v237, v246, v30 row_newbcast:15 row_mask:0xf bank_mask:0xf
	v_fmac_f32_dpp v236, v247, v46 row_newbcast:5 row_mask:0xf bank_mask:0xf
	v_fmac_f32_dpp v29, v251, v76 row_newbcast:10 row_mask:0xf bank_mask:0xf
	s_waitcnt lgkmcnt(0)
	v_add_u32_e32 v254, 0xc800, v208
	ds_read2_b32 v[242:243], v254 offset0:152 offset1:168
	v_fmac_f32_dpp v16, v252, v71 row_newbcast:0 row_mask:0xf bank_mask:0xf
	v_fmac_f32_dpp v17, v252, v235 row_newbcast:2 row_mask:0xf bank_mask:0xf
	v_fmac_f32_dpp v28, v251, v36 row_newbcast:12 row_mask:0xf bank_mask:0xf
	v_fmac_f32_dpp v237, v247, v40 row_newbcast:3 row_mask:0xf bank_mask:0xf
	v_fmac_f32_dpp v236, v247, v80 row_newbcast:9 row_mask:0xf bank_mask:0xf
	s_nop 0
	v_fmac_f32_dpp v237, v247, v74 row_newbcast:7 row_mask:0xf bank_mask:0xf
	v_fmac_f32_dpp v236, v247, v92 row_newbcast:13 row_mask:0xf bank_mask:0xf
	v_fmac_f32_dpp v16, v252, v4 row_newbcast:4 row_mask:0xf bank_mask:0xf
	v_fmac_f32_dpp v17, v252, v8 row_newbcast:6 row_mask:0xf bank_mask:0xf
	s_nop 0
	v_fmac_f32_dpp v237, v247, v86 row_newbcast:11 row_mask:0xf bank_mask:0xf
	v_fmac_f32_dpp v236, v250, v106 row_newbcast:1 row_mask:0xf bank_mask:0xf
	v_fmac_f32_dpp v16, v252, v12 row_newbcast:8 row_mask:0xf bank_mask:0xf
	v_fmac_f32_dpp v17, v252, v18 row_newbcast:10 row_mask:0xf bank_mask:0xf
	s_nop 0
	v_fmac_f32_dpp v237, v247, v98 row_newbcast:15 row_mask:0xf bank_mask:0xf
	v_fmac_f32_dpp v236, v250, v118 row_newbcast:5 row_mask:0xf bank_mask:0xf
	v_fmac_f32_dpp v16, v252, v22 row_newbcast:12 row_mask:0xf bank_mask:0xf
	v_fmac_f32_dpp v17, v252, v26 row_newbcast:14 row_mask:0xf bank_mask:0xf
	s_nop 0
	v_fmac_f32_dpp v237, v250, v112 row_newbcast:3 row_mask:0xf bank_mask:0xf
	v_fmac_f32_dpp v236, v250, v134 row_newbcast:9 row_mask:0xf bank_mask:0xf
	v_fmac_f32_dpp v16, v253, v32 row_newbcast:0 row_mask:0xf bank_mask:0xf
	v_fmac_f32_dpp v17, v253, v38 row_newbcast:2 row_mask:0xf bank_mask:0xf
	s_nop 0
	v_fmac_f32_dpp v237, v250, v126 row_newbcast:7 row_mask:0xf bank_mask:0xf
	v_fmac_f32_dpp v236, v250, v140 row_newbcast:13 row_mask:0xf bank_mask:0xf
	v_fmac_f32_dpp v16, v253, v42 row_newbcast:4 row_mask:0xf bank_mask:0xf
	v_fmac_f32_dpp v17, v253, v72 row_newbcast:6 row_mask:0xf bank_mask:0xf
	s_nop 0
	v_fmac_f32_dpp v237, v250, v142 row_newbcast:11 row_mask:0xf bank_mask:0xf
	v_fmac_f32_dpp v236, v251, v124 row_newbcast:1 row_mask:0xf bank_mask:0xf
	v_fmac_f32_dpp v16, v253, v78 row_newbcast:8 row_mask:0xf bank_mask:0xf
	v_fmac_f32_dpp v17, v253, v84 row_newbcast:10 row_mask:0xf bank_mask:0xf
	s_nop 0
	v_fmac_f32_dpp v237, v250, v132 row_newbcast:15 row_mask:0xf bank_mask:0xf
	v_fmac_f32_dpp v236, v251, v104 row_newbcast:5 row_mask:0xf bank_mask:0xf
	v_fmac_f32_dpp v16, v253, v90 row_newbcast:12 row_mask:0xf bank_mask:0xf
	v_fmac_f32_dpp v17, v253, v96 row_newbcast:14 row_mask:0xf bank_mask:0xf
	s_nop 0
	v_fmac_f32_dpp v237, v251, v114 row_newbcast:3 row_mask:0xf bank_mask:0xf
	v_fmac_f32_dpp v236, v251, v82 row_newbcast:9 row_mask:0xf bank_mask:0xf
	s_nop 0
	v_fmac_f32_dpp v237, v251, v94 row_newbcast:7 row_mask:0xf bank_mask:0xf
	s_nop 0
	v_fmac_f32_dpp v237, v251, v44 row_newbcast:11 row_mask:0xf bank_mask:0xf
	s_nop 0
	v_pk_add_f32 v[28:29], v[28:29], v[236:237]
	v_mul_f32_dpp v236, v252, v234 row_newbcast:1 row_mask:0xf bank_mask:0xf
	v_mul_f32_dpp v237, v252, v2 row_newbcast:3 row_mask:0xf bank_mask:0xf
	v_fmac_f32_dpp v236, v252, v6 row_newbcast:5 row_mask:0xf bank_mask:0xf
	s_waitcnt lgkmcnt(0)
; #define LAS __attribute__((address_space(3)))
; __device__ __forceinline__ void dn_prep_item(const Args& a, LAS unsigned char* lds, int item, int tid, int wave, int lane, int& cwh, int next_item) {
;     ...
;         { const LAS float* lrow = Lm + (lane & 15);
; #pragma unroll
;         for (int i = 1; i < 64; ++i) { float sa[4] = { x[i], 0.f, 0.f, 0.f };
;             int lr[4];
; #pragma unroll
;             for (int g = 0; g < (i + 15) / 16; ++g) lr[g] = __float_as_int(lrow[i * 68 + 16 * g]);
; #pragma unroll
;             for (int j = 0; j < i; ++j) { fmac_rowbcast_sel(sa[j & 3], lr[j >> 4], x[j], j); }
;             x[i] = (sa[0] + sa[1]) + (sa[2] + sa[3]); } }
	v_add_u32_e32 v254, 0xc800, v208
	ds_read2_b32 v[246:247], v254 offset0:188 offset1:204
	v_fmac_f32_dpp v16, v242, v102 row_newbcast:0 row_mask:0xf bank_mask:0xf
	v_fmac_f32_dpp v17, v242, v108 row_newbcast:2 row_mask:0xf bank_mask:0xf
	v_pk_add_f32 v[28:29], v[28:29], v[28:29] op_sel:[0,1] op_sel_hi:[1,0]
	v_fmac_f32_dpp v237, v252, v10 row_newbcast:7 row_mask:0xf bank_mask:0xf
	v_fmac_f32_dpp v236, v252, v14 row_newbcast:9 row_mask:0xf bank_mask:0xf
	v_fmac_f32_dpp v16, v242, v116 row_newbcast:4 row_mask:0xf bank_mask:0xf
	v_fmac_f32_dpp v17, v242, v122 row_newbcast:6 row_mask:0xf bank_mask:0xf
	s_nop 0
	v_fmac_f32_dpp v237, v252, v20 row_newbcast:11 row_mask:0xf bank_mask:0xf
	v_fmac_f32_dpp v236, v252, v24 row_newbcast:13 row_mask:0xf bank_mask:0xf
	v_fmac_f32_dpp v16, v242, v130 row_newbcast:8 row_mask:0xf bank_mask:0xf
	v_fmac_f32_dpp v17, v242, v138 row_newbcast:10 row_mask:0xf bank_mask:0xf
	s_nop 0
	v_fmac_f32_dpp v237, v252, v30 row_newbcast:15 row_mask:0xf bank_mask:0xf
	v_fmac_f32_dpp v236, v253, v34 row_newbcast:1 row_mask:0xf bank_mask:0xf
	v_fmac_f32_dpp v16, v242, v144 row_newbcast:12 row_mask:0xf bank_mask:0xf
	v_fmac_f32_dpp v17, v242, v136 row_newbcast:14 row_mask:0xf bank_mask:0xf
	s_nop 0
	v_fmac_f32_dpp v237, v253, v40 row_newbcast:3 row_mask:0xf bank_mask:0xf
	v_fmac_f32_dpp v236, v253, v46 row_newbcast:5 row_mask:0xf bank_mask:0xf
	v_fmac_f32_dpp v16, v243, v128 row_newbcast:0 row_mask:0xf bank_mask:0xf
	v_fmac_f32_dpp v17, v243, v120 row_newbcast:2 row_mask:0xf bank_mask:0xf
	s_nop 0
	v_fmac_f32_dpp v237, v253, v74 row_newbcast:7 row_mask:0xf bank_mask:0xf
	v_fmac_f32_dpp v236, v253, v80 row_newbcast:9 row_mask:0xf bank_mask:0xf
	v_fmac_f32_dpp v16, v243, v110 row_newbcast:4 row_mask:0xf bank_mask:0xf
	v_fmac_f32_dpp v17, v243, v100 row_newbcast:6 row_mask:0xf bank_mask:0xf
	s_nop 0
	v_fmac_f32_dpp v237, v253, v86 row_newbcast:11 row_mask:0xf bank_mask:0xf
	v_fmac_f32_dpp v236, v253, v92 row_newbcast:13 row_mask:0xf bank_mask:0xf
	v_fmac_f32_dpp v16, v243, v88 row_newbcast:8 row_mask:0xf bank_mask:0xf
	v_fmac_f32_dpp v17, v243, v76 row_newbcast:10 row_mask:0xf bank_mask:0xf
	s_nop 0
	v_fmac_f32_dpp v237, v253, v98 row_newbcast:15 row_mask:0xf bank_mask:0xf
	v_fmac_f32_dpp v236, v242, v106 row_newbcast:1 row_mask:0xf bank_mask:0xf
	v_fmac_f32_dpp v16, v243, v36 row_newbcast:12 row_mask:0xf bank_mask:0xf
	s_nop 0
	v_fmac_f32_dpp v237, v242, v112 row_newbcast:3 row_mask:0xf bank_mask:0xf
	v_fmac_f32_dpp v236, v242, v118 row_newbcast:5 row_mask:0xf bank_mask:0xf
	s_waitcnt lgkmcnt(0)
	v_add_u32_e32 v254, 0xc800, v208
	ds_read2_b32 v[248:249], v254 offset0:220 offset1:236
	v_fmac_f32_dpp v0, v246, v71 row_newbcast:0 row_mask:0xf bank_mask:0xf
	v_fmac_f32_dpp v237, v242, v126 row_newbcast:7 row_mask:0xf bank_mask:0xf
	v_fmac_f32_dpp v236, v242, v134 row_newbcast:9 row_mask:0xf bank_mask:0xf
	s_nop 0
	v_fmac_f32_dpp v0, v246, v4 row_newbcast:4 row_mask:0xf bank_mask:0xf
	v_fmac_f32_dpp v237, v242, v142 row_newbcast:11 row_mask:0xf bank_mask:0xf
	v_fmac_f32_dpp v236, v242, v140 row_newbcast:13 row_mask:0xf bank_mask:0xf
	s_nop 0
	v_fmac_f32_dpp v0, v246, v12 row_newbcast:8 row_mask:0xf bank_mask:0xf
	v_fmac_f32_dpp v237, v242, v132 row_newbcast:15 row_mask:0xf bank_mask:0xf
	v_fmac_f32_dpp v236, v243, v124 row_newbcast:1 row_mask:0xf bank_mask:0xf
	s_nop 0
	v_fmac_f32_dpp v0, v246, v22 row_newbcast:12 row_mask:0xf bank_mask:0xf
	v_fmac_f32_dpp v237, v243, v114 row_newbcast:3 row_mask:0xf bank_mask:0xf
	v_fmac_f32_dpp v236, v243, v104 row_newbcast:5 row_mask:0xf bank_mask:0xf
	s_nop 0
	v_fmac_f32_dpp v0, v247, v32 row_newbcast:0 row_mask:0xf bank_mask:0xf
	v_fmac_f32_dpp v237, v243, v94 row_newbcast:7 row_mask:0xf bank_mask:0xf
	v_fmac_f32_dpp v236, v243, v82 row_newbcast:9 row_mask:0xf bank_mask:0xf
	s_nop 0
	v_fmac_f32_dpp v0, v247, v42 row_newbcast:4 row_mask:0xf bank_mask:0xf
	v_fmac_f32_dpp v237, v243, v44 row_newbcast:11 row_mask:0xf bank_mask:0xf
	v_fmac_f32_dpp v236, v243, v28 row_newbcast:13 row_mask:0xf bank_mask:0xf
	s_nop 0
	v_pk_add_f32 v[16:17], v[16:17], v[236:237]
	v_mul_f32_dpp v1, v246, v235 row_newbcast:2 row_mask:0xf bank_mask:0xf
	v_mul_f32_dpp v236, v246, v234 row_newbcast:1 row_mask:0xf bank_mask:0xf
	v_fmac_f32_dpp v1, v246, v8 row_newbcast:6 row_mask:0xf bank_mask:0xf
	v_mul_f32_dpp v237, v246, v2 row_newbcast:3 row_mask:0xf bank_mask:0xf
	v_fmac_f32_dpp v236, v246, v6 row_newbcast:5 row_mask:0xf bank_mask:0xf
	v_fmac_f32_dpp v0, v247, v78 row_newbcast:8 row_mask:0xf bank_mask:0xf
	v_pk_add_f32 v[16:17], v[16:17], v[16:17] op_sel:[0,1] op_sel_hi:[1,0]
	v_fmac_f32_dpp v1, v246, v18 row_newbcast:10 row_mask:0xf bank_mask:0xf
	v_fmac_f32_dpp v237, v246, v10 row_newbcast:7 row_mask:0xf bank_mask:0xf
	v_fmac_f32_dpp v236, v246, v14 row_newbcast:9 row_mask:0xf bank_mask:0xf
	v_fmac_f32_dpp v0, v247, v90 row_newbcast:12 row_mask:0xf bank_mask:0xf
	s_nop 0
	v_fmac_f32_dpp v1, v246, v26 row_newbcast:14 row_mask:0xf bank_mask:0xf
	v_fmac_f32_dpp v237, v246, v20 row_newbcast:11 row_mask:0xf bank_mask:0xf
	v_fmac_f32_dpp v236, v246, v24 row_newbcast:13 row_mask:0xf bank_mask:0xf
	s_waitcnt lgkmcnt(0)
; #define LAS __attribute__((address_space(3)))
; __device__ __forceinline__ unsigned pk2(float lo, float hi) { const f32x2_t v = {lo, hi}; const bf16x2_t b = __builtin_convertvector(v, bf16x2_t); return __builtin_bit_cast(unsigned, b); }
; __device__ __forceinline__ void dn_prep_item(const Args& a, LAS unsigned char* lds, int item, int tid, int wave, int lane, int& cwh, int next_item) {
;     ...
;         for (int i = 1; i < 64; ++i) { float sa[4] = { x[i], 0.f, 0.f, 0.f };
;             int lr[4];
; #pragma unroll
;             for (int g = 0; g < (i + 15) / 16; ++g) lr[g] = __float_as_int(lrow[i * 68 + 16 * g]);
; #pragma unroll
;             for (int j = 0; j < i; ++j) { fmac_rowbcast_sel(sa[j & 3], lr[j >> 4], x[j], j); }
;             x[i] = (sa[0] + sa[1]) + (sa[2] + sa[3]); } }
; #pragma unroll
;         for (int q = 0; q < 8; ++q) { v4u w; w.x = pk2(x[8 * q], x[8 * q + 1]); w.y = pk2(x[8 * q + 2], x[8 * q + 3]); w.z = pk2(x[8 * q + 4], x[8 * q + 5]); w.w = pk2(x[8 * q + 6], x[8 * q + 7]);
;             *(LAS v4u*)(lds + L_SOL + tid * AS_ + 16 * q) = w; }
	v_fmac_f32_dpp v0, v248, v102 row_newbcast:0 row_mask:0xf bank_mask:0xf
	v_fmac_f32_dpp v1, v247, v38 row_newbcast:2 row_mask:0xf bank_mask:0xf
	v_fmac_f32_dpp v237, v246, v30 row_newbcast:15 row_mask:0xf bank_mask:0xf
	v_fmac_f32_dpp v236, v247, v34 row_newbcast:1 row_mask:0xf bank_mask:0xf
	s_nop 0
	v_fmac_f32_dpp v0, v248, v116 row_newbcast:4 row_mask:0xf bank_mask:0xf
	v_fmac_f32_dpp v1, v247, v72 row_newbcast:6 row_mask:0xf bank_mask:0xf
	v_fmac_f32_dpp v237, v247, v40 row_newbcast:3 row_mask:0xf bank_mask:0xf
	v_fmac_f32_dpp v236, v247, v46 row_newbcast:5 row_mask:0xf bank_mask:0xf
	s_nop 0
	v_fmac_f32_dpp v0, v248, v130 row_newbcast:8 row_mask:0xf bank_mask:0xf
	v_fmac_f32_dpp v1, v247, v84 row_newbcast:10 row_mask:0xf bank_mask:0xf
	v_fmac_f32_dpp v237, v247, v74 row_newbcast:7 row_mask:0xf bank_mask:0xf
	v_fmac_f32_dpp v236, v247, v80 row_newbcast:9 row_mask:0xf bank_mask:0xf
	s_nop 0
	v_fmac_f32_dpp v0, v248, v144 row_newbcast:12 row_mask:0xf bank_mask:0xf
	v_fmac_f32_dpp v1, v247, v96 row_newbcast:14 row_mask:0xf bank_mask:0xf
	v_fmac_f32_dpp v237, v247, v86 row_newbcast:11 row_mask:0xf bank_mask:0xf
	v_fmac_f32_dpp v236, v247, v92 row_newbcast:13 row_mask:0xf bank_mask:0xf
	s_nop 0
	v_fmac_f32_dpp v0, v249, v128 row_newbcast:0 row_mask:0xf bank_mask:0xf
	v_fmac_f32_dpp v1, v248, v108 row_newbcast:2 row_mask:0xf bank_mask:0xf
	v_fmac_f32_dpp v237, v247, v98 row_newbcast:15 row_mask:0xf bank_mask:0xf
	v_fmac_f32_dpp v236, v248, v106 row_newbcast:1 row_mask:0xf bank_mask:0xf
	s_nop 0
	v_fmac_f32_dpp v0, v249, v110 row_newbcast:4 row_mask:0xf bank_mask:0xf
	v_fmac_f32_dpp v1, v248, v122 row_newbcast:6 row_mask:0xf bank_mask:0xf
	v_fmac_f32_dpp v237, v248, v112 row_newbcast:3 row_mask:0xf bank_mask:0xf
	v_fmac_f32_dpp v236, v248, v118 row_newbcast:5 row_mask:0xf bank_mask:0xf
	s_nop 0
	v_fmac_f32_dpp v0, v249, v88 row_newbcast:8 row_mask:0xf bank_mask:0xf
	v_fmac_f32_dpp v1, v248, v138 row_newbcast:10 row_mask:0xf bank_mask:0xf
	v_fmac_f32_dpp v237, v248, v126 row_newbcast:7 row_mask:0xf bank_mask:0xf
	v_fmac_f32_dpp v236, v248, v134 row_newbcast:9 row_mask:0xf bank_mask:0xf
	s_nop 0
	v_fmac_f32_dpp v0, v249, v36 row_newbcast:12 row_mask:0xf bank_mask:0xf
	v_fmac_f32_dpp v1, v248, v136 row_newbcast:14 row_mask:0xf bank_mask:0xf
	v_fmac_f32_dpp v237, v248, v142 row_newbcast:11 row_mask:0xf bank_mask:0xf
	v_fmac_f32_dpp v236, v248, v140 row_newbcast:13 row_mask:0xf bank_mask:0xf
	s_nop 0
	v_fmac_f32_dpp v1, v249, v120 row_newbcast:2 row_mask:0xf bank_mask:0xf
	v_fmac_f32_dpp v237, v248, v132 row_newbcast:15 row_mask:0xf bank_mask:0xf
	v_fmac_f32_dpp v236, v249, v124 row_newbcast:1 row_mask:0xf bank_mask:0xf
	s_nop 0
	v_fmac_f32_dpp v1, v249, v100 row_newbcast:6 row_mask:0xf bank_mask:0xf
	v_fmac_f32_dpp v237, v249, v114 row_newbcast:3 row_mask:0xf bank_mask:0xf
	v_fmac_f32_dpp v236, v249, v104 row_newbcast:5 row_mask:0xf bank_mask:0xf
	s_nop 0
	v_fmac_f32_dpp v1, v249, v76 row_newbcast:10 row_mask:0xf bank_mask:0xf
	v_fmac_f32_dpp v237, v249, v94 row_newbcast:7 row_mask:0xf bank_mask:0xf
	v_fmac_f32_dpp v236, v249, v82 row_newbcast:9 row_mask:0xf bank_mask:0xf
	s_nop 0
	v_fmac_f32_dpp v1, v249, v16 row_newbcast:14 row_mask:0xf bank_mask:0xf
	v_fmac_f32_dpp v237, v249, v44 row_newbcast:11 row_mask:0xf bank_mask:0xf
	v_fmac_f32_dpp v236, v249, v28 row_newbcast:13 row_mask:0xf bank_mask:0xf
	s_nop 0
	v_pk_add_f32 v[0:1], v[0:1], v[236:237]
	s_nop 0
	v_pk_add_f32 v[146:147], v[0:1], v[0:1] op_sel_hi:[0,1]
	v_cvt_pk_bf16_f32 v0, v71, v234
	v_cvt_pk_bf16_f32 v1, v235, v2
	v_cvt_pk_bf16_f32 v2, v4, v6
	ds_write_b128 v223, v[0:3] offset:61440
	v_cvt_pk_bf16_f32 v0, v12, v14
	v_cvt_pk_bf16_f32 v1, v18, v20
	v_cvt_pk_bf16_f32 v2, v22, v24
	v_cvt_pk_bf16_f32 v3, v26, v30
	ds_write_b128 v223, v[0:3] offset:61456
	v_cvt_pk_bf16_f32 v0, v32, v34
	v_cvt_pk_bf16_f32 v1, v38, v40
	v_cvt_pk_bf16_f32 v2, v42, v46
	v_cvt_pk_bf16_f32 v3, v72, v74
	ds_write_b128 v223, v[0:3] offset:61472
	v_cvt_pk_bf16_f32 v0, v78, v80
	v_cvt_pk_bf16_f32 v1, v84, v86
	v_cvt_pk_bf16_f32 v2, v90, v92
	v_cvt_pk_bf16_f32 v3, v96, v98
	ds_write_b128 v223, v[0:3] offset:61488
	v_cvt_pk_bf16_f32 v0, v102, v106
	v_cvt_pk_bf16_f32 v1, v108, v112
	v_cvt_pk_bf16_f32 v2, v116, v118
	v_cvt_pk_bf16_f32 v3, v122, v126
	ds_write_b128 v223, v[0:3] offset:61504
	v_cvt_pk_bf16_f32 v0, v130, v134
	v_cvt_pk_bf16_f32 v1, v138, v142
	v_cvt_pk_bf16_f32 v2, v144, v140
	v_cvt_pk_bf16_f32 v3, v136, v132
	ds_write_b128 v223, v[0:3] offset:61520
	v_cvt_pk_bf16_f32 v0, v128, v124
	v_cvt_pk_bf16_f32 v1, v120, v114
	v_cvt_pk_bf16_f32 v2, v110, v104
	v_cvt_pk_bf16_f32 v3, v100, v94
	ds_write_b128 v223, v[0:3] offset:61536
	v_cvt_pk_bf16_f32 v0, v88, v82
	v_cvt_pk_bf16_f32 v1, v76, v44
	v_cvt_pk_bf16_f32 v2, v36, v28
	v_cvt_pk_bf16_f32 v3, v16, v147
	ds_write_b128 v223, v[0:3] offset:61552
